# E-j + resid-epilogue (DN, WOUT) second-half residual loads hoisted behind first-half loads with in-order counted waits + FFT1 twiddle loads batched up front + 24 redundant post-barrier lgkmcnt waits r
# baseline (speedup 1.0000x reference)
; #define PG8_STAGE(bufoff, gbase, voff) do { _Pragma("unroll") for (int _i = 0; _i < 2; ++_i) \
;         __builtin_amdgcn_global_load_lds((const unsigned*)((const char*)(gbase) + (voff)[_i]), (PG8_LAS unsigned*)(lds + (bufoff) + ldsw + _i * 8192), 16, 0, 0); } while (0)
; #define PG8_LDA(dst, b, h) do { _Pragma("unroll") for (int m = 0; m < 4; ++m) _Pragma("unroll") for (int k = 0; k < 2; ++k) dst[m][k] = *(const PG8_LAS bf16x8*)(lds + PG8_SA(b, h) + aoff + m * 2048 + k * 1024); } while (0)
; #define PG8_LDB(dst, b, h) do { _Pragma("unroll") for (int n = 0; n < 2; ++n) _Pragma("unroll") for (int k = 0; k < 2; ++k) dst[n][k] = *(const PG8_LAS bf16x8*)(lds + PG8_SB(b, h) + boff + n * 2048 + k * 1024); } while (0)
; #define PG8_MMA(ai, bj, At, Bt) do { __builtin_amdgcn_s_setprio(1); _Pragma("unroll") for (int m = 0; m < 4; ++m) _Pragma("unroll") for (int n = 0; n < 2; ++n) _Pragma("unroll") for (int k = 0; k < 2; ++k) \
;         acc[ai][bj][m][n] = __builtin_amdgcn_mfma_f32_16x16x32_bf16(Bt[n][k], At[m][k], acc[ai][bj][m][n], 0, 0, 0); __builtin_amdgcn_s_setprio(0); } while (0)
; #define PG8_WAIT_L(n) asm volatile("s_waitcnt lgkmcnt(" #n ")" ::: "memory")
; #define PG8_WAIT_VK do { if constexpr (HALFM) PG8_WAIT_V(6); else PG8_WAIT_V(8); } while (0)
; #define PG8_BAR __builtin_amdgcn_s_barrier()
; #define PG8_SCHED __builtin_amdgcn_sched_barrier(0)
; template <class Epi, class Sched, bool ALIGN_EPI = false, bool SP2 = false, bool HALFM = false, bool AMAP = false>
; __device__ __forceinline__ void gemm_phase(PG8_LAS unsigned char* lds, const Gemm g, const Sched& S, const Epi& E, int tid_in) {
;     ...
;             PG8_LDB(B0, 0, 0); PG8_LDB(B1, 0, 1); PG8_SCHED; PG8_LDA(At, 0, 0); if constexpr (!HALFM) PG8_STAGE(PG8_SA(1, 1), a1 + hstepA, voffA);
;             PG8_WAIT_VK; PG8_WAIT_L(0); PG8_BAR; PG8_MMA(0, 0, At, B0); PG8_MMA(0, 1, At, B1); PG8_BAR; PG8_SCHED;
;             if constexpr (!HALFM) { PG8_LDA(At, 0, 1); } PG8_STAGE(PG8_SB(0, 0), b2, voffB); PG8_STAGE(PG8_SB(0, 1), b2 + hstepB, voffB); PG8_STAGE(PG8_SA(0, 0), a2, voffA);
;             PG8_WAIT_VK; PG8_WAIT_L(0); PG8_BAR; if constexpr (!HALFM) { PG8_MMA(1, 0, At, B0); PG8_MMA(1, 1, At, B1); } PG8_BAR; PG8_SCHED;
.LBB0_163:
	s_add_u32 s28, s6, 0xfff80080
	s_addc_u32 s29, s7, -1
	s_add_i32 s76, 0, 0x10000
	s_cmp_eq_u32 s63, 28
	s_cselect_b32 s31, s23, s29
	s_cselect_b32 s30, s59, s28
	s_cselect_b32 s29, s43, s62
	s_cselect_b32 s28, s60, s61
	s_add_i32 s77, 0, 0x14000
	v_add_u32_e32 v140, s76, v205
	v_add_u32_e32 v156, s77, v205
	ds_read_b128 v[0:3], v140
	ds_read_b128 v[4:7], v140 offset:1024
	ds_read_b128 v[136:139], v140 offset:2048
	ds_read_b128 v[140:143], v140 offset:3072
	ds_read_b128 v[144:147], v156
	ds_read_b128 v[148:151], v156 offset:1024
	ds_read_b128 v[152:155], v156 offset:2048
	ds_read_b128 v[156:159], v156 offset:3072
	v_lshl_add_u64 v[218:219], s[6:7], 0, v[190:191]
	s_add_i32 m0, s11, 0xc000
	ds_read_b128 v[160:163], v208
	ds_read_b128 v[164:167], v208 offset:1024
	ds_read_b128 v[168:171], v208 offset:2048
	ds_read_b128 v[192:195], v208 offset:3072
	ds_read_b128 v[196:199], v208 offset:4096
	ds_read_b128 v[200:203], v208 offset:5120
	ds_read_b128 v[210:213], v208 offset:6144
	ds_read_b128 v[214:217], v208 offset:7168
	global_load_lds_dwordx4 v[218:219], off
	v_lshl_add_u64 v[218:219], s[6:7], 0, v[188:189]
	s_add_i32 m0, s11, 0xe000
	s_nop 0
	global_load_lds_dwordx4 v[218:219], off
	s_waitcnt vmcnt(8)
	s_waitcnt lgkmcnt(0)
	s_barrier
	s_setprio 1
	v_mfma_f32_16x16x32_bf16 v[132:135], v[0:3], v[160:163], v[132:135]
	v_mfma_f32_16x16x32_bf16 v[128:131], v[136:139], v[160:163], v[128:131]
	v_mfma_f32_16x16x32_bf16 v[116:119], v[0:3], v[168:171], v[116:119]
	v_mfma_f32_16x16x32_bf16 v[112:115], v[136:139], v[168:171], v[112:115]
	v_mfma_f32_16x16x32_bf16 v[100:103], v[0:3], v[196:199], v[100:103]
	v_mfma_f32_16x16x32_bf16 v[96:99], v[136:139], v[196:199], v[96:99]
	v_mfma_f32_16x16x32_bf16 v[84:87], v[0:3], v[210:213], v[84:87]
	v_mfma_f32_16x16x32_bf16 v[80:83], v[136:139], v[210:213], v[80:83]
	v_mfma_f32_16x16x32_bf16 v[132:135], v[4:7], v[164:167], v[132:135]
	v_mfma_f32_16x16x32_bf16 v[128:131], v[140:143], v[164:167], v[128:131]
	v_mfma_f32_16x16x32_bf16 v[116:119], v[4:7], v[192:195], v[116:119]
	v_mfma_f32_16x16x32_bf16 v[112:115], v[140:143], v[192:195], v[112:115]
	v_mfma_f32_16x16x32_bf16 v[100:103], v[4:7], v[200:203], v[100:103]
	v_mfma_f32_16x16x32_bf16 v[96:99], v[140:143], v[200:203], v[96:99]
	v_mfma_f32_16x16x32_bf16 v[84:87], v[4:7], v[214:217], v[84:87]
	v_mfma_f32_16x16x32_bf16 v[80:83], v[140:143], v[214:217], v[80:83]
	s_setprio 0
	s_setprio 1
	v_mfma_f32_16x16x32_bf16 v[124:127], v[144:147], v[160:163], v[124:127]
	v_mfma_f32_16x16x32_bf16 v[120:123], v[152:155], v[160:163], v[120:123]
	v_mfma_f32_16x16x32_bf16 v[108:111], v[144:147], v[168:171], v[108:111]
	v_mfma_f32_16x16x32_bf16 v[104:107], v[152:155], v[168:171], v[104:107]
	v_mfma_f32_16x16x32_bf16 v[92:95], v[144:147], v[196:199], v[92:95]
	v_mfma_f32_16x16x32_bf16 v[88:91], v[152:155], v[196:199], v[88:91]
	v_mfma_f32_16x16x32_bf16 v[76:79], v[144:147], v[210:213], v[76:79]
	v_mfma_f32_16x16x32_bf16 v[72:75], v[152:155], v[210:213], v[72:75]
	v_mfma_f32_16x16x32_bf16 v[124:127], v[148:151], v[164:167], v[124:127]
	v_mfma_f32_16x16x32_bf16 v[120:123], v[156:159], v[164:167], v[120:123]
	v_mfma_f32_16x16x32_bf16 v[108:111], v[148:151], v[192:195], v[108:111]
	v_mfma_f32_16x16x32_bf16 v[104:107], v[156:159], v[192:195], v[104:107]
	v_mfma_f32_16x16x32_bf16 v[92:95], v[148:151], v[200:203], v[92:95]
	v_mfma_f32_16x16x32_bf16 v[88:91], v[156:159], v[200:203], v[88:91]
	v_mfma_f32_16x16x32_bf16 v[76:79], v[148:151], v[214:217], v[76:79]
	v_mfma_f32_16x16x32_bf16 v[72:75], v[156:159], v[214:217], v[72:75]
	s_setprio 0
	s_barrier
	s_add_i32 s76, s76, s10
	v_lshl_add_u64 v[218:219], s[28:29], 0, v[176:177]
	s_mov_b32 m0, s76
	ds_read_b128 v[160:163], v208 offset:16384
	ds_read_b128 v[164:167], v208 offset:17408
	ds_read_b128 v[168:171], v208 offset:18432
	ds_read_b128 v[192:195], v208 offset:19456
	ds_read_b128 v[196:199], v208 offset:20480
	ds_read_b128 v[200:203], v208 offset:21504
	ds_read_b128 v[210:213], v208 offset:22528
	ds_read_b128 v[214:217], v208 offset:23552
	global_load_lds_dwordx4 v[218:219], off
	s_add_i32 m0, s76, 0x2000
	s_add_u32 s80, s28, 0x80000
	v_lshl_add_u64 v[222:223], s[28:29], 0, v[172:173]
	s_addc_u32 s81, s29, 0
	s_add_i32 s76, s77, s10
	global_load_lds_dwordx4 v[222:223], off
	v_lshl_add_u64 v[224:225], s[80:81], 0, v[176:177]
	s_mov_b32 m0, s76
	v_lshl_add_u64 v[228:229], s[30:31], 0, v[174:175]
	global_load_lds_dwordx4 v[224:225], off
	v_lshl_add_u64 v[224:225], s[80:81], 0, v[172:173]
	s_add_i32 m0, s76, 0x2000
	s_nop 0
	global_load_lds_dwordx4 v[224:225], off
	v_lshl_add_u64 v[224:225], s[30:31], 0, v[184:185]
	s_mov_b32 m0, s11
	s_nop 0
	global_load_lds_dwordx4 v[224:225], off
	s_mov_b32 m0, s25
	s_nop 0
	global_load_lds_dwordx4 v[228:229], off
	s_waitcnt vmcnt(8)
	s_waitcnt lgkmcnt(0)
	s_barrier
; #define PG8_STAGE(bufoff, gbase, voff) do { _Pragma("unroll") for (int _i = 0; _i < 2; ++_i) \
;         __builtin_amdgcn_global_load_lds((const unsigned*)((const char*)(gbase) + (voff)[_i]), (PG8_LAS unsigned*)(lds + (bufoff) + ldsw + _i * 8192), 16, 0, 0); } while (0)
; #define PG8_LDA(dst, b, h) do { _Pragma("unroll") for (int m = 0; m < 4; ++m) _Pragma("unroll") for (int k = 0; k < 2; ++k) dst[m][k] = *(const PG8_LAS bf16x8*)(lds + PG8_SA(b, h) + aoff + m * 2048 + k * 1024); } while (0)
; #define PG8_LDB(dst, b, h) do { _Pragma("unroll") for (int n = 0; n < 2; ++n) _Pragma("unroll") for (int k = 0; k < 2; ++k) dst[n][k] = *(const PG8_LAS bf16x8*)(lds + PG8_SB(b, h) + boff + n * 2048 + k * 1024); } while (0)
; #define PG8_MMA(ai, bj, At, Bt) do { __builtin_amdgcn_s_setprio(1); _Pragma("unroll") for (int m = 0; m < 4; ++m) _Pragma("unroll") for (int n = 0; n < 2; ++n) _Pragma("unroll") for (int k = 0; k < 2; ++k) \
;         acc[ai][bj][m][n] = __builtin_amdgcn_mfma_f32_16x16x32_bf16(Bt[n][k], At[m][k], acc[ai][bj][m][n], 0, 0, 0); __builtin_amdgcn_s_setprio(0); } while (0)
; #define PG8_WAIT_L(n) asm volatile("s_waitcnt lgkmcnt(" #n ")" ::: "memory")
; #define PG8_WAIT_VK do { if constexpr (HALFM) PG8_WAIT_V(6); else PG8_WAIT_V(8); } while (0)
; #define PG8_BAR __builtin_amdgcn_s_barrier()
; #define PG8_SCHED __builtin_amdgcn_sched_barrier(0)
; template <class Epi, class Sched, bool ALIGN_EPI = false, bool SP2 = false, bool HALFM = false, bool AMAP = false>
; __device__ __forceinline__ void gemm_phase(PG8_LAS unsigned char* lds, const Gemm g, const Sched& S, const Epi& E, int tid_in) {
;     ...
;             PG8_WAIT_VK; PG8_WAIT_L(0); PG8_BAR; if constexpr (!HALFM) { PG8_MMA(1, 0, At, B0); PG8_MMA(1, 1, At, B1); } PG8_BAR; PG8_SCHED;
;             PG8_LDB(B0, 1, 0); PG8_LDB(B1, 1, 1); PG8_SCHED; PG8_LDA(At, 1, 0); if constexpr (!HALFM) PG8_STAGE(PG8_SA(0, 1), a2 + hstepA, voffA);
;             PG8_WAIT_VK; PG8_WAIT_L(0); PG8_BAR; PG8_MMA(0, 0, At, B0); PG8_MMA(0, 1, At, B1); PG8_BAR; PG8_SCHED;
	s_setprio 1
	v_mfma_f32_16x16x32_bf16 v[68:71], v[0:3], v[160:163], v[68:71]
	v_mfma_f32_16x16x32_bf16 v[64:67], v[136:139], v[160:163], v[64:67]
	v_mfma_f32_16x16x32_bf16 v[52:55], v[0:3], v[168:171], v[52:55]
	v_mfma_f32_16x16x32_bf16 v[48:51], v[136:139], v[168:171], v[48:51]
	v_mfma_f32_16x16x32_bf16 v[36:39], v[0:3], v[196:199], v[36:39]
	v_mfma_f32_16x16x32_bf16 v[32:35], v[136:139], v[196:199], v[32:35]
	v_mfma_f32_16x16x32_bf16 v[0:3], v[0:3], v[210:213], v[20:23]
	v_mfma_f32_16x16x32_bf16 v[68:71], v[4:7], v[164:167], v[68:71]
	v_mfma_f32_16x16x32_bf16 v[64:67], v[140:143], v[164:167], v[64:67]
	v_mfma_f32_16x16x32_bf16 v[52:55], v[4:7], v[192:195], v[52:55]
	v_mfma_f32_16x16x32_bf16 v[48:51], v[140:143], v[192:195], v[48:51]
	v_mfma_f32_16x16x32_bf16 v[36:39], v[4:7], v[200:203], v[36:39]
	v_mfma_f32_16x16x32_bf16 v[32:35], v[140:143], v[200:203], v[32:35]
	v_mfma_f32_16x16x32_bf16 v[0:3], v[4:7], v[214:217], v[0:3]
	v_mfma_f32_16x16x32_bf16 v[4:7], v[136:139], v[210:213], v[16:19]
	v_mfma_f32_16x16x32_bf16 v[4:7], v[140:143], v[214:217], v[4:7]
	s_setprio 0
	s_setprio 1
	v_mfma_f32_16x16x32_bf16 v[16:19], v[144:147], v[160:163], v[60:63]
	v_mfma_f32_16x16x32_bf16 v[60:63], v[148:151], v[164:167], v[16:19]
	v_mfma_f32_16x16x32_bf16 v[16:19], v[152:155], v[160:163], v[56:59]
	v_mfma_f32_16x16x32_bf16 v[56:59], v[156:159], v[164:167], v[16:19]
	v_mfma_f32_16x16x32_bf16 v[16:19], v[144:147], v[168:171], v[44:47]
	v_mfma_f32_16x16x32_bf16 v[44:47], v[148:151], v[192:195], v[16:19]
	v_mfma_f32_16x16x32_bf16 v[16:19], v[152:155], v[168:171], v[40:43]
	v_mfma_f32_16x16x32_bf16 v[40:43], v[156:159], v[192:195], v[16:19]
	v_mfma_f32_16x16x32_bf16 v[16:19], v[144:147], v[196:199], v[28:31]
	v_mfma_f32_16x16x32_bf16 v[28:31], v[148:151], v[200:203], v[16:19]
	v_mfma_f32_16x16x32_bf16 v[16:19], v[152:155], v[196:199], v[24:27]
	v_mfma_f32_16x16x32_bf16 v[12:15], v[144:147], v[210:213], v[12:15]
	v_mfma_f32_16x16x32_bf16 v[8:11], v[152:155], v[210:213], v[8:11]
	v_mfma_f32_16x16x32_bf16 v[24:27], v[156:159], v[200:203], v[16:19]
	v_mfma_f32_16x16x32_bf16 v[12:15], v[148:151], v[214:217], v[12:15]
	v_mfma_f32_16x16x32_bf16 v[8:11], v[156:159], v[214:217], v[8:11]
	s_setprio 0
	s_barrier
	s_add_i32 s76, 0, 0x18000
	s_add_i32 s77, 0, 0x1c000
	v_add_u32_e32 v140, s76, v205
	v_add_u32_e32 v156, s77, v205
	ds_read_b128 v[16:19], v140
	ds_read_b128 v[20:23], v140 offset:1024
	ds_read_b128 v[136:139], v140 offset:2048
	ds_read_b128 v[140:143], v140 offset:3072
	ds_read_b128 v[144:147], v156
	ds_read_b128 v[148:151], v156 offset:1024
	ds_read_b128 v[152:155], v156 offset:2048
	ds_read_b128 v[156:159], v156 offset:3072
	s_add_u32 s30, s30, 0x80000
	s_addc_u32 s31, s31, 0
	s_mov_b32 m0, s36
	v_lshl_add_u64 v[230:231], s[30:31], 0, v[184:185]
	ds_read_b128 v[160:163], v208 offset:32768
	ds_read_b128 v[164:167], v208 offset:33792
	ds_read_b128 v[168:171], v208 offset:34816
	ds_read_b128 v[192:195], v208 offset:35840
	ds_read_b128 v[196:199], v208 offset:36864
	ds_read_b128 v[200:203], v208 offset:37888
	ds_read_b128 v[210:213], v208 offset:38912
	ds_read_b128 v[214:217], v208 offset:39936
	global_load_lds_dwordx4 v[230:231], off
	v_lshl_add_u64 v[230:231], s[30:31], 0, v[174:175]
	s_mov_b32 m0, s37
	s_nop 0
	global_load_lds_dwordx4 v[230:231], off
	s_waitcnt vmcnt(8)
	s_waitcnt lgkmcnt(0)
	s_barrier
	s_setprio 1
	v_mfma_f32_16x16x32_bf16 v[132:135], v[16:19], v[160:163], v[132:135]
	v_mfma_f32_16x16x32_bf16 v[128:131], v[136:139], v[160:163], v[128:131]
	v_mfma_f32_16x16x32_bf16 v[116:119], v[16:19], v[168:171], v[116:119]
	v_mfma_f32_16x16x32_bf16 v[112:115], v[136:139], v[168:171], v[112:115]
	v_mfma_f32_16x16x32_bf16 v[100:103], v[16:19], v[196:199], v[100:103]
	v_mfma_f32_16x16x32_bf16 v[96:99], v[136:139], v[196:199], v[96:99]
	v_mfma_f32_16x16x32_bf16 v[84:87], v[16:19], v[210:213], v[84:87]
	v_mfma_f32_16x16x32_bf16 v[80:83], v[136:139], v[210:213], v[80:83]
	v_mfma_f32_16x16x32_bf16 v[132:135], v[20:23], v[164:167], v[132:135]
	v_mfma_f32_16x16x32_bf16 v[128:131], v[140:143], v[164:167], v[128:131]
	v_mfma_f32_16x16x32_bf16 v[116:119], v[20:23], v[192:195], v[116:119]
	v_mfma_f32_16x16x32_bf16 v[112:115], v[140:143], v[192:195], v[112:115]
	v_mfma_f32_16x16x32_bf16 v[100:103], v[20:23], v[200:203], v[100:103]
	v_mfma_f32_16x16x32_bf16 v[96:99], v[140:143], v[200:203], v[96:99]
	v_mfma_f32_16x16x32_bf16 v[84:87], v[20:23], v[214:217], v[84:87]
	v_mfma_f32_16x16x32_bf16 v[80:83], v[140:143], v[214:217], v[80:83]
	s_setprio 0
	s_setprio 1
	v_mfma_f32_16x16x32_bf16 v[124:127], v[144:147], v[160:163], v[124:127]
	v_mfma_f32_16x16x32_bf16 v[120:123], v[152:155], v[160:163], v[120:123]
	v_mfma_f32_16x16x32_bf16 v[108:111], v[144:147], v[168:171], v[108:111]
	v_mfma_f32_16x16x32_bf16 v[104:107], v[152:155], v[168:171], v[104:107]
	v_mfma_f32_16x16x32_bf16 v[92:95], v[144:147], v[196:199], v[92:95]
	v_mfma_f32_16x16x32_bf16 v[88:91], v[152:155], v[196:199], v[88:91]
	v_mfma_f32_16x16x32_bf16 v[76:79], v[144:147], v[210:213], v[76:79]
	v_mfma_f32_16x16x32_bf16 v[72:75], v[152:155], v[210:213], v[72:75]
	v_mfma_f32_16x16x32_bf16 v[124:127], v[148:151], v[164:167], v[124:127]
	v_mfma_f32_16x16x32_bf16 v[120:123], v[156:159], v[164:167], v[120:123]
	v_mfma_f32_16x16x32_bf16 v[108:111], v[148:151], v[192:195], v[108:111]
	v_mfma_f32_16x16x32_bf16 v[104:107], v[156:159], v[192:195], v[104:107]
	v_mfma_f32_16x16x32_bf16 v[92:95], v[148:151], v[200:203], v[92:95]
	v_mfma_f32_16x16x32_bf16 v[88:91], v[156:159], v[200:203], v[88:91]
	v_mfma_f32_16x16x32_bf16 v[76:79], v[148:151], v[214:217], v[76:79]
	v_mfma_f32_16x16x32_bf16 v[72:75], v[156:159], v[214:217], v[72:75]
	s_setprio 0
	s_barrier
; #define PG8_STAGE(bufoff, gbase, voff) do { _Pragma("unroll") for (int _i = 0; _i < 2; ++_i) \
;         __builtin_amdgcn_global_load_lds((const unsigned*)((const char*)(gbase) + (voff)[_i]), (PG8_LAS unsigned*)(lds + (bufoff) + ldsw + _i * 8192), 16, 0, 0); } while (0)
; #define PG8_LDA(dst, b, h) do { _Pragma("unroll") for (int m = 0; m < 4; ++m) _Pragma("unroll") for (int k = 0; k < 2; ++k) dst[m][k] = *(const PG8_LAS bf16x8*)(lds + PG8_SA(b, h) + aoff + m * 2048 + k * 1024); } while (0)
; #define PG8_MMA(ai, bj, At, Bt) do { __builtin_amdgcn_s_setprio(1); _Pragma("unroll") for (int m = 0; m < 4; ++m) _Pragma("unroll") for (int n = 0; n < 2; ++n) _Pragma("unroll") for (int k = 0; k < 2; ++k) \
;         acc[ai][bj][m][n] = __builtin_amdgcn_mfma_f32_16x16x32_bf16(Bt[n][k], At[m][k], acc[ai][bj][m][n], 0, 0, 0); __builtin_amdgcn_s_setprio(0); } while (0)
; #define PG8_WAIT_L(n) asm volatile("s_waitcnt lgkmcnt(" #n ")" ::: "memory")
; #define PG8_WAIT_VK do { if constexpr (HALFM) PG8_WAIT_V(6); else PG8_WAIT_V(8); } while (0)
; #define PG8_BAR __builtin_amdgcn_s_barrier()
; #define PG8_SCHED __builtin_amdgcn_sched_barrier(0)
; template <class Epi, class Sched, bool ALIGN_EPI = false, bool SP2 = false, bool HALFM = false, bool AMAP = false>
; __device__ __forceinline__ void gemm_phase(PG8_LAS unsigned char* lds, const Gemm g, const Sched& S, const Epi& E, int tid_in) {
;     ...
;             if constexpr (!HALFM) { PG8_LDA(At, 1, 1); } PG8_STAGE(PG8_SB(1, 0), b3, voffB); PG8_STAGE(PG8_SB(1, 1), b3 + hstepB, voffB); PG8_STAGE(PG8_SA(1, 0), a3, voffA);
;             PG8_WAIT_VK; PG8_WAIT_L(0); PG8_BAR; if constexpr (!HALFM) { PG8_MMA(1, 0, At, B0); PG8_MMA(1, 1, At, B1); } PG8_BAR; PG8_SCHED;
	s_add_i32 s30, s76, s10
	v_lshl_add_u64 v[218:219], v[218:219], 0, s[66:67]
	s_mov_b32 m0, s30
	ds_read_b128 v[160:163], v208 offset:49152
	ds_read_b128 v[164:167], v208 offset:50176
	ds_read_b128 v[168:171], v208 offset:51200
	ds_read_b128 v[192:195], v208 offset:52224
	ds_read_b128 v[196:199], v208 offset:53248
	ds_read_b128 v[200:203], v208 offset:54272
	ds_read_b128 v[210:213], v208 offset:55296
	ds_read_b128 v[214:217], v208 offset:56320
	global_load_lds_dwordx4 v[218:219], off
	s_add_i32 m0, s30, 0x2000
	s_add_u32 s28, s28, 0x80080
	v_lshl_add_u64 v[218:219], v[222:223], 0, s[66:67]
	s_addc_u32 s29, s29, 0
	s_add_i32 s30, s77, s10
	global_load_lds_dwordx4 v[218:219], off
	v_lshl_add_u64 v[218:219], s[28:29], 0, v[176:177]
	s_mov_b32 m0, s30
	s_nop 0
	global_load_lds_dwordx4 v[218:219], off
	v_lshl_add_u64 v[218:219], s[28:29], 0, v[172:173]
	s_add_i32 m0, s30, 0x2000
	s_nop 0
	global_load_lds_dwordx4 v[218:219], off
	v_lshl_add_u64 v[218:219], v[224:225], 0, s[66:67]
	s_mov_b32 m0, s38
	s_nop 0
	global_load_lds_dwordx4 v[218:219], off
	v_lshl_add_u64 v[218:219], v[228:229], 0, s[66:67]
	s_mov_b32 m0, s39
	s_nop 0
	global_load_lds_dwordx4 v[218:219], off
	s_waitcnt vmcnt(8)
	s_waitcnt lgkmcnt(0)
	s_barrier
	s_setprio 1
	v_mfma_f32_16x16x32_bf16 v[68:71], v[16:19], v[160:163], v[68:71]
	v_mfma_f32_16x16x32_bf16 v[52:55], v[16:19], v[168:171], v[52:55]
	v_mfma_f32_16x16x32_bf16 v[36:39], v[16:19], v[196:199], v[36:39]
	v_mfma_f32_16x16x32_bf16 v[0:3], v[16:19], v[210:213], v[0:3]
	v_mfma_f32_16x16x32_bf16 v[68:71], v[20:23], v[164:167], v[68:71]
	v_mfma_f32_16x16x32_bf16 v[64:67], v[136:139], v[160:163], v[64:67]
	v_mfma_f32_16x16x32_bf16 v[52:55], v[20:23], v[192:195], v[52:55]
	v_mfma_f32_16x16x32_bf16 v[48:51], v[136:139], v[168:171], v[48:51]
	v_mfma_f32_16x16x32_bf16 v[36:39], v[20:23], v[200:203], v[36:39]
	v_mfma_f32_16x16x32_bf16 v[32:35], v[136:139], v[196:199], v[32:35]
	v_mfma_f32_16x16x32_bf16 v[20:23], v[20:23], v[214:217], v[0:3]
	v_mfma_f32_16x16x32_bf16 v[0:3], v[136:139], v[210:213], v[4:7]
	v_mfma_f32_16x16x32_bf16 v[64:67], v[140:143], v[164:167], v[64:67]
	v_mfma_f32_16x16x32_bf16 v[48:51], v[140:143], v[192:195], v[48:51]
	v_mfma_f32_16x16x32_bf16 v[32:35], v[140:143], v[200:203], v[32:35]
	v_mfma_f32_16x16x32_bf16 v[16:19], v[140:143], v[214:217], v[0:3]
	s_setprio 0
	s_setprio 1
	v_mfma_f32_16x16x32_bf16 v[0:3], v[144:147], v[160:163], v[60:63]
	v_mfma_f32_16x16x32_bf16 v[60:63], v[148:151], v[164:167], v[0:3]
	v_mfma_f32_16x16x32_bf16 v[0:3], v[152:155], v[160:163], v[56:59]
	v_mfma_f32_16x16x32_bf16 v[56:59], v[156:159], v[164:167], v[0:3]
	v_mfma_f32_16x16x32_bf16 v[0:3], v[144:147], v[168:171], v[44:47]
	v_mfma_f32_16x16x32_bf16 v[44:47], v[148:151], v[192:195], v[0:3]
	v_mfma_f32_16x16x32_bf16 v[0:3], v[152:155], v[168:171], v[40:43]
	v_mfma_f32_16x16x32_bf16 v[40:43], v[156:159], v[192:195], v[0:3]
	v_mfma_f32_16x16x32_bf16 v[0:3], v[144:147], v[196:199], v[28:31]
	v_mfma_f32_16x16x32_bf16 v[28:31], v[148:151], v[200:203], v[0:3]
	v_mfma_f32_16x16x32_bf16 v[0:3], v[152:155], v[196:199], v[24:27]
	v_mfma_f32_16x16x32_bf16 v[24:27], v[156:159], v[200:203], v[0:3]
	v_mfma_f32_16x16x32_bf16 v[0:3], v[144:147], v[210:213], v[12:15]
	v_mfma_f32_16x16x32_bf16 v[12:15], v[148:151], v[214:217], v[0:3]
	v_mfma_f32_16x16x32_bf16 v[0:3], v[152:155], v[210:213], v[8:11]
	v_mfma_f32_16x16x32_bf16 v[8:11], v[156:159], v[214:217], v[0:3]
	s_setprio 0
	s_barrier
	s_add_i32 s63, s63, 2
	s_add_u32 s61, s61, 0x100
	s_addc_u32 s62, s62, 0
	s_add_u32 s6, s6, 0x100
	s_addc_u32 s7, s7, 0
	s_cmp_gt_u32 s63, 29
	s_cbranch_scc0 .LBB0_163
	s_and_b64 vcc, exec, s[20:21]
	s_cbranch_vccz .LBB0_166
	s_barrier

; #define PG8_STAGE(bufoff, gbase, voff) do { _Pragma("unroll") for (int _i = 0; _i < 2; ++_i) \
;         __builtin_amdgcn_global_load_lds((const unsigned*)((const char*)(gbase) + (voff)[_i]), (PG8_LAS unsigned*)(lds + (bufoff) + ldsw + _i * 8192), 16, 0, 0); } while (0)
; #define PG8_LDA(dst, b, h) do { _Pragma("unroll") for (int m = 0; m < 4; ++m) _Pragma("unroll") for (int k = 0; k < 2; ++k) dst[m][k] = *(const PG8_LAS bf16x8*)(lds + PG8_SA(b, h) + aoff + m * 2048 + k * 1024); } while (0)
; #define PG8_LDB(dst, b, h) do { _Pragma("unroll") for (int n = 0; n < 2; ++n) _Pragma("unroll") for (int k = 0; k < 2; ++k) dst[n][k] = *(const PG8_LAS bf16x8*)(lds + PG8_SB(b, h) + boff + n * 2048 + k * 1024); } while (0)
; #define PG8_MMA(ai, bj, At, Bt) do { __builtin_amdgcn_s_setprio(1); _Pragma("unroll") for (int m = 0; m < 4; ++m) _Pragma("unroll") for (int n = 0; n < 2; ++n) _Pragma("unroll") for (int k = 0; k < 2; ++k) \
;         acc[ai][bj][m][n] = __builtin_amdgcn_mfma_f32_16x16x32_bf16(Bt[n][k], At[m][k], acc[ai][bj][m][n], 0, 0, 0); __builtin_amdgcn_s_setprio(0); } while (0)
; #define PG8_WAIT_L(n) asm volatile("s_waitcnt lgkmcnt(" #n ")" ::: "memory")
; #define PG8_WAIT_VK do { if constexpr (HALFM) PG8_WAIT_V(6); else PG8_WAIT_V(8); } while (0)
; #define PG8_BAR __builtin_amdgcn_s_barrier()
; #define PG8_SCHED __builtin_amdgcn_sched_barrier(0)
; template <class Epi, class Sched, bool ALIGN_EPI = false, bool SP2 = false, bool HALFM = false, bool AMAP = false>
; __device__ __forceinline__ void gemm_phase(PG8_LAS unsigned char* lds, const Gemm g, const Sched& S, const Epi& E, int tid_in) {
;     ...
;             PG8_LDB(B0, 0, 0); PG8_LDB(B1, 0, 1); PG8_SCHED; PG8_LDA(At, 0, 0); if constexpr (!HALFM) PG8_STAGE(PG8_SA(1, 1), a1 + hstepA, voffA);
;             PG8_WAIT_VK; PG8_WAIT_L(0); PG8_BAR; PG8_MMA(0, 0, At, B0); PG8_MMA(0, 1, At, B1); PG8_BAR; PG8_SCHED;
;             if constexpr (!HALFM) { PG8_LDA(At, 0, 1); } PG8_STAGE(PG8_SB(0, 0), b2, voffB); PG8_STAGE(PG8_SB(0, 1), b2 + hstepB, voffB); PG8_STAGE(PG8_SA(0, 0), a2, voffA);
;             PG8_WAIT_VK; PG8_WAIT_L(0); PG8_BAR; if constexpr (!HALFM) { PG8_MMA(1, 0, At, B0); PG8_MMA(1, 1, At, B1); } PG8_BAR; PG8_SCHED;
.LBB0_191:
	s_add_i32 s36, 0, 0x10000
	s_cmp_eq_u32 s31, 28
	s_cselect_b64 vcc, -1, 0
	s_cselect_b32 s7, s25, s30
	s_cselect_b32 s6, s28, s29
	s_add_i32 s43, 0, 0x14000
	v_add_u32_e32 v80, s36, v126
	v_add_u32_e32 v96, s43, v126
	ds_read_b128 v[4:7], v80
	ds_read_b128 v[72:75], v80 offset:1024
	ds_read_b128 v[76:79], v80 offset:2048
	ds_read_b128 v[80:83], v80 offset:3072
	ds_read_b128 v[84:87], v96
	ds_read_b128 v[88:91], v96 offset:1024
	ds_read_b128 v[92:95], v96 offset:2048
	ds_read_b128 v[96:99], v96 offset:3072
	v_cndmask_b32_e32 v147, v1, v2, vcc
	v_cndmask_b32_e32 v146, v0, v3, vcc
	ds_read_b128 v[100:103], v129
	ds_read_b128 v[104:107], v129 offset:1024
	ds_read_b128 v[116:119], v129 offset:2048
	ds_read_b128 v[120:123], v129 offset:3072
	ds_read_b128 v[130:133], v129 offset:4096
	ds_read_b128 v[134:137], v129 offset:5120
	ds_read_b128 v[138:141], v129 offset:6144
	ds_read_b128 v[142:145], v129 offset:7168
	s_waitcnt vmcnt(6)
	s_waitcnt lgkmcnt(0)
	s_barrier
	s_setprio 1
	v_mfma_f32_16x16x32_bf16 v[68:71], v[4:7], v[100:103], v[68:71]
	v_mfma_f32_16x16x32_bf16 v[64:67], v[76:79], v[100:103], v[64:67]
	v_mfma_f32_16x16x32_bf16 v[52:55], v[4:7], v[116:119], v[52:55]
	v_mfma_f32_16x16x32_bf16 v[48:51], v[76:79], v[116:119], v[48:51]
	v_mfma_f32_16x16x32_bf16 v[36:39], v[4:7], v[130:133], v[36:39]
	v_mfma_f32_16x16x32_bf16 v[32:35], v[76:79], v[130:133], v[32:35]
	v_mfma_f32_16x16x32_bf16 v[16:19], v[76:79], v[138:141], v[16:19]
	v_mfma_f32_16x16x32_bf16 v[68:71], v[72:75], v[104:107], v[68:71]
	v_mfma_f32_16x16x32_bf16 v[64:67], v[80:83], v[104:107], v[64:67]
	v_mfma_f32_16x16x32_bf16 v[52:55], v[72:75], v[120:123], v[52:55]
	v_mfma_f32_16x16x32_bf16 v[48:51], v[80:83], v[120:123], v[48:51]
	v_mfma_f32_16x16x32_bf16 v[36:39], v[72:75], v[134:137], v[36:39]
	v_mfma_f32_16x16x32_bf16 v[32:35], v[80:83], v[134:137], v[32:35]
	v_mfma_f32_16x16x32_bf16 v[4:7], v[4:7], v[138:141], v[20:23]
	v_mfma_f32_16x16x32_bf16 v[16:19], v[80:83], v[142:145], v[16:19]
	v_mfma_f32_16x16x32_bf16 v[4:7], v[72:75], v[142:145], v[4:7]
	s_setprio 0
	s_setprio 1
	v_mfma_f32_16x16x32_bf16 v[20:23], v[84:87], v[100:103], v[60:63]
	v_mfma_f32_16x16x32_bf16 v[60:63], v[88:91], v[104:107], v[20:23]
	v_mfma_f32_16x16x32_bf16 v[20:23], v[92:95], v[100:103], v[56:59]
	v_mfma_f32_16x16x32_bf16 v[56:59], v[96:99], v[104:107], v[20:23]
	v_mfma_f32_16x16x32_bf16 v[20:23], v[84:87], v[116:119], v[44:47]
	v_mfma_f32_16x16x32_bf16 v[44:47], v[88:91], v[120:123], v[20:23]
	v_mfma_f32_16x16x32_bf16 v[20:23], v[92:95], v[116:119], v[40:43]
	v_mfma_f32_16x16x32_bf16 v[40:43], v[96:99], v[120:123], v[20:23]
	v_mfma_f32_16x16x32_bf16 v[20:23], v[84:87], v[130:133], v[28:31]
	v_mfma_f32_16x16x32_bf16 v[28:31], v[88:91], v[134:137], v[20:23]
	v_mfma_f32_16x16x32_bf16 v[20:23], v[92:95], v[130:133], v[24:27]
	v_mfma_f32_16x16x32_bf16 v[12:15], v[84:87], v[138:141], v[12:15]
	v_mfma_f32_16x16x32_bf16 v[8:11], v[92:95], v[138:141], v[8:11]
	v_mfma_f32_16x16x32_bf16 v[24:27], v[96:99], v[134:137], v[20:23]
	v_mfma_f32_16x16x32_bf16 v[12:15], v[88:91], v[142:145], v[12:15]
	v_mfma_f32_16x16x32_bf16 v[8:11], v[96:99], v[142:145], v[8:11]
	s_setprio 0
	s_barrier
	s_add_i32 s36, s36, s10
	v_lshl_add_u64 v[148:149], s[6:7], 0, v[176:177]
	s_mov_b32 m0, s36
	v_lshl_add_u64 v[150:151], s[6:7], 0, v[108:109]
	global_load_lds_dwordx4 v[148:149], off
	s_add_i32 m0, s36, 0x2000
	s_add_u32 s36, s6, 0x80000
	s_addc_u32 s37, s7, 0
	s_add_i32 s43, s43, s10
	global_load_lds_dwordx4 v[150:151], off
	v_lshl_add_u64 v[20:21], s[36:37], 0, v[176:177]
	s_mov_b32 m0, s43
	v_lshl_add_u64 v[152:153], v[146:147], 0, v[112:113]
	global_load_lds_dwordx4 v[20:21], off
	v_lshl_add_u64 v[20:21], s[36:37], 0, v[108:109]
	s_add_i32 m0, s43, 0x2000
	v_lshl_add_u64 v[146:147], v[146:147], 0, v[110:111]
	global_load_lds_dwordx4 v[20:21], off
	s_mov_b32 m0, s11
	s_nop 0
	global_load_lds_dwordx4 v[152:153], off
	s_mov_b32 m0, s15
	s_nop 0
	global_load_lds_dwordx4 v[146:147], off
	s_waitcnt vmcnt(6)
	s_waitcnt lgkmcnt(0)
	s_barrier
	s_barrier
; #define PG8_STAGE(bufoff, gbase, voff) do { _Pragma("unroll") for (int _i = 0; _i < 2; ++_i) \
;         __builtin_amdgcn_global_load_lds((const unsigned*)((const char*)(gbase) + (voff)[_i]), (PG8_LAS unsigned*)(lds + (bufoff) + ldsw + _i * 8192), 16, 0, 0); } while (0)
; #define PG8_LDA(dst, b, h) do { _Pragma("unroll") for (int m = 0; m < 4; ++m) _Pragma("unroll") for (int k = 0; k < 2; ++k) dst[m][k] = *(const PG8_LAS bf16x8*)(lds + PG8_SA(b, h) + aoff + m * 2048 + k * 1024); } while (0)
; #define PG8_LDB(dst, b, h) do { _Pragma("unroll") for (int n = 0; n < 2; ++n) _Pragma("unroll") for (int k = 0; k < 2; ++k) dst[n][k] = *(const PG8_LAS bf16x8*)(lds + PG8_SB(b, h) + boff + n * 2048 + k * 1024); } while (0)
; #define PG8_MMA(ai, bj, At, Bt) do { __builtin_amdgcn_s_setprio(1); _Pragma("unroll") for (int m = 0; m < 4; ++m) _Pragma("unroll") for (int n = 0; n < 2; ++n) _Pragma("unroll") for (int k = 0; k < 2; ++k) \
;         acc[ai][bj][m][n] = __builtin_amdgcn_mfma_f32_16x16x32_bf16(Bt[n][k], At[m][k], acc[ai][bj][m][n], 0, 0, 0); __builtin_amdgcn_s_setprio(0); } while (0)
; #define PG8_WAIT_L(n) asm volatile("s_waitcnt lgkmcnt(" #n ")" ::: "memory")
; #define PG8_WAIT_VK do { if constexpr (HALFM) PG8_WAIT_V(6); else PG8_WAIT_V(8); } while (0)
; #define PG8_BAR __builtin_amdgcn_s_barrier()
; #define PG8_SCHED __builtin_amdgcn_sched_barrier(0)
; template <class Epi, class Sched, bool ALIGN_EPI = false, bool SP2 = false, bool HALFM = false, bool AMAP = false>
; __device__ __forceinline__ void gemm_phase(PG8_LAS unsigned char* lds, const Gemm g, const Sched& S, const Epi& E, int tid_in) {
;     ...
;             PG8_LDB(B0, 1, 0); PG8_LDB(B1, 1, 1); PG8_SCHED; PG8_LDA(At, 1, 0); if constexpr (!HALFM) PG8_STAGE(PG8_SA(0, 1), a2 + hstepA, voffA);
;             PG8_WAIT_VK; PG8_WAIT_L(0); PG8_BAR; PG8_MMA(0, 0, At, B0); PG8_MMA(0, 1, At, B1); PG8_BAR; PG8_SCHED;
;             if constexpr (!HALFM) { PG8_LDA(At, 1, 1); } PG8_STAGE(PG8_SB(1, 0), b3, voffB); PG8_STAGE(PG8_SB(1, 1), b3 + hstepB, voffB); PG8_STAGE(PG8_SA(1, 0), a3, voffA);
;             PG8_WAIT_VK; PG8_WAIT_L(0); PG8_BAR; if constexpr (!HALFM) { PG8_MMA(1, 0, At, B0); PG8_MMA(1, 1, At, B1); } PG8_BAR; PG8_SCHED;
	s_add_i32 s36, 0, 0x18000
	s_add_i32 s37, 0, 0x1c000
	v_add_u32_e32 v80, s36, v126
	v_add_u32_e32 v96, s37, v126
	ds_read_b128 v[20:23], v80
	ds_read_b128 v[72:75], v80 offset:1024
	ds_read_b128 v[76:79], v80 offset:2048
	ds_read_b128 v[80:83], v80 offset:3072
	ds_read_b128 v[84:87], v96
	ds_read_b128 v[88:91], v96 offset:1024
	ds_read_b128 v[92:95], v96 offset:2048
	ds_read_b128 v[96:99], v96 offset:3072
	ds_read_b128 v[100:103], v129 offset:32768
	ds_read_b128 v[104:107], v129 offset:33792
	ds_read_b128 v[116:119], v129 offset:34816
	ds_read_b128 v[120:123], v129 offset:35840
	ds_read_b128 v[130:133], v129 offset:36864
	ds_read_b128 v[134:137], v129 offset:37888
	ds_read_b128 v[138:141], v129 offset:38912
	ds_read_b128 v[142:145], v129 offset:39936
	s_waitcnt vmcnt(6)
	s_waitcnt lgkmcnt(0)
	s_barrier
	s_setprio 1
	v_mfma_f32_16x16x32_bf16 v[4:7], v[20:23], v[138:141], v[4:7]
	v_mfma_f32_16x16x32_bf16 v[68:71], v[20:23], v[100:103], v[68:71]
	v_mfma_f32_16x16x32_bf16 v[64:67], v[76:79], v[100:103], v[64:67]
	v_mfma_f32_16x16x32_bf16 v[52:55], v[20:23], v[116:119], v[52:55]
	v_mfma_f32_16x16x32_bf16 v[48:51], v[76:79], v[116:119], v[48:51]
	v_mfma_f32_16x16x32_bf16 v[36:39], v[20:23], v[130:133], v[36:39]
	v_mfma_f32_16x16x32_bf16 v[32:35], v[76:79], v[130:133], v[32:35]
	v_mfma_f32_16x16x32_bf16 v[20:23], v[72:75], v[142:145], v[4:7]
	v_mfma_f32_16x16x32_bf16 v[4:7], v[76:79], v[138:141], v[16:19]
	v_mfma_f32_16x16x32_bf16 v[68:71], v[72:75], v[104:107], v[68:71]
	v_mfma_f32_16x16x32_bf16 v[64:67], v[80:83], v[104:107], v[64:67]
	v_mfma_f32_16x16x32_bf16 v[52:55], v[72:75], v[120:123], v[52:55]
	v_mfma_f32_16x16x32_bf16 v[48:51], v[80:83], v[120:123], v[48:51]
	v_mfma_f32_16x16x32_bf16 v[36:39], v[72:75], v[134:137], v[36:39]
	v_mfma_f32_16x16x32_bf16 v[32:35], v[80:83], v[134:137], v[32:35]
	v_mfma_f32_16x16x32_bf16 v[16:19], v[80:83], v[142:145], v[4:7]
	s_setprio 0
	s_setprio 1
	v_mfma_f32_16x16x32_bf16 v[4:7], v[84:87], v[100:103], v[60:63]
	v_mfma_f32_16x16x32_bf16 v[60:63], v[88:91], v[104:107], v[4:7]
	v_mfma_f32_16x16x32_bf16 v[4:7], v[92:95], v[100:103], v[56:59]
	v_mfma_f32_16x16x32_bf16 v[56:59], v[96:99], v[104:107], v[4:7]
	v_mfma_f32_16x16x32_bf16 v[4:7], v[84:87], v[116:119], v[44:47]
	v_mfma_f32_16x16x32_bf16 v[44:47], v[88:91], v[120:123], v[4:7]
	v_mfma_f32_16x16x32_bf16 v[4:7], v[92:95], v[116:119], v[40:43]
	v_mfma_f32_16x16x32_bf16 v[40:43], v[96:99], v[120:123], v[4:7]
	v_mfma_f32_16x16x32_bf16 v[4:7], v[84:87], v[130:133], v[28:31]
	v_mfma_f32_16x16x32_bf16 v[28:31], v[88:91], v[134:137], v[4:7]
	v_mfma_f32_16x16x32_bf16 v[4:7], v[92:95], v[130:133], v[24:27]
	v_mfma_f32_16x16x32_bf16 v[24:27], v[96:99], v[134:137], v[4:7]
	v_mfma_f32_16x16x32_bf16 v[4:7], v[84:87], v[138:141], v[12:15]
	v_mfma_f32_16x16x32_bf16 v[12:15], v[88:91], v[142:145], v[4:7]
	v_mfma_f32_16x16x32_bf16 v[4:7], v[92:95], v[138:141], v[8:11]
	v_mfma_f32_16x16x32_bf16 v[8:11], v[96:99], v[142:145], v[4:7]
	s_setprio 0
	s_barrier
	s_add_i32 s36, s36, s10
	s_nop 3
	v_lshl_add_u64 v[4:5], v[148:149], 0, s[66:67]
	s_mov_b32 m0, s36
	s_nop 0
	global_load_lds_dwordx4 v[4:5], off
	s_add_i32 m0, s36, 0x2000
	s_add_u32 s6, s6, 0x80080
	v_lshl_add_u64 v[4:5], v[150:151], 0, s[66:67]
	s_addc_u32 s7, s7, 0
	s_add_i32 s36, s37, s10
	global_load_lds_dwordx4 v[4:5], off
	v_lshl_add_u64 v[4:5], s[6:7], 0, v[176:177]
	s_mov_b32 m0, s36
	s_nop 0
	global_load_lds_dwordx4 v[4:5], off
	v_lshl_add_u64 v[4:5], s[6:7], 0, v[108:109]
	s_add_i32 m0, s36, 0x2000
	s_nop 0
	global_load_lds_dwordx4 v[4:5], off
	v_lshl_add_u64 v[4:5], v[152:153], 0, s[66:67]
	s_mov_b32 m0, s18
	s_nop 0
	global_load_lds_dwordx4 v[4:5], off
	v_lshl_add_u64 v[4:5], v[146:147], 0, s[66:67]
	s_mov_b32 m0, s19
	s_nop 0
	global_load_lds_dwordx4 v[4:5], off
	s_waitcnt vmcnt(6)
	s_waitcnt lgkmcnt(0)
	s_barrier
	s_barrier
	s_add_i32 s31, s31, 2
	s_add_u32 s29, s29, 0x100
	s_addc_u32 s30, s30, 0
	s_cmp_gt_u32 s31, 29
	v_lshl_add_u64 v[0:1], v[0:1], 0, s[68:69]
	s_cbranch_scc0 .LBB0_191
	s_and_b64 vcc, exec, s[22:23]
	s_cbranch_vccz .LBB0_194
	s_barrier

; #define PG8_STAGE(bufoff, gbase, voff) do { _Pragma("unroll") for (int _i = 0; _i < 2; ++_i) \
;         __builtin_amdgcn_global_load_lds((const unsigned*)((const char*)(gbase) + (voff)[_i]), (PG8_LAS unsigned*)(lds + (bufoff) + ldsw + _i * 8192), 16, 0, 0); } while (0)
; #define PG8_LDA(dst, b, h) do { _Pragma("unroll") for (int m = 0; m < 4; ++m) _Pragma("unroll") for (int k = 0; k < 2; ++k) dst[m][k] = *(const PG8_LAS bf16x8*)(lds + PG8_SA(b, h) + aoff + m * 2048 + k * 1024); } while (0)
; #define PG8_LDB(dst, b, h) do { _Pragma("unroll") for (int n = 0; n < 2; ++n) _Pragma("unroll") for (int k = 0; k < 2; ++k) dst[n][k] = *(const PG8_LAS bf16x8*)(lds + PG8_SB(b, h) + boff + n * 2048 + k * 1024); } while (0)
; #define PG8_MMA(ai, bj, At, Bt) do { __builtin_amdgcn_s_setprio(1); _Pragma("unroll") for (int m = 0; m < 4; ++m) _Pragma("unroll") for (int n = 0; n < 2; ++n) _Pragma("unroll") for (int k = 0; k < 2; ++k) \
;         acc[ai][bj][m][n] = __builtin_amdgcn_mfma_f32_16x16x32_bf16(Bt[n][k], At[m][k], acc[ai][bj][m][n], 0, 0, 0); __builtin_amdgcn_s_setprio(0); } while (0)
; #define PG8_WAIT_L(n) asm volatile("s_waitcnt lgkmcnt(" #n ")" ::: "memory")
; #define PG8_WAIT_VK do { if constexpr (HALFM) PG8_WAIT_V(6); else PG8_WAIT_V(8); } while (0)
; #define PG8_BAR __builtin_amdgcn_s_barrier()
; #define PG8_SCHED __builtin_amdgcn_sched_barrier(0)
; template <class Epi, class Sched, bool ALIGN_EPI = false, bool SP2 = false, bool HALFM = false, bool AMAP = false>
; __device__ __forceinline__ void gemm_phase(PG8_LAS unsigned char* lds, const Gemm g, const Sched& S, const Epi& E, int tid_in) {
;     ...
;             PG8_LDB(B0, 0, 0); PG8_LDB(B1, 0, 1); PG8_SCHED; PG8_LDA(At, 0, 0); if constexpr (!HALFM) PG8_STAGE(PG8_SA(1, 1), a1 + hstepA, voffA);
;             PG8_WAIT_VK; PG8_WAIT_L(0); PG8_BAR; PG8_MMA(0, 0, At, B0); PG8_MMA(0, 1, At, B1); PG8_BAR; PG8_SCHED;
;             if constexpr (!HALFM) { PG8_LDA(At, 0, 1); } PG8_STAGE(PG8_SB(0, 0), b2, voffB); PG8_STAGE(PG8_SB(0, 1), b2 + hstepB, voffB); PG8_STAGE(PG8_SA(0, 0), a2, voffA);
;             PG8_WAIT_VK; PG8_WAIT_L(0); PG8_BAR; if constexpr (!HALFM) { PG8_MMA(1, 0, At, B0); PG8_MMA(1, 1, At, B1); } PG8_BAR; PG8_SCHED;
.LBB0_276:
	s_add_i32 s29, 0, 0x10000
	s_cmpk_eq_i32 s28, 0x54
	s_cselect_b64 vcc, -1, 0
	s_cselect_b32 s11, s59, s5
	s_cselect_b32 s10, s58, s4
	s_add_i32 s76, 0, 0x14000
	v_add_u32_e32 v144, s29, v193
	v_add_u32_e32 v172, s76, v193
	ds_read_b128 v[132:135], v144
	ds_read_b128 v[136:139], v144 offset:1024
	ds_read_b128 v[140:143], v144 offset:2048
	ds_read_b128 v[144:147], v144 offset:3072
	ds_read_b128 v[148:151], v172
	ds_read_b128 v[152:155], v172 offset:1024
	ds_read_b128 v[168:171], v172 offset:2048
	ds_read_b128 v[172:175], v172 offset:3072
	v_lshl_add_u64 v[130:131], v[128:129], 0, s[68:69]
	v_cndmask_b32_e32 v223, v131, v167, vcc
	v_cndmask_b32_e32 v222, v130, v166, vcc
	v_lshl_add_u64 v[224:225], v[128:129], 0, v[164:165]
	s_add_i32 m0, s19, 0xc000
	ds_read_b128 v[184:187], v195
	ds_read_b128 v[188:191], v195 offset:1024
	ds_read_b128 v[196:199], v195 offset:2048
	ds_read_b128 v[200:203], v195 offset:3072
	ds_read_b128 v[204:207], v195 offset:4096
	ds_read_b128 v[208:211], v195 offset:5120
	ds_read_b128 v[212:215], v195 offset:6144
	ds_read_b128 v[216:219], v195 offset:7168
	global_load_lds_dwordx4 v[224:225], off
	v_lshl_add_u64 v[128:129], v[128:129], 0, v[162:163]
	s_add_i32 m0, s19, 0xe000
	s_nop 0
	global_load_lds_dwordx4 v[128:129], off
	s_waitcnt vmcnt(8)
	s_waitcnt lgkmcnt(0)
	s_barrier
	s_setprio 1
	v_mfma_f32_16x16x32_bf16 v[124:127], v[132:135], v[184:187], v[124:127]
	v_mfma_f32_16x16x32_bf16 v[120:123], v[140:143], v[184:187], v[120:123]
	v_mfma_f32_16x16x32_bf16 v[108:111], v[132:135], v[196:199], v[108:111]
	v_mfma_f32_16x16x32_bf16 v[104:107], v[140:143], v[196:199], v[104:107]
	v_mfma_f32_16x16x32_bf16 v[92:95], v[132:135], v[204:207], v[92:95]
	v_mfma_f32_16x16x32_bf16 v[88:91], v[140:143], v[204:207], v[88:91]
	v_mfma_f32_16x16x32_bf16 v[76:79], v[132:135], v[212:215], v[76:79]
	v_mfma_f32_16x16x32_bf16 v[72:75], v[140:143], v[212:215], v[72:75]
	v_mfma_f32_16x16x32_bf16 v[124:127], v[136:139], v[188:191], v[124:127]
	v_mfma_f32_16x16x32_bf16 v[120:123], v[144:147], v[188:191], v[120:123]
	v_mfma_f32_16x16x32_bf16 v[108:111], v[136:139], v[200:203], v[108:111]
	v_mfma_f32_16x16x32_bf16 v[104:107], v[144:147], v[200:203], v[104:107]
	v_mfma_f32_16x16x32_bf16 v[92:95], v[136:139], v[208:211], v[92:95]
	v_mfma_f32_16x16x32_bf16 v[88:91], v[144:147], v[208:211], v[88:91]
	v_mfma_f32_16x16x32_bf16 v[76:79], v[136:139], v[216:219], v[76:79]
	v_mfma_f32_16x16x32_bf16 v[72:75], v[144:147], v[216:219], v[72:75]
	s_setprio 0
	s_setprio 1
	v_mfma_f32_16x16x32_bf16 v[116:119], v[148:151], v[184:187], v[116:119]
	v_mfma_f32_16x16x32_bf16 v[112:115], v[168:171], v[184:187], v[112:115]
	v_mfma_f32_16x16x32_bf16 v[100:103], v[148:151], v[196:199], v[100:103]
	v_mfma_f32_16x16x32_bf16 v[96:99], v[168:171], v[196:199], v[96:99]
	v_mfma_f32_16x16x32_bf16 v[84:87], v[148:151], v[204:207], v[84:87]
	v_mfma_f32_16x16x32_bf16 v[80:83], v[168:171], v[204:207], v[80:83]
	v_mfma_f32_16x16x32_bf16 v[68:71], v[148:151], v[212:215], v[68:71]
	v_mfma_f32_16x16x32_bf16 v[64:67], v[168:171], v[212:215], v[64:67]
	v_mfma_f32_16x16x32_bf16 v[116:119], v[152:155], v[188:191], v[116:119]
	v_mfma_f32_16x16x32_bf16 v[112:115], v[172:175], v[188:191], v[112:115]
	v_mfma_f32_16x16x32_bf16 v[100:103], v[152:155], v[200:203], v[100:103]
	v_mfma_f32_16x16x32_bf16 v[96:99], v[172:175], v[200:203], v[96:99]
	v_mfma_f32_16x16x32_bf16 v[84:87], v[152:155], v[208:211], v[84:87]
	v_mfma_f32_16x16x32_bf16 v[80:83], v[172:175], v[208:211], v[80:83]
	v_mfma_f32_16x16x32_bf16 v[68:71], v[152:155], v[216:219], v[68:71]
	v_mfma_f32_16x16x32_bf16 v[64:67], v[172:175], v[216:219], v[64:67]
	s_setprio 0
	s_barrier
	s_add_i32 s29, s29, s18
	v_lshl_add_u64 v[128:129], s[10:11], 0, v[176:177]
	s_mov_b32 m0, s29
	ds_read_b128 v[184:187], v195 offset:16384
	ds_read_b128 v[188:191], v195 offset:17408
	ds_read_b128 v[196:199], v195 offset:18432
	ds_read_b128 v[200:203], v195 offset:19456
	ds_read_b128 v[204:207], v195 offset:20480
	ds_read_b128 v[208:211], v195 offset:21504
	ds_read_b128 v[212:215], v195 offset:22528
	ds_read_b128 v[216:219], v195 offset:23552
	global_load_lds_dwordx4 v[128:129], off
	s_add_i32 m0, s29, 0x2000
	s_add_u32 s30, s10, 0x160000
	v_lshl_add_u64 v[224:225], s[10:11], 0, v[156:157]
	s_addc_u32 s31, s11, 0
	s_add_i32 s29, s76, s18
	global_load_lds_dwordx4 v[224:225], off
	v_lshl_add_u64 v[228:229], s[30:31], 0, v[176:177]
	s_mov_b32 m0, s29
	v_lshl_add_u64 v[230:231], v[222:223], 0, v[158:159]
	global_load_lds_dwordx4 v[228:229], off
	v_lshl_add_u64 v[228:229], s[30:31], 0, v[156:157]
	s_add_i32 m0, s29, 0x2000
	s_nop 0
	global_load_lds_dwordx4 v[228:229], off
	v_lshl_add_u64 v[228:229], v[222:223], 0, v[160:161]
	s_mov_b32 m0, s19
	s_nop 0
	global_load_lds_dwordx4 v[228:229], off
	s_mov_b32 m0, s25
	s_nop 0
	global_load_lds_dwordx4 v[230:231], off
	s_waitcnt vmcnt(8)
	s_waitcnt lgkmcnt(0)
	s_barrier
; #define PG8_STAGE(bufoff, gbase, voff) do { _Pragma("unroll") for (int _i = 0; _i < 2; ++_i) \
;         __builtin_amdgcn_global_load_lds((const unsigned*)((const char*)(gbase) + (voff)[_i]), (PG8_LAS unsigned*)(lds + (bufoff) + ldsw + _i * 8192), 16, 0, 0); } while (0)
; #define PG8_LDA(dst, b, h) do { _Pragma("unroll") for (int m = 0; m < 4; ++m) _Pragma("unroll") for (int k = 0; k < 2; ++k) dst[m][k] = *(const PG8_LAS bf16x8*)(lds + PG8_SA(b, h) + aoff + m * 2048 + k * 1024); } while (0)
; #define PG8_LDB(dst, b, h) do { _Pragma("unroll") for (int n = 0; n < 2; ++n) _Pragma("unroll") for (int k = 0; k < 2; ++k) dst[n][k] = *(const PG8_LAS bf16x8*)(lds + PG8_SB(b, h) + boff + n * 2048 + k * 1024); } while (0)
; #define PG8_MMA(ai, bj, At, Bt) do { __builtin_amdgcn_s_setprio(1); _Pragma("unroll") for (int m = 0; m < 4; ++m) _Pragma("unroll") for (int n = 0; n < 2; ++n) _Pragma("unroll") for (int k = 0; k < 2; ++k) \
;         acc[ai][bj][m][n] = __builtin_amdgcn_mfma_f32_16x16x32_bf16(Bt[n][k], At[m][k], acc[ai][bj][m][n], 0, 0, 0); __builtin_amdgcn_s_setprio(0); } while (0)
; #define PG8_WAIT_L(n) asm volatile("s_waitcnt lgkmcnt(" #n ")" ::: "memory")
; #define PG8_WAIT_VK do { if constexpr (HALFM) PG8_WAIT_V(6); else PG8_WAIT_V(8); } while (0)
; #define PG8_BAR __builtin_amdgcn_s_barrier()
; #define PG8_SCHED __builtin_amdgcn_sched_barrier(0)
; template <class Epi, class Sched, bool ALIGN_EPI = false, bool SP2 = false, bool HALFM = false, bool AMAP = false>
; __device__ __forceinline__ void gemm_phase(PG8_LAS unsigned char* lds, const Gemm g, const Sched& S, const Epi& E, int tid_in) {
;     ...
;             PG8_WAIT_VK; PG8_WAIT_L(0); PG8_BAR; if constexpr (!HALFM) { PG8_MMA(1, 0, At, B0); PG8_MMA(1, 1, At, B1); } PG8_BAR; PG8_SCHED;
;             PG8_LDB(B0, 1, 0); PG8_LDB(B1, 1, 1); PG8_SCHED; PG8_LDA(At, 1, 0); if constexpr (!HALFM) PG8_STAGE(PG8_SA(0, 1), a2 + hstepA, voffA);
;             PG8_WAIT_VK; PG8_WAIT_L(0); PG8_BAR; PG8_MMA(0, 0, At, B0); PG8_MMA(0, 1, At, B1); PG8_BAR; PG8_SCHED;
	s_setprio 1
	v_mfma_f32_16x16x32_bf16 v[60:63], v[132:135], v[184:187], v[60:63]
	v_mfma_f32_16x16x32_bf16 v[56:59], v[140:143], v[184:187], v[56:59]
	v_mfma_f32_16x16x32_bf16 v[44:47], v[132:135], v[196:199], v[44:47]
	v_mfma_f32_16x16x32_bf16 v[40:43], v[140:143], v[196:199], v[40:43]
	v_mfma_f32_16x16x32_bf16 v[28:31], v[132:135], v[204:207], v[28:31]
	v_mfma_f32_16x16x32_bf16 v[24:27], v[140:143], v[204:207], v[24:27]
	v_mfma_f32_16x16x32_bf16 v[12:15], v[132:135], v[212:215], v[12:15]
	v_mfma_f32_16x16x32_bf16 v[8:11], v[140:143], v[212:215], v[8:11]
	v_mfma_f32_16x16x32_bf16 v[60:63], v[136:139], v[188:191], v[60:63]
	v_mfma_f32_16x16x32_bf16 v[56:59], v[144:147], v[188:191], v[56:59]
	v_mfma_f32_16x16x32_bf16 v[44:47], v[136:139], v[200:203], v[44:47]
	v_mfma_f32_16x16x32_bf16 v[40:43], v[144:147], v[200:203], v[40:43]
	v_mfma_f32_16x16x32_bf16 v[28:31], v[136:139], v[208:211], v[28:31]
	v_mfma_f32_16x16x32_bf16 v[24:27], v[144:147], v[208:211], v[24:27]
	v_mfma_f32_16x16x32_bf16 v[12:15], v[136:139], v[216:219], v[12:15]
	v_mfma_f32_16x16x32_bf16 v[8:11], v[144:147], v[216:219], v[8:11]
	s_setprio 0
	s_setprio 1
	v_mfma_f32_16x16x32_bf16 v[52:55], v[148:151], v[184:187], v[52:55]
	v_mfma_f32_16x16x32_bf16 v[48:51], v[168:171], v[184:187], v[48:51]
	v_mfma_f32_16x16x32_bf16 v[36:39], v[148:151], v[196:199], v[36:39]
	v_mfma_f32_16x16x32_bf16 v[32:35], v[168:171], v[196:199], v[32:35]
	v_mfma_f32_16x16x32_bf16 v[20:23], v[148:151], v[204:207], v[20:23]
	v_mfma_f32_16x16x32_bf16 v[16:19], v[168:171], v[204:207], v[16:19]
	v_mfma_f32_16x16x32_bf16 v[4:7], v[148:151], v[212:215], v[4:7]
	v_mfma_f32_16x16x32_bf16 v[0:3], v[168:171], v[212:215], v[0:3]
	v_mfma_f32_16x16x32_bf16 v[52:55], v[152:155], v[188:191], v[52:55]
	v_mfma_f32_16x16x32_bf16 v[48:51], v[172:175], v[188:191], v[48:51]
	v_mfma_f32_16x16x32_bf16 v[36:39], v[152:155], v[200:203], v[36:39]
	v_mfma_f32_16x16x32_bf16 v[32:35], v[172:175], v[200:203], v[32:35]
	v_mfma_f32_16x16x32_bf16 v[20:23], v[152:155], v[208:211], v[20:23]
	v_mfma_f32_16x16x32_bf16 v[16:19], v[172:175], v[208:211], v[16:19]
	v_mfma_f32_16x16x32_bf16 v[4:7], v[152:155], v[216:219], v[4:7]
	v_mfma_f32_16x16x32_bf16 v[0:3], v[172:175], v[216:219], v[0:3]
	s_setprio 0
	s_barrier
	s_add_i32 s29, 0, 0x18000
	s_add_i32 s30, 0, 0x1c000
	v_add_u32_e32 v144, s29, v193
	v_add_u32_e32 v172, s30, v193
	ds_read_b128 v[132:135], v144
	ds_read_b128 v[136:139], v144 offset:1024
	ds_read_b128 v[140:143], v144 offset:2048
	ds_read_b128 v[144:147], v144 offset:3072
	ds_read_b128 v[148:151], v172
	ds_read_b128 v[152:155], v172 offset:1024
	ds_read_b128 v[168:171], v172 offset:2048
	ds_read_b128 v[172:175], v172 offset:3072
	v_lshl_add_u64 v[222:223], v[222:223], 0, s[78:79]
	s_mov_b32 m0, s36
	v_lshl_add_u64 v[232:233], v[222:223], 0, v[160:161]
	ds_read_b128 v[184:187], v195 offset:32768
	ds_read_b128 v[188:191], v195 offset:33792
	ds_read_b128 v[196:199], v195 offset:34816
	ds_read_b128 v[200:203], v195 offset:35840
	ds_read_b128 v[204:207], v195 offset:36864
	ds_read_b128 v[208:211], v195 offset:37888
	ds_read_b128 v[212:215], v195 offset:38912
	ds_read_b128 v[216:219], v195 offset:39936
	global_load_lds_dwordx4 v[232:233], off
	v_lshl_add_u64 v[222:223], v[222:223], 0, v[158:159]
	s_mov_b32 m0, s37
	s_nop 0
	global_load_lds_dwordx4 v[222:223], off
	s_waitcnt vmcnt(8)
	s_waitcnt lgkmcnt(0)
	s_barrier
	s_setprio 1
	v_mfma_f32_16x16x32_bf16 v[124:127], v[132:135], v[184:187], v[124:127]
	v_mfma_f32_16x16x32_bf16 v[120:123], v[140:143], v[184:187], v[120:123]
	v_mfma_f32_16x16x32_bf16 v[108:111], v[132:135], v[196:199], v[108:111]
	v_mfma_f32_16x16x32_bf16 v[104:107], v[140:143], v[196:199], v[104:107]
	v_mfma_f32_16x16x32_bf16 v[92:95], v[132:135], v[204:207], v[92:95]
	v_mfma_f32_16x16x32_bf16 v[88:91], v[140:143], v[204:207], v[88:91]
	v_mfma_f32_16x16x32_bf16 v[76:79], v[132:135], v[212:215], v[76:79]
	v_mfma_f32_16x16x32_bf16 v[72:75], v[140:143], v[212:215], v[72:75]
	v_mfma_f32_16x16x32_bf16 v[124:127], v[136:139], v[188:191], v[124:127]
	v_mfma_f32_16x16x32_bf16 v[120:123], v[144:147], v[188:191], v[120:123]
	v_mfma_f32_16x16x32_bf16 v[108:111], v[136:139], v[200:203], v[108:111]
	v_mfma_f32_16x16x32_bf16 v[104:107], v[144:147], v[200:203], v[104:107]
	v_mfma_f32_16x16x32_bf16 v[92:95], v[136:139], v[208:211], v[92:95]
	v_mfma_f32_16x16x32_bf16 v[88:91], v[144:147], v[208:211], v[88:91]
	v_mfma_f32_16x16x32_bf16 v[76:79], v[136:139], v[216:219], v[76:79]
	v_mfma_f32_16x16x32_bf16 v[72:75], v[144:147], v[216:219], v[72:75]
	s_setprio 0
	s_setprio 1
	v_mfma_f32_16x16x32_bf16 v[116:119], v[148:151], v[184:187], v[116:119]
	v_mfma_f32_16x16x32_bf16 v[112:115], v[168:171], v[184:187], v[112:115]
	v_mfma_f32_16x16x32_bf16 v[100:103], v[148:151], v[196:199], v[100:103]
	v_mfma_f32_16x16x32_bf16 v[96:99], v[168:171], v[196:199], v[96:99]
	v_mfma_f32_16x16x32_bf16 v[84:87], v[148:151], v[204:207], v[84:87]
	v_mfma_f32_16x16x32_bf16 v[80:83], v[168:171], v[204:207], v[80:83]
	v_mfma_f32_16x16x32_bf16 v[68:71], v[148:151], v[212:215], v[68:71]
	v_mfma_f32_16x16x32_bf16 v[64:67], v[168:171], v[212:215], v[64:67]
	v_mfma_f32_16x16x32_bf16 v[116:119], v[152:155], v[188:191], v[116:119]
	v_mfma_f32_16x16x32_bf16 v[112:115], v[172:175], v[188:191], v[112:115]
	v_mfma_f32_16x16x32_bf16 v[100:103], v[152:155], v[200:203], v[100:103]
	v_mfma_f32_16x16x32_bf16 v[96:99], v[172:175], v[200:203], v[96:99]
	v_mfma_f32_16x16x32_bf16 v[84:87], v[152:155], v[208:211], v[84:87]
	v_mfma_f32_16x16x32_bf16 v[80:83], v[172:175], v[208:211], v[80:83]
	v_mfma_f32_16x16x32_bf16 v[68:71], v[152:155], v[216:219], v[68:71]
	v_mfma_f32_16x16x32_bf16 v[64:67], v[172:175], v[216:219], v[64:67]
	s_setprio 0
	s_barrier
; #define PG8_STAGE(bufoff, gbase, voff) do { _Pragma("unroll") for (int _i = 0; _i < 2; ++_i) \
;         __builtin_amdgcn_global_load_lds((const unsigned*)((const char*)(gbase) + (voff)[_i]), (PG8_LAS unsigned*)(lds + (bufoff) + ldsw + _i * 8192), 16, 0, 0); } while (0)
; #define PG8_LDA(dst, b, h) do { _Pragma("unroll") for (int m = 0; m < 4; ++m) _Pragma("unroll") for (int k = 0; k < 2; ++k) dst[m][k] = *(const PG8_LAS bf16x8*)(lds + PG8_SA(b, h) + aoff + m * 2048 + k * 1024); } while (0)
; #define PG8_MMA(ai, bj, At, Bt) do { __builtin_amdgcn_s_setprio(1); _Pragma("unroll") for (int m = 0; m < 4; ++m) _Pragma("unroll") for (int n = 0; n < 2; ++n) _Pragma("unroll") for (int k = 0; k < 2; ++k) \
;         acc[ai][bj][m][n] = __builtin_amdgcn_mfma_f32_16x16x32_bf16(Bt[n][k], At[m][k], acc[ai][bj][m][n], 0, 0, 0); __builtin_amdgcn_s_setprio(0); } while (0)
; #define PG8_WAIT_L(n) asm volatile("s_waitcnt lgkmcnt(" #n ")" ::: "memory")
; #define PG8_WAIT_VK do { if constexpr (HALFM) PG8_WAIT_V(6); else PG8_WAIT_V(8); } while (0)
; #define PG8_BAR __builtin_amdgcn_s_barrier()
; #define PG8_SCHED __builtin_amdgcn_sched_barrier(0)
; template <class Epi, class Sched, bool ALIGN_EPI = false, bool SP2 = false, bool HALFM = false, bool AMAP = false>
; __device__ __forceinline__ void gemm_phase(PG8_LAS unsigned char* lds, const Gemm g, const Sched& S, const Epi& E, int tid_in) {
;     ...
;             if constexpr (!HALFM) { PG8_LDA(At, 1, 1); } PG8_STAGE(PG8_SB(1, 0), b3, voffB); PG8_STAGE(PG8_SB(1, 1), b3 + hstepB, voffB); PG8_STAGE(PG8_SA(1, 0), a3, voffA);
;             PG8_WAIT_VK; PG8_WAIT_L(0); PG8_BAR; if constexpr (!HALFM) { PG8_MMA(1, 0, At, B0); PG8_MMA(1, 1, At, B1); } PG8_BAR; PG8_SCHED;
	s_add_i32 s29, s29, s18
	v_lshl_add_u64 v[128:129], v[128:129], 0, s[66:67]
	s_mov_b32 m0, s29
	ds_read_b128 v[184:187], v195 offset:49152
	ds_read_b128 v[188:191], v195 offset:50176
	ds_read_b128 v[196:199], v195 offset:51200
	ds_read_b128 v[200:203], v195 offset:52224
	ds_read_b128 v[204:207], v195 offset:53248
	ds_read_b128 v[208:211], v195 offset:54272
	ds_read_b128 v[212:215], v195 offset:55296
	ds_read_b128 v[216:219], v195 offset:56320
	global_load_lds_dwordx4 v[128:129], off
	s_add_i32 m0, s29, 0x2000
	s_add_u32 s10, s10, 0x160080
	v_lshl_add_u64 v[128:129], v[224:225], 0, s[66:67]
	s_addc_u32 s11, s11, 0
	s_add_i32 s29, s30, s18
	global_load_lds_dwordx4 v[128:129], off
	v_lshl_add_u64 v[128:129], s[10:11], 0, v[176:177]
	s_mov_b32 m0, s29
	s_nop 0
	global_load_lds_dwordx4 v[128:129], off
	v_lshl_add_u64 v[128:129], s[10:11], 0, v[156:157]
	s_add_i32 m0, s29, 0x2000
	s_nop 0
	global_load_lds_dwordx4 v[128:129], off
	v_lshl_add_u64 v[128:129], v[228:229], 0, s[66:67]
	s_mov_b32 m0, s39
	s_nop 0
	global_load_lds_dwordx4 v[128:129], off
	v_lshl_add_u64 v[128:129], v[230:231], 0, s[66:67]
	s_mov_b32 m0, s60
	s_nop 0
	global_load_lds_dwordx4 v[128:129], off
	s_waitcnt vmcnt(8)
	s_waitcnt lgkmcnt(0)
	s_barrier
	s_setprio 1
	v_mfma_f32_16x16x32_bf16 v[60:63], v[132:135], v[184:187], v[60:63]
	v_mfma_f32_16x16x32_bf16 v[56:59], v[140:143], v[184:187], v[56:59]
	v_mfma_f32_16x16x32_bf16 v[44:47], v[132:135], v[196:199], v[44:47]
	v_mfma_f32_16x16x32_bf16 v[40:43], v[140:143], v[196:199], v[40:43]
	v_mfma_f32_16x16x32_bf16 v[28:31], v[132:135], v[204:207], v[28:31]
	v_mfma_f32_16x16x32_bf16 v[24:27], v[140:143], v[204:207], v[24:27]
	v_mfma_f32_16x16x32_bf16 v[12:15], v[132:135], v[212:215], v[12:15]
	v_mfma_f32_16x16x32_bf16 v[8:11], v[140:143], v[212:215], v[8:11]
	v_mfma_f32_16x16x32_bf16 v[60:63], v[136:139], v[188:191], v[60:63]
	v_mfma_f32_16x16x32_bf16 v[56:59], v[144:147], v[188:191], v[56:59]
	v_mfma_f32_16x16x32_bf16 v[44:47], v[136:139], v[200:203], v[44:47]
	v_mfma_f32_16x16x32_bf16 v[40:43], v[144:147], v[200:203], v[40:43]
	v_mfma_f32_16x16x32_bf16 v[28:31], v[136:139], v[208:211], v[28:31]
	v_mfma_f32_16x16x32_bf16 v[24:27], v[144:147], v[208:211], v[24:27]
	v_mfma_f32_16x16x32_bf16 v[12:15], v[136:139], v[216:219], v[12:15]
	v_mfma_f32_16x16x32_bf16 v[8:11], v[144:147], v[216:219], v[8:11]
	s_setprio 0
	s_setprio 1
	v_mfma_f32_16x16x32_bf16 v[52:55], v[148:151], v[184:187], v[52:55]
	v_mfma_f32_16x16x32_bf16 v[48:51], v[168:171], v[184:187], v[48:51]
	v_mfma_f32_16x16x32_bf16 v[36:39], v[148:151], v[196:199], v[36:39]
	v_mfma_f32_16x16x32_bf16 v[32:35], v[168:171], v[196:199], v[32:35]
	v_mfma_f32_16x16x32_bf16 v[20:23], v[148:151], v[204:207], v[20:23]
	v_mfma_f32_16x16x32_bf16 v[16:19], v[168:171], v[204:207], v[16:19]
	v_mfma_f32_16x16x32_bf16 v[4:7], v[148:151], v[212:215], v[4:7]
	v_mfma_f32_16x16x32_bf16 v[0:3], v[168:171], v[212:215], v[0:3]
	v_mfma_f32_16x16x32_bf16 v[52:55], v[152:155], v[188:191], v[52:55]
	v_mfma_f32_16x16x32_bf16 v[48:51], v[172:175], v[188:191], v[48:51]
	v_mfma_f32_16x16x32_bf16 v[36:39], v[152:155], v[200:203], v[36:39]
	v_mfma_f32_16x16x32_bf16 v[32:35], v[172:175], v[200:203], v[32:35]
	v_mfma_f32_16x16x32_bf16 v[20:23], v[152:155], v[208:211], v[20:23]
	v_mfma_f32_16x16x32_bf16 v[16:19], v[172:175], v[208:211], v[16:19]
	v_mfma_f32_16x16x32_bf16 v[4:7], v[152:155], v[216:219], v[4:7]
	v_mfma_f32_16x16x32_bf16 v[0:3], v[172:175], v[216:219], v[0:3]
	s_setprio 0
	s_barrier
	s_add_i32 s28, s28, 2
	s_add_u32 s4, s4, 0x100
	s_addc_u32 s5, s5, 0
	s_cmpk_gt_u32 s28, 0x55
	v_mov_b64_e32 v[128:129], v[130:131]
	s_cbranch_scc0 .LBB0_276
	s_and_b64 vcc, exec, s[48:49]
	s_cbranch_vccz .LBB0_279
	s_barrier
; __device__ __forceinline__ int opaque0() { int z; asm volatile("v_mov_b32 %0, 0" : "=v"(z)); return z; }
;     __device__ __forceinline__ void operator()(const f32x4 (&acc)[2][2][4][2], const Unit& u, int wr, int wc, int fr, int fq) const {
;         const int z = opaque0(); const int row0 = u.pm * BM + wr * 64 + fr + z, col0 = u.pn * BM + wc * 32 + 8 * fq + z;
; #pragma unroll
;         for (int ai = 0; ai < 2; ++ai) {
;             u32x4 rb[4][2];
; #pragma unroll
;             for (int m = 0; m < 4; ++m) { const size_t off = (size_t)(row0 + ai * HALF + m * 16) * 2048 + col0;
; #pragma unroll
;                 for (int bj = 0; bj < 2; ++bj) rb[m][bj] = *(const u32x4*)(xb + off + bj * HALF); }
;             __builtin_amdgcn_sched_barrier(0);
; #pragma unroll
;             for (int m = 0; m < 4; ++m) { const int row = row0 + ai * HALF + m * 16; const size_t off = (size_t)row * 2048 + col0; float sq = 0.f;
; #pragma unroll
;                 for (int bj = 0; bj < 2; ++bj) { const u32x4 r = rb[m][bj];
;                     const f32x4 b0 = (f32x4){__builtin_bit_cast(float, r.x << 16), __builtin_bit_cast(float, r.x & 0xffff0000u), __builtin_bit_cast(float, r.y << 16), __builtin_bit_cast(float, r.y & 0xffff0000u)};
;                     const f32x4 b1 = (f32x4){__builtin_bit_cast(float, r.z << 16), __builtin_bit_cast(float, r.z & 0xffff0000u), __builtin_bit_cast(float, r.w << 16), __builtin_bit_cast(float, r.w & 0xffff0000u)};
;                     const f32x4 o0 = b0 + acc[ai][bj][m][0] * alpha, o1 = b1 + acc[ai][bj][m][1] * alpha;
.LBB0_279:
	s_lshl_b32 s4, s81, 8
	v_lshl_or_b32 v129, s80, 8, v194
	v_mov_b32 v128, 0
	s_nop 0
	v_add3_u32 v172, s4, v192, v128
	v_add_u32_e32 v170, v129, v128
	v_ashrrev_i32_e32 v171, 31, v170
	v_ashrrev_i32_e32 v173, 31, v172
	v_lshl_add_u64 v[168:169], v[170:171], 1, s[46:47]
	v_lshlrev_b64 v[128:129], 12, v[172:173]
	v_add_u32_e32 v186, 16, v172
	v_lshl_add_u64 v[128:129], v[168:169], 0, v[128:129]
	v_ashrrev_i32_e32 v187, 31, v186
	global_load_dwordx4 v[196:199], v[128:129], off
	global_load_dwordx4 v[152:155], v[128:129], off offset:256
	v_lshlrev_b64 v[128:129], 12, v[186:187]
	v_add_u32_e32 v184, 32, v172
	v_lshl_add_u64 v[128:129], v[168:169], 0, v[128:129]
	v_ashrrev_i32_e32 v185, 31, v184
	global_load_dwordx4 v[148:151], v[128:129], off
	global_load_dwordx4 v[144:147], v[128:129], off offset:256
	v_lshlrev_b64 v[128:129], 12, v[184:185]
	v_add_u32_e32 v174, 48, v172
	v_lshl_add_u64 v[128:129], v[168:169], 0, v[128:129]
	v_ashrrev_i32_e32 v175, 31, v174
	global_load_dwordx4 v[140:143], v[128:129], off
	global_load_dwordx4 v[136:139], v[128:129], off offset:256
	v_lshlrev_b64 v[128:129], 12, v[174:175]
	v_lshl_add_u64 v[128:129], v[168:169], 0, v[128:129]
	global_load_dwordx4 v[132:135], v[128:129], off
	s_nop 0
	global_load_dwordx4 v[128:131], v[128:129], off offset:256
	v_add_u32_e32 v236, 0x80, v172
	v_ashrrev_i32_e32 v237, 31, v236
	v_lshlrev_b64 v[238:239], 12, v[236:237]
	v_lshl_add_u64 v[238:239], v[168:169], 0, v[238:239]
	global_load_dwordx4 v[180:183], v[238:239], off
	global_load_dwordx4 v[204:207], v[238:239], off offset:256
	v_add_u32_e32 v236, 0x90, v172
	v_ashrrev_i32_e32 v237, 31, v236
	v_lshlrev_b64 v[238:239], 12, v[236:237]
	v_lshl_add_u64 v[238:239], v[168:169], 0, v[238:239]
	global_load_dwordx4 v[208:211], v[238:239], off
	global_load_dwordx4 v[212:215], v[238:239], off offset:256
	v_add_u32_e32 v236, 0xa0, v172
	v_ashrrev_i32_e32 v237, 31, v236
	v_lshlrev_b64 v[238:239], 12, v[236:237]
	v_lshl_add_u64 v[238:239], v[168:169], 0, v[238:239]
	global_load_dwordx4 v[216:219], v[238:239], off
	global_load_dwordx4 v[222:225], v[238:239], off offset:256
	v_add_u32_e32 v236, 0xb0, v172
	v_ashrrev_i32_e32 v237, 31, v236
	v_lshlrev_b64 v[238:239], 12, v[236:237]
	v_lshl_add_u64 v[238:239], v[168:169], 0, v[238:239]
	global_load_dwordx4 v[228:231], v[238:239], off
	global_load_dwordx4 v[232:235], v[238:239], off offset:256
	v_lshlrev_b64 v[188:189], 11, v[172:173]
	v_lshl_add_u64 v[190:191], v[188:189], 0, v[170:171]
	s_waitcnt vmcnt(8)
	v_lshlrev_b32_e32 v200, 16, v196
	v_and_b32_e32 v201, 0xffff0000, v196
	v_lshlrev_b32_e32 v196, 16, v197
	v_and_b32_e32 v197, 0xffff0000, v197
	v_lshlrev_b32_e32 v202, 16, v198
	v_and_b32_e32 v203, 0xffff0000, v198
	v_lshlrev_b32_e32 v198, 16, v199
	v_and_b32_e32 v199, 0xffff0000, v199
	v_cndmask_b32_e64 v178, 0, 1, s[42:43]
	v_pk_fma_f32 v[126:127], v[126:127], 0.5, v[196:197] op_sel_hi:[1,0,1]
	v_pk_fma_f32 v[124:125], v[124:125], 0.5, v[200:201] op_sel_hi:[1,0,1]
	v_pk_fma_f32 v[122:123], v[122:123], 0.5, v[198:199] op_sel_hi:[1,0,1]
	v_pk_fma_f32 v[120:121], v[120:121], 0.5, v[202:203] op_sel_hi:[1,0,1]
	v_cmp_ne_u32_e64 s[10:11], 1, v178
	s_andn2_b64 vcc, exec, s[42:43]
	v_lshl_add_u64 v[190:191], v[190:191], 2, s[12:13]
	s_cbranch_vccnz .LBB0_281
	global_store_dwordx4 v[190:191], v[124:127], off
	global_store_dwordx4 v[190:191], v[120:123], off offset:16

; __device__ __forceinline__ unsigned cvt_pk_bf16(float lo, float hi) { unsigned r; asm volatile("v_cvt_pk_bf16_f32 %0, %1, %2" : "=v"(r) : "v"(lo), "v"(hi)); return r; }
;     __device__ __forceinline__ void operator()(const f32x4 (&acc)[2][2][4][2], const Unit& u, int wr, int wc, int fr, int fq) const {
;     ...
;         for (int ai = 0; ai < 2; ++ai) {
;             u32x4 rb[4][2];
; #pragma unroll
;             for (int m = 0; m < 4; ++m) { const size_t off = (size_t)(row0 + ai * HALF + m * 16) * 2048 + col0;
; #pragma unroll
;                 for (int bj = 0; bj < 2; ++bj) rb[m][bj] = *(const u32x4*)(xb + off + bj * HALF); }
;             __builtin_amdgcn_sched_barrier(0);
; #pragma unroll
;             for (int m = 0; m < 4; ++m) { const int row = row0 + ai * HALF + m * 16; const size_t off = (size_t)row * 2048 + col0; float sq = 0.f;
; #pragma unroll
;                 for (int bj = 0; bj < 2; ++bj) { const u32x4 r = rb[m][bj];
;                     const f32x4 b0 = (f32x4){__builtin_bit_cast(float, r.x << 16), __builtin_bit_cast(float, r.x & 0xffff0000u), __builtin_bit_cast(float, r.y << 16), __builtin_bit_cast(float, r.y & 0xffff0000u)};
;                     const f32x4 b1 = (f32x4){__builtin_bit_cast(float, r.z << 16), __builtin_bit_cast(float, r.z & 0xffff0000u), __builtin_bit_cast(float, r.w << 16), __builtin_bit_cast(float, r.w & 0xffff0000u)};
;                     const f32x4 o0 = b0 + acc[ai][bj][m][0] * alpha, o1 = b1 + acc[ai][bj][m][1] * alpha;
;                     if (wf) { *(f32x4*)(fout + off + bj * HALF) = o0; *(f32x4*)(fout + off + bj * HALF + 4) = o1; }
;                     sq += (o0[0] * o0[0] + o0[1] * o0[1]) + (o0[2] * o0[2] + o0[3] * o0[3]) + (o1[0] * o1[0] + o1[1] * o1[1]) + (o1[2] * o1[2] + o1[3] * o1[3]);
;                     u32x4 w; w.x = cvt_pk_bf16(o0[0], o0[1]); w.y = cvt_pk_bf16(o0[2], o0[3]); w.z = cvt_pk_bf16(o1[0], o1[1]); w.w = cvt_pk_bf16(o1[2], o1[3]);
;                     *(u32x4*)(xb + off + bj * HALF) = w; }
.LBB0_303:
	s_or_b64 exec, exec, s[30:31]
	v_add_u32_e32 v98, 0x80, v172
	v_ashrrev_i32_e32 v99, 31, v98
	v_lshlrev_b64 v[64:65], 12, v[98:99]
	v_add_u32_e32 v96, 0x90, v172
	v_lshl_add_u64 v[64:65], v[168:169], 0, v[64:65]
	v_ashrrev_i32_e32 v97, 31, v96
	v_lshlrev_b64 v[64:65], 12, v[96:97]
	v_add_u32_e32 v94, 0xa0, v172
	v_lshl_add_u64 v[64:65], v[168:169], 0, v[64:65]
	v_ashrrev_i32_e32 v95, 31, v94
	v_lshlrev_b64 v[64:65], 12, v[94:95]
	v_add_u32_e32 v92, 0xb0, v172
	v_lshl_add_u64 v[64:65], v[168:169], 0, v[64:65]
	v_ashrrev_i32_e32 v93, 31, v92
	v_lshlrev_b64 v[64:65], 12, v[92:93]
	v_lshl_add_u64 v[64:65], v[168:169], 0, v[64:65]
	v_lshlrev_b64 v[100:101], 11, v[98:99]
	v_lshl_add_u64 v[106:107], v[100:101], 0, v[170:171]
	s_waitcnt vmcnt(8)
	v_lshlrev_b32_e32 v108, 16, v180
	v_and_b32_e32 v109, 0xffff0000, v180
	v_lshlrev_b32_e32 v102, 16, v181
	v_and_b32_e32 v103, 0xffff0000, v181
	v_lshlrev_b32_e32 v110, 16, v182
	v_and_b32_e32 v111, 0xffff0000, v182
	v_lshlrev_b32_e32 v104, 16, v183
	v_and_b32_e32 v105, 0xffff0000, v183
	v_pk_fma_f32 v[62:63], v[62:63], 0.5, v[102:103] op_sel_hi:[1,0,1]
	v_pk_fma_f32 v[60:61], v[60:61], 0.5, v[108:109] op_sel_hi:[1,0,1]
	v_pk_fma_f32 v[58:59], v[58:59], 0.5, v[104:105] op_sel_hi:[1,0,1]
	v_pk_fma_f32 v[56:57], v[56:57], 0.5, v[110:111] op_sel_hi:[1,0,1]
	s_and_b64 vcc, exec, s[10:11]
	v_lshl_add_u64 v[102:103], v[106:107], 2, s[12:13]
	s_cbranch_vccnz .LBB0_305
	global_store_dwordx4 v[102:103], v[60:63], off
	global_store_dwordx4 v[102:103], v[56:59], off offset:16
.LBB0_305:
	v_cvt_pk_bf16_f32 v104, v60, v61
	v_cvt_pk_bf16_f32 v105, v62, v63
	v_cvt_pk_bf16_f32 v106, v56, v57
	v_cvt_pk_bf16_f32 v107, v58, v59
	v_lshl_add_u64 v[100:101], v[100:101], 1, v[168:169]
	global_store_dwordx4 v[100:101], v[104:107], off
	s_and_b64 vcc, exec, s[10:11]
	v_lshlrev_b32_e32 v104, 16, v204
	v_and_b32_e32 v105, 0xffff0000, v204
	v_lshlrev_b32_e32 v88, 16, v205
	v_and_b32_e32 v89, 0xffff0000, v205
	v_lshlrev_b32_e32 v106, 16, v206
	v_and_b32_e32 v107, 0xffff0000, v206
	v_lshlrev_b32_e32 v90, 16, v207
	v_and_b32_e32 v91, 0xffff0000, v207
	v_pk_fma_f32 v[54:55], v[54:55], 0.5, v[88:89] op_sel_hi:[1,0,1]
	v_pk_fma_f32 v[52:53], v[52:53], 0.5, v[104:105] op_sel_hi:[1,0,1]
	v_pk_fma_f32 v[50:51], v[50:51], 0.5, v[90:91] op_sel_hi:[1,0,1]
	v_pk_fma_f32 v[48:49], v[48:49], 0.5, v[106:107] op_sel_hi:[1,0,1]
	s_cbranch_vccnz .LBB0_307
	global_store_dwordx4 v[102:103], v[52:55], off offset:512
	global_store_dwordx4 v[102:103], v[48:51], off offset:528

; __device__ __forceinline__ unsigned cvt_pk_bf16(float lo, float hi) { unsigned r; asm volatile("v_cvt_pk_bf16_f32 %0, %1, %2" : "=v"(r) : "v"(lo), "v"(hi)); return r; }
;     __device__ __forceinline__ void operator()(const f32x4 (&acc)[2][2][4][2], const Unit& u, int wr, int wc, int fr, int fq) const {
;     ...
;             for (int m = 0; m < 4; ++m) { const int row = row0 + ai * HALF + m * 16; const size_t off = (size_t)row * 2048 + col0; float sq = 0.f;
; #pragma unroll
;                 for (int bj = 0; bj < 2; ++bj) { const u32x4 r = rb[m][bj];
;                     const f32x4 b0 = (f32x4){__builtin_bit_cast(float, r.x << 16), __builtin_bit_cast(float, r.x & 0xffff0000u), __builtin_bit_cast(float, r.y << 16), __builtin_bit_cast(float, r.y & 0xffff0000u)};
;                     const f32x4 b1 = (f32x4){__builtin_bit_cast(float, r.z << 16), __builtin_bit_cast(float, r.z & 0xffff0000u), __builtin_bit_cast(float, r.w << 16), __builtin_bit_cast(float, r.w & 0xffff0000u)};
;                     const f32x4 o0 = b0 + acc[ai][bj][m][0] * alpha, o1 = b1 + acc[ai][bj][m][1] * alpha;
;                     if (wf) { *(f32x4*)(fout + off + bj * HALF) = o0; *(f32x4*)(fout + off + bj * HALF + 4) = o1; }
;                     sq += (o0[0] * o0[0] + o0[1] * o0[1]) + (o0[2] * o0[2] + o0[3] * o0[3]) + (o1[0] * o1[0] + o1[1] * o1[1]) + (o1[2] * o1[2] + o1[3] * o1[3]);
;                     u32x4 w; w.x = cvt_pk_bf16(o0[0], o0[1]); w.y = cvt_pk_bf16(o0[2], o0[3]); w.z = cvt_pk_bf16(o1[0], o1[1]); w.w = cvt_pk_bf16(o1[2], o1[3]);
;                     *(u32x4*)(xb + off + bj * HALF) = w; }
.LBB0_309:
	s_or_b64 exec, exec, s[30:31]
	v_lshlrev_b64 v[48:49], 11, v[96:97]
	v_lshl_add_u64 v[50:51], v[48:49], 0, v[170:171]
	v_lshlrev_b32_e32 v52, 16, v208
	v_and_b32_e32 v53, 0xffff0000, v208
	v_lshlrev_b32_e32 v54, 16, v209
	v_and_b32_e32 v55, 0xffff0000, v209
	v_lshlrev_b32_e32 v56, 16, v210
	v_and_b32_e32 v57, 0xffff0000, v210
	v_lshlrev_b32_e32 v58, 16, v211
	v_and_b32_e32 v59, 0xffff0000, v211
	v_pk_fma_f32 v[46:47], v[46:47], 0.5, v[54:55] op_sel_hi:[1,0,1]
	v_pk_fma_f32 v[44:45], v[44:45], 0.5, v[52:53] op_sel_hi:[1,0,1]
	v_pk_fma_f32 v[42:43], v[42:43], 0.5, v[58:59] op_sel_hi:[1,0,1]
	v_pk_fma_f32 v[40:41], v[40:41], 0.5, v[56:57] op_sel_hi:[1,0,1]
	s_and_b64 vcc, exec, s[10:11]
	v_lshl_add_u64 v[50:51], v[50:51], 2, s[12:13]
	s_cbranch_vccnz .LBB0_311
	global_store_dwordx4 v[50:51], v[44:47], off
	global_store_dwordx4 v[50:51], v[40:43], off offset:16
.LBB0_311:
	v_cvt_pk_bf16_f32 v52, v44, v45
	v_cvt_pk_bf16_f32 v53, v46, v47
	v_cvt_pk_bf16_f32 v54, v40, v41
	v_cvt_pk_bf16_f32 v55, v42, v43
	v_lshl_add_u64 v[48:49], v[48:49], 1, v[168:169]
	global_store_dwordx4 v[48:49], v[52:55], off
	v_lshlrev_b32_e32 v56, 16, v214
	v_and_b32_e32 v57, 0xffff0000, v214
	v_lshlrev_b32_e32 v52, 16, v212
	v_and_b32_e32 v53, 0xffff0000, v212
	v_lshlrev_b32_e32 v54, 16, v213
	v_and_b32_e32 v55, 0xffff0000, v213
	v_lshlrev_b32_e32 v58, 16, v215
	v_and_b32_e32 v59, 0xffff0000, v215
	v_pk_fma_f32 v[38:39], v[38:39], 0.5, v[54:55] op_sel_hi:[1,0,1]
	v_pk_fma_f32 v[36:37], v[36:37], 0.5, v[52:53] op_sel_hi:[1,0,1]
	v_pk_fma_f32 v[34:35], v[34:35], 0.5, v[58:59] op_sel_hi:[1,0,1]
	s_and_b64 vcc, exec, s[10:11]
	v_pk_fma_f32 v[32:33], v[32:33], 0.5, v[56:57] op_sel_hi:[1,0,1]
	s_cbranch_vccnz .LBB0_313
	global_store_dwordx4 v[50:51], v[36:39], off offset:512
	global_store_dwordx4 v[50:51], v[32:35], off offset:528

; __device__ __forceinline__ unsigned cvt_pk_bf16(float lo, float hi) { unsigned r; asm volatile("v_cvt_pk_bf16_f32 %0, %1, %2" : "=v"(r) : "v"(lo), "v"(hi)); return r; }
;     __device__ __forceinline__ void operator()(const f32x4 (&acc)[2][2][4][2], const Unit& u, int wr, int wc, int fr, int fq) const {
;     ...
;             for (int m = 0; m < 4; ++m) { const int row = row0 + ai * HALF + m * 16; const size_t off = (size_t)row * 2048 + col0; float sq = 0.f;
; #pragma unroll
;                 for (int bj = 0; bj < 2; ++bj) { const u32x4 r = rb[m][bj];
;                     const f32x4 b0 = (f32x4){__builtin_bit_cast(float, r.x << 16), __builtin_bit_cast(float, r.x & 0xffff0000u), __builtin_bit_cast(float, r.y << 16), __builtin_bit_cast(float, r.y & 0xffff0000u)};
;                     const f32x4 b1 = (f32x4){__builtin_bit_cast(float, r.z << 16), __builtin_bit_cast(float, r.z & 0xffff0000u), __builtin_bit_cast(float, r.w << 16), __builtin_bit_cast(float, r.w & 0xffff0000u)};
;                     const f32x4 o0 = b0 + acc[ai][bj][m][0] * alpha, o1 = b1 + acc[ai][bj][m][1] * alpha;
;                     if (wf) { *(f32x4*)(fout + off + bj * HALF) = o0; *(f32x4*)(fout + off + bj * HALF + 4) = o1; }
;                     sq += (o0[0] * o0[0] + o0[1] * o0[1]) + (o0[2] * o0[2] + o0[3] * o0[3]) + (o1[0] * o1[0] + o1[1] * o1[1]) + (o1[2] * o1[2] + o1[3] * o1[3]);
;                     u32x4 w; w.x = cvt_pk_bf16(o0[0], o0[1]); w.y = cvt_pk_bf16(o0[2], o0[3]); w.z = cvt_pk_bf16(o1[0], o1[1]); w.w = cvt_pk_bf16(o1[2], o1[3]);
;                     *(u32x4*)(xb + off + bj * HALF) = w; }
.LBB0_315:
	s_or_b64 exec, exec, s[30:31]
	v_lshlrev_b64 v[32:33], 11, v[94:95]
	v_lshl_add_u64 v[34:35], v[32:33], 0, v[170:171]
	v_lshlrev_b32_e32 v36, 16, v216
	v_and_b32_e32 v37, 0xffff0000, v216
	v_lshlrev_b32_e32 v38, 16, v217
	v_and_b32_e32 v39, 0xffff0000, v217
	v_lshlrev_b32_e32 v40, 16, v218
	v_and_b32_e32 v41, 0xffff0000, v218
	v_lshlrev_b32_e32 v42, 16, v219
	v_and_b32_e32 v43, 0xffff0000, v219
	v_pk_fma_f32 v[30:31], v[30:31], 0.5, v[38:39] op_sel_hi:[1,0,1]
	v_pk_fma_f32 v[28:29], v[28:29], 0.5, v[36:37] op_sel_hi:[1,0,1]
	v_pk_fma_f32 v[26:27], v[26:27], 0.5, v[42:43] op_sel_hi:[1,0,1]
	v_pk_fma_f32 v[24:25], v[24:25], 0.5, v[40:41] op_sel_hi:[1,0,1]
	s_and_b64 vcc, exec, s[10:11]
	v_lshl_add_u64 v[34:35], v[34:35], 2, s[12:13]
	s_cbranch_vccnz .LBB0_317
	global_store_dwordx4 v[34:35], v[28:31], off
	global_store_dwordx4 v[34:35], v[24:27], off offset:16
.LBB0_317:
	v_cvt_pk_bf16_f32 v36, v28, v29
	v_cvt_pk_bf16_f32 v37, v30, v31
	v_cvt_pk_bf16_f32 v38, v24, v25
	v_cvt_pk_bf16_f32 v39, v26, v27
	v_lshl_add_u64 v[32:33], v[32:33], 1, v[168:169]
	global_store_dwordx4 v[32:33], v[36:39], off
	v_lshlrev_b32_e32 v40, 16, v224
	v_and_b32_e32 v41, 0xffff0000, v224
	v_lshlrev_b32_e32 v36, 16, v222
	v_and_b32_e32 v37, 0xffff0000, v222
	v_lshlrev_b32_e32 v38, 16, v223
	v_and_b32_e32 v39, 0xffff0000, v223
	v_lshlrev_b32_e32 v42, 16, v225
	v_and_b32_e32 v43, 0xffff0000, v225
	v_pk_fma_f32 v[22:23], v[22:23], 0.5, v[38:39] op_sel_hi:[1,0,1]
	v_pk_fma_f32 v[20:21], v[20:21], 0.5, v[36:37] op_sel_hi:[1,0,1]
	v_pk_fma_f32 v[18:19], v[18:19], 0.5, v[42:43] op_sel_hi:[1,0,1]
	s_and_b64 vcc, exec, s[10:11]
	v_pk_fma_f32 v[16:17], v[16:17], 0.5, v[40:41] op_sel_hi:[1,0,1]
	s_cbranch_vccnz .LBB0_319
	global_store_dwordx4 v[34:35], v[20:23], off offset:512
	global_store_dwordx4 v[34:35], v[16:19], off offset:528

; __device__ __forceinline__ unsigned cvt_pk_bf16(float lo, float hi) { unsigned r; asm volatile("v_cvt_pk_bf16_f32 %0, %1, %2" : "=v"(r) : "v"(lo), "v"(hi)); return r; }
;     __device__ __forceinline__ void operator()(const f32x4 (&acc)[2][2][4][2], const Unit& u, int wr, int wc, int fr, int fq) const {
;     ...
;             for (int m = 0; m < 4; ++m) { const int row = row0 + ai * HALF + m * 16; const size_t off = (size_t)row * 2048 + col0; float sq = 0.f;
; #pragma unroll
;                 for (int bj = 0; bj < 2; ++bj) { const u32x4 r = rb[m][bj];
;                     const f32x4 b0 = (f32x4){__builtin_bit_cast(float, r.x << 16), __builtin_bit_cast(float, r.x & 0xffff0000u), __builtin_bit_cast(float, r.y << 16), __builtin_bit_cast(float, r.y & 0xffff0000u)};
;                     const f32x4 b1 = (f32x4){__builtin_bit_cast(float, r.z << 16), __builtin_bit_cast(float, r.z & 0xffff0000u), __builtin_bit_cast(float, r.w << 16), __builtin_bit_cast(float, r.w & 0xffff0000u)};
;                     const f32x4 o0 = b0 + acc[ai][bj][m][0] * alpha, o1 = b1 + acc[ai][bj][m][1] * alpha;
;                     if (wf) { *(f32x4*)(fout + off + bj * HALF) = o0; *(f32x4*)(fout + off + bj * HALF + 4) = o1; }
;                     sq += (o0[0] * o0[0] + o0[1] * o0[1]) + (o0[2] * o0[2] + o0[3] * o0[3]) + (o1[0] * o1[0] + o1[1] * o1[1]) + (o1[2] * o1[2] + o1[3] * o1[3]);
;                     u32x4 w; w.x = cvt_pk_bf16(o0[0], o0[1]); w.y = cvt_pk_bf16(o0[2], o0[3]); w.z = cvt_pk_bf16(o1[0], o1[1]); w.w = cvt_pk_bf16(o1[2], o1[3]);
;                     *(u32x4*)(xb + off + bj * HALF) = w; }
.LBB0_321:
	s_or_b64 exec, exec, s[30:31]
	v_lshlrev_b64 v[16:17], 11, v[92:93]
	v_lshl_add_u64 v[18:19], v[16:17], 0, v[170:171]
	v_lshlrev_b32_e32 v20, 16, v228
	v_and_b32_e32 v21, 0xffff0000, v228
	v_lshlrev_b32_e32 v22, 16, v229
	v_and_b32_e32 v23, 0xffff0000, v229
	v_lshlrev_b32_e32 v24, 16, v230
	v_and_b32_e32 v25, 0xffff0000, v230
	v_lshlrev_b32_e32 v26, 16, v231
	v_and_b32_e32 v27, 0xffff0000, v231
	v_pk_fma_f32 v[14:15], v[14:15], 0.5, v[22:23] op_sel_hi:[1,0,1]
	v_pk_fma_f32 v[12:13], v[12:13], 0.5, v[20:21] op_sel_hi:[1,0,1]
	v_pk_fma_f32 v[10:11], v[10:11], 0.5, v[26:27] op_sel_hi:[1,0,1]
	v_pk_fma_f32 v[8:9], v[8:9], 0.5, v[24:25] op_sel_hi:[1,0,1]
	s_and_b64 vcc, exec, s[10:11]
	v_lshl_add_u64 v[18:19], v[18:19], 2, s[12:13]
	s_cbranch_vccnz .LBB0_323
	global_store_dwordx4 v[18:19], v[12:15], off
	global_store_dwordx4 v[18:19], v[8:11], off offset:16
.LBB0_323:
	v_cvt_pk_bf16_f32 v20, v12, v13
	v_cvt_pk_bf16_f32 v21, v14, v15
	v_cvt_pk_bf16_f32 v22, v8, v9
	v_cvt_pk_bf16_f32 v23, v10, v11
	v_lshl_add_u64 v[16:17], v[16:17], 1, v[168:169]
	global_store_dwordx4 v[16:17], v[20:23], off
	v_lshlrev_b32_e32 v24, 16, v234
	v_and_b32_e32 v25, 0xffff0000, v234
	v_lshlrev_b32_e32 v20, 16, v232
	v_and_b32_e32 v21, 0xffff0000, v232
	v_lshlrev_b32_e32 v22, 16, v233
	v_and_b32_e32 v23, 0xffff0000, v233
	v_lshlrev_b32_e32 v26, 16, v235
	v_and_b32_e32 v27, 0xffff0000, v235
	v_pk_fma_f32 v[6:7], v[6:7], 0.5, v[22:23] op_sel_hi:[1,0,1]
	v_pk_fma_f32 v[4:5], v[4:5], 0.5, v[20:21] op_sel_hi:[1,0,1]
	v_pk_fma_f32 v[2:3], v[2:3], 0.5, v[26:27] op_sel_hi:[1,0,1]
	s_and_b64 vcc, exec, s[10:11]
	v_pk_fma_f32 v[0:1], v[0:1], 0.5, v[24:25] op_sel_hi:[1,0,1]
	s_cbranch_vccnz .LBB0_325
	global_store_dwordx4 v[18:19], v[4:7], off offset:512
	global_store_dwordx4 v[18:19], v[0:3], off offset:528

; #define PG8_STAGE(bufoff, gbase, voff) do { _Pragma("unroll") for (int _i = 0; _i < 2; ++_i) \
;         __builtin_amdgcn_global_load_lds((const unsigned*)((const char*)(gbase) + (voff)[_i]), (PG8_LAS unsigned*)(lds + (bufoff) + ldsw + _i * 8192), 16, 0, 0); } while (0)
; #define PG8_LDA(dst, b, h) do { _Pragma("unroll") for (int m = 0; m < 4; ++m) _Pragma("unroll") for (int k = 0; k < 2; ++k) dst[m][k] = *(const PG8_LAS bf16x8*)(lds + PG8_SA(b, h) + aoff + m * 2048 + k * 1024); } while (0)
; #define PG8_LDB(dst, b, h) do { _Pragma("unroll") for (int n = 0; n < 2; ++n) _Pragma("unroll") for (int k = 0; k < 2; ++k) dst[n][k] = *(const PG8_LAS bf16x8*)(lds + PG8_SB(b, h) + boff + n * 2048 + k * 1024); } while (0)
; #define PG8_MMA(ai, bj, At, Bt) do { __builtin_amdgcn_s_setprio(1); _Pragma("unroll") for (int m = 0; m < 4; ++m) _Pragma("unroll") for (int n = 0; n < 2; ++n) _Pragma("unroll") for (int k = 0; k < 2; ++k) \
;         acc[ai][bj][m][n] = __builtin_amdgcn_mfma_f32_16x16x32_bf16(Bt[n][k], At[m][k], acc[ai][bj][m][n], 0, 0, 0); __builtin_amdgcn_s_setprio(0); } while (0)
; #define PG8_WAIT_L(n) asm volatile("s_waitcnt lgkmcnt(" #n ")" ::: "memory")
; #define PG8_WAIT_VK do { if constexpr (HALFM) PG8_WAIT_V(6); else PG8_WAIT_V(8); } while (0)
; #define PG8_BAR __builtin_amdgcn_s_barrier()
; #define PG8_SCHED __builtin_amdgcn_sched_barrier(0)
; template <class Epi, class Sched, bool ALIGN_EPI = false, bool SP2 = false, bool HALFM = false, bool AMAP = false>
; __device__ __forceinline__ void gemm_phase(PG8_LAS unsigned char* lds, const Gemm g, const Sched& S, const Epi& E, int tid_in) {
;     ...
;             PG8_LDB(B0, 0, 0); PG8_LDB(B1, 0, 1); PG8_SCHED; PG8_LDA(At, 0, 0); if constexpr (!HALFM) PG8_STAGE(PG8_SA(1, 1), a1 + hstepA, voffA);
;             PG8_WAIT_VK; PG8_WAIT_L(0); PG8_BAR; PG8_MMA(0, 0, At, B0); PG8_MMA(0, 1, At, B1); PG8_BAR; PG8_SCHED;
;             if constexpr (!HALFM) { PG8_LDA(At, 0, 1); } PG8_STAGE(PG8_SB(0, 0), b2, voffB); PG8_STAGE(PG8_SB(0, 1), b2 + hstepB, voffB); PG8_STAGE(PG8_SA(0, 0), a2, voffA);
;             PG8_WAIT_VK; PG8_WAIT_L(0); PG8_BAR; if constexpr (!HALFM) { PG8_MMA(1, 0, At, B0); PG8_MMA(1, 1, At, B1); } PG8_BAR; PG8_SCHED;
.LBB0_399:
	s_add_u32 s28, s8, 0xfff00080
	s_addc_u32 s29, s9, -1
	s_add_i32 s76, 0, 0x10000
	s_cmp_eq_u32 vcc_lo, 28
	s_cselect_b32 s31, s17, s29
	s_cselect_b32 s30, s16, s28
	s_cselect_b32 s29, s5, s97
	s_cselect_b32 s28, s36, s37
	s_add_i32 vcc_hi, 0, 0x14000
	v_add_u32_e32 v140, s76, v233
	v_add_u32_e32 v156, vcc_hi, v233
	ds_read_b128 v[128:131], v140
	ds_read_b128 v[132:135], v140 offset:1024
	ds_read_b128 v[136:139], v140 offset:2048
	ds_read_b128 v[140:143], v140 offset:3072
	ds_read_b128 v[144:147], v156
	ds_read_b128 v[148:151], v156 offset:1024
	ds_read_b128 v[152:155], v156 offset:2048
	ds_read_b128 v[156:159], v156 offset:3072
	v_lshl_add_u64 v[210:211], s[8:9], 0, v[192:193]
	s_add_i32 m0, s38, 0xc000
	ds_read_b128 v[160:163], v236
	ds_read_b128 v[164:167], v236 offset:1024
	ds_read_b128 v[168:171], v236 offset:2048
	ds_read_b128 v[172:175], v236 offset:3072
	s_waitcnt lgkmcnt(0)
	ds_read_b128 v[194:197], v236 offset:4096
	ds_read_b128 v[198:201], v236 offset:5120
	ds_read_b128 v[202:205], v236 offset:6144
	ds_read_b128 v[206:209], v236 offset:7168
	global_load_lds_dwordx4 v[210:211], off
	v_lshl_add_u64 v[210:211], s[8:9], 0, v[190:191]
	s_add_i32 m0, s38, 0xe000
	s_nop 0
	global_load_lds_dwordx4 v[210:211], off
	s_waitcnt vmcnt(8)
	s_waitcnt lgkmcnt(0)
	s_barrier
	s_setprio 1
	v_mfma_f32_16x16x32_bf16 v[124:127], v[128:131], v[160:163], v[124:127]
	v_mfma_f32_16x16x32_bf16 v[92:95], v[136:139], v[160:163], v[92:95]
	v_mfma_f32_16x16x32_bf16 v[120:123], v[128:131], v[168:171], v[120:123]
	v_mfma_f32_16x16x32_bf16 v[88:91], v[136:139], v[168:171], v[88:91]
	v_mfma_f32_16x16x32_bf16 v[116:119], v[128:131], v[194:197], v[116:119]
	v_mfma_f32_16x16x32_bf16 v[84:87], v[136:139], v[194:197], v[84:87]
	v_mfma_f32_16x16x32_bf16 v[112:115], v[128:131], v[202:205], v[112:115]
	v_mfma_f32_16x16x32_bf16 v[80:83], v[136:139], v[202:205], v[80:83]
	v_mfma_f32_16x16x32_bf16 v[124:127], v[132:135], v[164:167], v[124:127]
	v_mfma_f32_16x16x32_bf16 v[92:95], v[140:143], v[164:167], v[92:95]
	v_mfma_f32_16x16x32_bf16 v[120:123], v[132:135], v[172:175], v[120:123]
	v_mfma_f32_16x16x32_bf16 v[88:91], v[140:143], v[172:175], v[88:91]
	v_mfma_f32_16x16x32_bf16 v[116:119], v[132:135], v[198:201], v[116:119]
	v_mfma_f32_16x16x32_bf16 v[84:87], v[140:143], v[198:201], v[84:87]
	v_mfma_f32_16x16x32_bf16 v[112:115], v[132:135], v[206:209], v[112:115]
	v_mfma_f32_16x16x32_bf16 v[80:83], v[140:143], v[206:209], v[80:83]
	s_setprio 0
	s_setprio 1
	v_mfma_f32_16x16x32_bf16 v[60:63], v[144:147], v[160:163], v[60:63]
	v_mfma_f32_16x16x32_bf16 v[28:31], v[152:155], v[160:163], v[28:31]
	v_mfma_f32_16x16x32_bf16 v[56:59], v[144:147], v[168:171], v[56:59]
	v_mfma_f32_16x16x32_bf16 v[24:27], v[152:155], v[168:171], v[24:27]
	v_mfma_f32_16x16x32_bf16 v[52:55], v[144:147], v[194:197], v[52:55]
	v_mfma_f32_16x16x32_bf16 v[20:23], v[152:155], v[194:197], v[20:23]
	v_mfma_f32_16x16x32_bf16 v[48:51], v[144:147], v[202:205], v[48:51]
	v_mfma_f32_16x16x32_bf16 v[16:19], v[152:155], v[202:205], v[16:19]
	v_mfma_f32_16x16x32_bf16 v[60:63], v[148:151], v[164:167], v[60:63]
	v_mfma_f32_16x16x32_bf16 v[28:31], v[156:159], v[164:167], v[28:31]
	v_mfma_f32_16x16x32_bf16 v[56:59], v[148:151], v[172:175], v[56:59]
	v_mfma_f32_16x16x32_bf16 v[24:27], v[156:159], v[172:175], v[24:27]
	v_mfma_f32_16x16x32_bf16 v[52:55], v[148:151], v[198:201], v[52:55]
	v_mfma_f32_16x16x32_bf16 v[20:23], v[156:159], v[198:201], v[20:23]
	v_mfma_f32_16x16x32_bf16 v[48:51], v[148:151], v[206:209], v[48:51]
	v_mfma_f32_16x16x32_bf16 v[16:19], v[156:159], v[206:209], v[16:19]
	s_setprio 0
	s_barrier
	s_add_i32 s76, s76, s25
	v_lshl_add_u64 v[210:211], s[28:29], 0, v[176:177]
	s_mov_b32 m0, s76
	ds_read_b128 v[160:163], v236 offset:16384
	ds_read_b128 v[164:167], v236 offset:17408
	ds_read_b128 v[168:171], v236 offset:18432
	ds_read_b128 v[172:175], v236 offset:19456
	ds_read_b128 v[194:197], v236 offset:20480
	ds_read_b128 v[198:201], v236 offset:21504
	ds_read_b128 v[202:205], v236 offset:22528
	ds_read_b128 v[206:209], v236 offset:23552
	global_load_lds_dwordx4 v[210:211], off
	s_add_i32 m0, s76, 0x2000
	s_add_u32 s76, s28, 0x80000
	v_lshl_add_u64 v[212:213], s[28:29], 0, v[184:185]
	s_addc_u32 s77, s29, 0
	s_add_i32 vcc_hi, vcc_hi, s25
	global_load_lds_dwordx4 v[212:213], off
	v_lshl_add_u64 v[214:215], s[76:77], 0, v[176:177]
	s_mov_b32 m0, vcc_hi
	v_lshl_add_u64 v[216:217], s[30:31], 0, v[186:187]
	global_load_lds_dwordx4 v[214:215], off
	v_lshl_add_u64 v[214:215], s[76:77], 0, v[184:185]
	s_add_i32 m0, vcc_hi, 0x2000
	s_nop 0
	global_load_lds_dwordx4 v[214:215], off
	v_lshl_add_u64 v[214:215], s[30:31], 0, v[188:189]
	s_mov_b32 m0, s38
	s_nop 0
	global_load_lds_dwordx4 v[214:215], off
	s_mov_b32 m0, s39
	s_nop 0
	global_load_lds_dwordx4 v[216:217], off
	s_waitcnt vmcnt(8)
	s_waitcnt lgkmcnt(0)
	s_barrier
; #define PG8_STAGE(bufoff, gbase, voff) do { _Pragma("unroll") for (int _i = 0; _i < 2; ++_i) \
;         __builtin_amdgcn_global_load_lds((const unsigned*)((const char*)(gbase) + (voff)[_i]), (PG8_LAS unsigned*)(lds + (bufoff) + ldsw + _i * 8192), 16, 0, 0); } while (0)
; #define PG8_LDA(dst, b, h) do { _Pragma("unroll") for (int m = 0; m < 4; ++m) _Pragma("unroll") for (int k = 0; k < 2; ++k) dst[m][k] = *(const PG8_LAS bf16x8*)(lds + PG8_SA(b, h) + aoff + m * 2048 + k * 1024); } while (0)
; #define PG8_LDB(dst, b, h) do { _Pragma("unroll") for (int n = 0; n < 2; ++n) _Pragma("unroll") for (int k = 0; k < 2; ++k) dst[n][k] = *(const PG8_LAS bf16x8*)(lds + PG8_SB(b, h) + boff + n * 2048 + k * 1024); } while (0)
; #define PG8_MMA(ai, bj, At, Bt) do { __builtin_amdgcn_s_setprio(1); _Pragma("unroll") for (int m = 0; m < 4; ++m) _Pragma("unroll") for (int n = 0; n < 2; ++n) _Pragma("unroll") for (int k = 0; k < 2; ++k) \
;         acc[ai][bj][m][n] = __builtin_amdgcn_mfma_f32_16x16x32_bf16(Bt[n][k], At[m][k], acc[ai][bj][m][n], 0, 0, 0); __builtin_amdgcn_s_setprio(0); } while (0)
; #define PG8_WAIT_L(n) asm volatile("s_waitcnt lgkmcnt(" #n ")" ::: "memory")
; #define PG8_WAIT_VK do { if constexpr (HALFM) PG8_WAIT_V(6); else PG8_WAIT_V(8); } while (0)
; #define PG8_BAR __builtin_amdgcn_s_barrier()
; #define PG8_SCHED __builtin_amdgcn_sched_barrier(0)
; template <class Epi, class Sched, bool ALIGN_EPI = false, bool SP2 = false, bool HALFM = false, bool AMAP = false>
; __device__ __forceinline__ void gemm_phase(PG8_LAS unsigned char* lds, const Gemm g, const Sched& S, const Epi& E, int tid_in) {
;     ...
;             PG8_WAIT_VK; PG8_WAIT_L(0); PG8_BAR; if constexpr (!HALFM) { PG8_MMA(1, 0, At, B0); PG8_MMA(1, 1, At, B1); } PG8_BAR; PG8_SCHED;
;             PG8_LDB(B0, 1, 0); PG8_LDB(B1, 1, 1); PG8_SCHED; PG8_LDA(At, 1, 0); if constexpr (!HALFM) PG8_STAGE(PG8_SA(0, 1), a2 + hstepA, voffA);
;             PG8_WAIT_VK; PG8_WAIT_L(0); PG8_BAR; PG8_MMA(0, 0, At, B0); PG8_MMA(0, 1, At, B1); PG8_BAR; PG8_SCHED;
	s_setprio 1
	v_mfma_f32_16x16x32_bf16 v[108:111], v[128:131], v[160:163], v[108:111]
	v_mfma_f32_16x16x32_bf16 v[76:79], v[136:139], v[160:163], v[76:79]
	v_mfma_f32_16x16x32_bf16 v[104:107], v[128:131], v[168:171], v[104:107]
	v_mfma_f32_16x16x32_bf16 v[72:75], v[136:139], v[168:171], v[72:75]
	v_mfma_f32_16x16x32_bf16 v[100:103], v[128:131], v[194:197], v[100:103]
	v_mfma_f32_16x16x32_bf16 v[68:71], v[136:139], v[194:197], v[68:71]
	v_mfma_f32_16x16x32_bf16 v[96:99], v[128:131], v[202:205], v[96:99]
	v_mfma_f32_16x16x32_bf16 v[64:67], v[136:139], v[202:205], v[64:67]
	v_mfma_f32_16x16x32_bf16 v[108:111], v[132:135], v[164:167], v[108:111]
	v_mfma_f32_16x16x32_bf16 v[76:79], v[140:143], v[164:167], v[76:79]
	v_mfma_f32_16x16x32_bf16 v[104:107], v[132:135], v[172:175], v[104:107]
	v_mfma_f32_16x16x32_bf16 v[72:75], v[140:143], v[172:175], v[72:75]
	v_mfma_f32_16x16x32_bf16 v[100:103], v[132:135], v[198:201], v[100:103]
	v_mfma_f32_16x16x32_bf16 v[68:71], v[140:143], v[198:201], v[68:71]
	v_mfma_f32_16x16x32_bf16 v[96:99], v[132:135], v[206:209], v[96:99]
	v_mfma_f32_16x16x32_bf16 v[64:67], v[140:143], v[206:209], v[64:67]
	s_setprio 0
	s_setprio 1
	v_mfma_f32_16x16x32_bf16 v[44:47], v[144:147], v[160:163], v[44:47]
	v_mfma_f32_16x16x32_bf16 v[12:15], v[152:155], v[160:163], v[12:15]
	v_mfma_f32_16x16x32_bf16 v[40:43], v[144:147], v[168:171], v[40:43]
	v_mfma_f32_16x16x32_bf16 v[8:11], v[152:155], v[168:171], v[8:11]
	v_mfma_f32_16x16x32_bf16 v[36:39], v[144:147], v[194:197], v[36:39]
	v_mfma_f32_16x16x32_bf16 v[4:7], v[152:155], v[194:197], v[4:7]
	v_mfma_f32_16x16x32_bf16 v[32:35], v[144:147], v[202:205], v[32:35]
	v_mfma_f32_16x16x32_bf16 v[0:3], v[152:155], v[202:205], v[0:3]
	v_mfma_f32_16x16x32_bf16 v[44:47], v[148:151], v[164:167], v[44:47]
	v_mfma_f32_16x16x32_bf16 v[12:15], v[156:159], v[164:167], v[12:15]
	v_mfma_f32_16x16x32_bf16 v[40:43], v[148:151], v[172:175], v[40:43]
	v_mfma_f32_16x16x32_bf16 v[8:11], v[156:159], v[172:175], v[8:11]
	v_mfma_f32_16x16x32_bf16 v[36:39], v[148:151], v[198:201], v[36:39]
	v_mfma_f32_16x16x32_bf16 v[4:7], v[156:159], v[198:201], v[4:7]
	v_mfma_f32_16x16x32_bf16 v[32:35], v[148:151], v[206:209], v[32:35]
	v_mfma_f32_16x16x32_bf16 v[0:3], v[156:159], v[206:209], v[0:3]
	s_setprio 0
	s_barrier
	s_add_i32 s76, 0, 0x18000
	s_add_i32 s77, 0, 0x1c000
	v_add_u32_e32 v140, s76, v233
	v_add_u32_e32 v156, s77, v233
	ds_read_b128 v[128:131], v140
	ds_read_b128 v[132:135], v140 offset:1024
	ds_read_b128 v[136:139], v140 offset:2048
	ds_read_b128 v[140:143], v140 offset:3072
	ds_read_b128 v[144:147], v156
	ds_read_b128 v[148:151], v156 offset:1024
	ds_read_b128 v[152:155], v156 offset:2048
	ds_read_b128 v[156:159], v156 offset:3072
	s_add_u32 s30, s30, 0x100000
	s_addc_u32 s31, s31, 0
	s_mov_b32 m0, s88
	v_lshl_add_u64 v[218:219], s[30:31], 0, v[188:189]
	ds_read_b128 v[160:163], v236 offset:32768
	ds_read_b128 v[164:167], v236 offset:33792
	ds_read_b128 v[168:171], v236 offset:34816
	ds_read_b128 v[172:175], v236 offset:35840
	ds_read_b128 v[194:197], v236 offset:36864
	ds_read_b128 v[198:201], v236 offset:37888
	ds_read_b128 v[202:205], v236 offset:38912
	ds_read_b128 v[206:209], v236 offset:39936
	global_load_lds_dwordx4 v[218:219], off
	v_lshl_add_u64 v[218:219], s[30:31], 0, v[186:187]
	s_mov_b32 m0, s90
	s_nop 0
	global_load_lds_dwordx4 v[218:219], off
	s_waitcnt vmcnt(8)
	s_waitcnt lgkmcnt(0)
	s_barrier
	s_setprio 1
	v_mfma_f32_16x16x32_bf16 v[124:127], v[128:131], v[160:163], v[124:127]
	v_mfma_f32_16x16x32_bf16 v[92:95], v[136:139], v[160:163], v[92:95]
	v_mfma_f32_16x16x32_bf16 v[120:123], v[128:131], v[168:171], v[120:123]
	v_mfma_f32_16x16x32_bf16 v[88:91], v[136:139], v[168:171], v[88:91]
	v_mfma_f32_16x16x32_bf16 v[116:119], v[128:131], v[194:197], v[116:119]
	v_mfma_f32_16x16x32_bf16 v[84:87], v[136:139], v[194:197], v[84:87]
	v_mfma_f32_16x16x32_bf16 v[112:115], v[128:131], v[202:205], v[112:115]
	v_mfma_f32_16x16x32_bf16 v[80:83], v[136:139], v[202:205], v[80:83]
	v_mfma_f32_16x16x32_bf16 v[124:127], v[132:135], v[164:167], v[124:127]
	v_mfma_f32_16x16x32_bf16 v[92:95], v[140:143], v[164:167], v[92:95]
	v_mfma_f32_16x16x32_bf16 v[120:123], v[132:135], v[172:175], v[120:123]
	v_mfma_f32_16x16x32_bf16 v[88:91], v[140:143], v[172:175], v[88:91]
	v_mfma_f32_16x16x32_bf16 v[116:119], v[132:135], v[198:201], v[116:119]
	v_mfma_f32_16x16x32_bf16 v[84:87], v[140:143], v[198:201], v[84:87]
	v_mfma_f32_16x16x32_bf16 v[112:115], v[132:135], v[206:209], v[112:115]
	v_mfma_f32_16x16x32_bf16 v[80:83], v[140:143], v[206:209], v[80:83]
	s_setprio 0
	s_setprio 1
	v_mfma_f32_16x16x32_bf16 v[60:63], v[144:147], v[160:163], v[60:63]
	v_mfma_f32_16x16x32_bf16 v[28:31], v[152:155], v[160:163], v[28:31]
	v_mfma_f32_16x16x32_bf16 v[56:59], v[144:147], v[168:171], v[56:59]
	v_mfma_f32_16x16x32_bf16 v[24:27], v[152:155], v[168:171], v[24:27]
	v_mfma_f32_16x16x32_bf16 v[52:55], v[144:147], v[194:197], v[52:55]
	v_mfma_f32_16x16x32_bf16 v[20:23], v[152:155], v[194:197], v[20:23]
	v_mfma_f32_16x16x32_bf16 v[48:51], v[144:147], v[202:205], v[48:51]
	v_mfma_f32_16x16x32_bf16 v[16:19], v[152:155], v[202:205], v[16:19]
	v_mfma_f32_16x16x32_bf16 v[60:63], v[148:151], v[164:167], v[60:63]
	v_mfma_f32_16x16x32_bf16 v[28:31], v[156:159], v[164:167], v[28:31]
	v_mfma_f32_16x16x32_bf16 v[56:59], v[148:151], v[172:175], v[56:59]
	v_mfma_f32_16x16x32_bf16 v[24:27], v[156:159], v[172:175], v[24:27]
	v_mfma_f32_16x16x32_bf16 v[52:55], v[148:151], v[198:201], v[52:55]
	v_mfma_f32_16x16x32_bf16 v[20:23], v[156:159], v[198:201], v[20:23]
	v_mfma_f32_16x16x32_bf16 v[48:51], v[148:151], v[206:209], v[48:51]
	v_mfma_f32_16x16x32_bf16 v[16:19], v[156:159], v[206:209], v[16:19]
	s_setprio 0
	s_barrier
; #define PG8_STAGE(bufoff, gbase, voff) do { _Pragma("unroll") for (int _i = 0; _i < 2; ++_i) \
;         __builtin_amdgcn_global_load_lds((const unsigned*)((const char*)(gbase) + (voff)[_i]), (PG8_LAS unsigned*)(lds + (bufoff) + ldsw + _i * 8192), 16, 0, 0); } while (0)
; #define PG8_LDA(dst, b, h) do { _Pragma("unroll") for (int m = 0; m < 4; ++m) _Pragma("unroll") for (int k = 0; k < 2; ++k) dst[m][k] = *(const PG8_LAS bf16x8*)(lds + PG8_SA(b, h) + aoff + m * 2048 + k * 1024); } while (0)
; #define PG8_MMA(ai, bj, At, Bt) do { __builtin_amdgcn_s_setprio(1); _Pragma("unroll") for (int m = 0; m < 4; ++m) _Pragma("unroll") for (int n = 0; n < 2; ++n) _Pragma("unroll") for (int k = 0; k < 2; ++k) \
;         acc[ai][bj][m][n] = __builtin_amdgcn_mfma_f32_16x16x32_bf16(Bt[n][k], At[m][k], acc[ai][bj][m][n], 0, 0, 0); __builtin_amdgcn_s_setprio(0); } while (0)
; #define PG8_WAIT_L(n) asm volatile("s_waitcnt lgkmcnt(" #n ")" ::: "memory")
; #define PG8_WAIT_VK do { if constexpr (HALFM) PG8_WAIT_V(6); else PG8_WAIT_V(8); } while (0)
; #define PG8_BAR __builtin_amdgcn_s_barrier()
; #define PG8_SCHED __builtin_amdgcn_sched_barrier(0)
; template <class Epi, class Sched, bool ALIGN_EPI = false, bool SP2 = false, bool HALFM = false, bool AMAP = false>
; __device__ __forceinline__ void gemm_phase(PG8_LAS unsigned char* lds, const Gemm g, const Sched& S, const Epi& E, int tid_in) {
;     ...
;             if constexpr (!HALFM) { PG8_LDA(At, 1, 1); } PG8_STAGE(PG8_SB(1, 0), b3, voffB); PG8_STAGE(PG8_SB(1, 1), b3 + hstepB, voffB); PG8_STAGE(PG8_SA(1, 0), a3, voffA);
;             PG8_WAIT_VK; PG8_WAIT_L(0); PG8_BAR; if constexpr (!HALFM) { PG8_MMA(1, 0, At, B0); PG8_MMA(1, 1, At, B1); } PG8_BAR; PG8_SCHED;
	s_add_i32 s30, s76, s25
	v_lshl_add_u64 v[210:211], v[210:211], 0, s[66:67]
	s_mov_b32 m0, s30
	ds_read_b128 v[160:163], v236 offset:49152
	ds_read_b128 v[164:167], v236 offset:50176
	ds_read_b128 v[168:171], v236 offset:51200
	ds_read_b128 v[172:175], v236 offset:52224
	ds_read_b128 v[194:197], v236 offset:53248
	ds_read_b128 v[198:201], v236 offset:54272
	ds_read_b128 v[202:205], v236 offset:55296
	ds_read_b128 v[206:209], v236 offset:56320
	global_load_lds_dwordx4 v[210:211], off
	s_add_i32 m0, s30, 0x2000
	s_add_u32 s28, s28, 0x80080
	v_lshl_add_u64 v[210:211], v[212:213], 0, s[66:67]
	s_addc_u32 s29, s29, 0
	s_add_i32 s30, s77, s25
	global_load_lds_dwordx4 v[210:211], off
	v_lshl_add_u64 v[210:211], s[28:29], 0, v[176:177]
	s_mov_b32 m0, s30
	s_nop 0
	global_load_lds_dwordx4 v[210:211], off
	v_lshl_add_u64 v[210:211], s[28:29], 0, v[184:185]
	s_add_i32 m0, s30, 0x2000
	s_nop 0
	global_load_lds_dwordx4 v[210:211], off
	v_lshl_add_u64 v[210:211], v[214:215], 0, s[66:67]
	s_mov_b32 m0, s18
	s_nop 0
	global_load_lds_dwordx4 v[210:211], off
	v_lshl_add_u64 v[210:211], v[216:217], 0, s[66:67]
	s_mov_b32 m0, s19
	s_nop 0
	global_load_lds_dwordx4 v[210:211], off
	s_waitcnt vmcnt(8)
	s_waitcnt lgkmcnt(0)
	s_barrier
	s_setprio 1
	v_mfma_f32_16x16x32_bf16 v[108:111], v[128:131], v[160:163], v[108:111]
	v_mfma_f32_16x16x32_bf16 v[76:79], v[136:139], v[160:163], v[76:79]
	v_mfma_f32_16x16x32_bf16 v[104:107], v[128:131], v[168:171], v[104:107]
	v_mfma_f32_16x16x32_bf16 v[72:75], v[136:139], v[168:171], v[72:75]
	v_mfma_f32_16x16x32_bf16 v[100:103], v[128:131], v[194:197], v[100:103]
	v_mfma_f32_16x16x32_bf16 v[68:71], v[136:139], v[194:197], v[68:71]
	v_mfma_f32_16x16x32_bf16 v[96:99], v[128:131], v[202:205], v[96:99]
	v_mfma_f32_16x16x32_bf16 v[64:67], v[136:139], v[202:205], v[64:67]
	v_mfma_f32_16x16x32_bf16 v[108:111], v[132:135], v[164:167], v[108:111]
	v_mfma_f32_16x16x32_bf16 v[76:79], v[140:143], v[164:167], v[76:79]
	v_mfma_f32_16x16x32_bf16 v[104:107], v[132:135], v[172:175], v[104:107]
	v_mfma_f32_16x16x32_bf16 v[72:75], v[140:143], v[172:175], v[72:75]
	v_mfma_f32_16x16x32_bf16 v[100:103], v[132:135], v[198:201], v[100:103]
	v_mfma_f32_16x16x32_bf16 v[68:71], v[140:143], v[198:201], v[68:71]
	v_mfma_f32_16x16x32_bf16 v[96:99], v[132:135], v[206:209], v[96:99]
	v_mfma_f32_16x16x32_bf16 v[64:67], v[140:143], v[206:209], v[64:67]
	s_setprio 0
	s_setprio 1
	v_mfma_f32_16x16x32_bf16 v[44:47], v[144:147], v[160:163], v[44:47]
	v_mfma_f32_16x16x32_bf16 v[12:15], v[152:155], v[160:163], v[12:15]
	v_mfma_f32_16x16x32_bf16 v[40:43], v[144:147], v[168:171], v[40:43]
	v_mfma_f32_16x16x32_bf16 v[8:11], v[152:155], v[168:171], v[8:11]
	v_mfma_f32_16x16x32_bf16 v[36:39], v[144:147], v[194:197], v[36:39]
	v_mfma_f32_16x16x32_bf16 v[4:7], v[152:155], v[194:197], v[4:7]
	v_mfma_f32_16x16x32_bf16 v[32:35], v[144:147], v[202:205], v[32:35]
	v_mfma_f32_16x16x32_bf16 v[0:3], v[152:155], v[202:205], v[0:3]
	v_mfma_f32_16x16x32_bf16 v[44:47], v[148:151], v[164:167], v[44:47]
	v_mfma_f32_16x16x32_bf16 v[12:15], v[156:159], v[164:167], v[12:15]
	v_mfma_f32_16x16x32_bf16 v[40:43], v[148:151], v[172:175], v[40:43]
	v_mfma_f32_16x16x32_bf16 v[8:11], v[156:159], v[172:175], v[8:11]
	v_mfma_f32_16x16x32_bf16 v[36:39], v[148:151], v[198:201], v[36:39]
	v_mfma_f32_16x16x32_bf16 v[4:7], v[156:159], v[198:201], v[4:7]
	v_mfma_f32_16x16x32_bf16 v[32:35], v[148:151], v[206:209], v[32:35]
	v_mfma_f32_16x16x32_bf16 v[0:3], v[156:159], v[206:209], v[0:3]
	s_setprio 0
	s_barrier
	s_add_i32 vcc_lo, vcc_lo, 2
	s_add_u32 s37, s37, 0x100
	s_addc_u32 s97, s97, 0
	s_add_u32 s8, s8, 0x100
	s_addc_u32 s9, s9, 0
	s_cmp_gt_u32 vcc_lo, 29
	s_cbranch_scc0 .LBB0_399
	s_and_b64 vcc, exec, s[22:23]
	s_cbranch_vccz .LBB0_402
	s_barrier

; #define PG8_STAGE(bufoff, gbase, voff) do { _Pragma("unroll") for (int _i = 0; _i < 2; ++_i) \
;         __builtin_amdgcn_global_load_lds((const unsigned*)((const char*)(gbase) + (voff)[_i]), (PG8_LAS unsigned*)(lds + (bufoff) + ldsw + _i * 8192), 16, 0, 0); } while (0)
; #define PG8_LDA(dst, b, h) do { _Pragma("unroll") for (int m = 0; m < 4; ++m) _Pragma("unroll") for (int k = 0; k < 2; ++k) dst[m][k] = *(const PG8_LAS bf16x8*)(lds + PG8_SA(b, h) + aoff + m * 2048 + k * 1024); } while (0)
; #define PG8_LDB(dst, b, h) do { _Pragma("unroll") for (int n = 0; n < 2; ++n) _Pragma("unroll") for (int k = 0; k < 2; ++k) dst[n][k] = *(const PG8_LAS bf16x8*)(lds + PG8_SB(b, h) + boff + n * 2048 + k * 1024); } while (0)
; #define PG8_WAIT_L(n) asm volatile("s_waitcnt lgkmcnt(" #n ")" ::: "memory")
; #define PG8_WAIT_VK do { if constexpr (HALFM) PG8_WAIT_V(6); else PG8_WAIT_V(8); } while (0)
; template <class Epi, class Sched, bool ALIGN_EPI = false, bool SP2 = false, bool HALFM = false, bool AMAP = false>
; __device__ __forceinline__ void gemm_phase(PG8_LAS unsigned char* lds, const Gemm g, const Sched& S, const Epi& E, int tid_in) {
;     ...
;         const char* nA = has_next ? gA + PG8_ATILE(nxt.pm) : cA + (size_t)(nt - 2) * kstep; const char* nB = has_next ? gB + (size_t)nxt.pn * tstepB : cB + (size_t)(nt - 2) * kstep;
;         for (int t = 0; t < nt; t += 2) {
;             const bool last = (t == nt - 2);
;             const char* a1 = cA + (size_t)(t + 1) * kstep;
;             const char* a2 = last ? nA : cA + (size_t)(t + 2) * kstep; const char* b2 = last ? nB : cB + (size_t)(t + 2) * kstep;
;             const char* a3 = a2 + kstep; const char* b3 = b2 + kstep;
;             if (last && has_next) S.a_ready(nxt);
;             if constexpr (SP2) {
;             PG8_LDB(B0, 0, 0); PG8_LDB(B1, 0, 1); PG8_SCHED; PG8_LDA(At, 0, 0); if constexpr (!HALFM) PG8_STAGE(PG8_SA(1, 1), a1 + hstepA, voffA);
;             PG8_WAIT_VK; PG8_WAIT_L(0); PG8_BAR; PG8_MMA(0, 0, At, B0); PG8_MMA(0, 1, At, B1); PG8_BAR; PG8_SCHED;
;             if constexpr (!HALFM) { PG8_LDA(At, 0, 1); } PG8_STAGE(PG8_SB(0, 0), b2, voffB); PG8_STAGE(PG8_SB(0, 1), b2 + hstepB, voffB); PG8_STAGE(PG8_SA(0, 0), a2, voffA);
;             PG8_WAIT_VK; PG8_WAIT_L(0); PG8_BAR; if constexpr (!HALFM) { PG8_MMA(1, 0, At, B0); PG8_MMA(1, 1, At, B1); } PG8_BAR; PG8_SCHED;
.LBB0_489:
	s_ashr_i32 s47, s46, 31
	s_lshl_b64 s[28:29], s[46:47], 16
	s_add_u32 s48, s8, s28
	s_addc_u32 s49, s9, s29
	s_ashr_i32 s45, s44, 31
	s_lshl_b64 s[28:29], s[44:45], 16
	s_add_u32 s58, s12, s28
	v_mov_b32_e32 v4, s49
	s_addc_u32 s59, s13, s29
	s_add_i32 s5, 0, 0x10000
	s_add_i32 s28, 0, 0x14000
	v_cndmask_b32_e64 v137, v3, v4, s[6:7]
	v_mov_b32_e32 v4, s48
	v_add_u32_e32 v14, s5, v151
	v_add_u32_e32 v30, s28, v151
	v_cndmask_b32_e64 v136, v2, v4, s[6:7]
	v_lshl_add_u64 v[66:67], v[2:3], 0, s[84:85]
	ds_read_b128 v[2:5], v14
	ds_read_b128 v[6:9], v14 offset:1024
	ds_read_b128 v[10:13], v14 offset:2048
	ds_read_b128 v[14:17], v14 offset:3072
	ds_read_b128 v[18:21], v30
	ds_read_b128 v[22:25], v30 offset:1024
	ds_read_b128 v[26:29], v30 offset:2048
	ds_read_b128 v[30:33], v30 offset:3072
	v_mov_b32_e32 v34, s59
	v_cndmask_b32_e64 v179, v1, v34, s[6:7]
	v_mov_b32_e32 v1, s58
	v_cndmask_b32_e64 v178, v0, v1, s[6:7]
	v_lshl_add_u64 v[0:1], v[178:179], 0, s[82:83]
	v_lshl_add_u64 v[174:175], v[136:137], 0, s[82:83]
	v_lshl_add_u64 v[68:69], v[66:67], 0, v[144:145]
	s_add_i32 m0, s11, 0xc000
	ds_read_b128 v[34:37], v153
	ds_read_b128 v[38:41], v153 offset:1024
	ds_read_b128 v[42:45], v153 offset:2048
	ds_read_b128 v[46:49], v153 offset:3072
	ds_read_b128 v[50:53], v153 offset:4096
	ds_read_b128 v[54:57], v153 offset:5120
	ds_read_b128 v[58:61], v153 offset:6144
	ds_read_b128 v[62:65], v153 offset:7168
	global_load_lds_dwordx4 v[68:69], off
	v_lshl_add_u64 v[66:67], v[66:67], 0, v[142:143]
	s_add_i32 m0, s11, 0xe000
	s_nop 0
	global_load_lds_dwordx4 v[66:67], off
	s_waitcnt vmcnt(8)
	s_waitcnt lgkmcnt(0)
	s_barrier
	s_setprio 1
	v_mfma_f32_16x16x32_bf16 v[66:69], v[2:5], v[34:37], 0
	v_mfma_f32_16x16x32_bf16 v[70:73], v[10:13], v[34:37], 0
	v_mfma_f32_16x16x32_bf16 v[74:77], v[2:5], v[42:45], 0
	v_mfma_f32_16x16x32_bf16 v[78:81], v[10:13], v[42:45], 0
	v_mfma_f32_16x16x32_bf16 v[84:87], v[2:5], v[50:53], 0
	v_mfma_f32_16x16x32_bf16 v[88:91], v[10:13], v[50:53], 0
	v_mfma_f32_16x16x32_bf16 v[92:95], v[2:5], v[58:61], 0
	v_mfma_f32_16x16x32_bf16 v[96:99], v[10:13], v[58:61], 0
	v_mfma_f32_16x16x32_bf16 v[66:69], v[6:9], v[38:41], v[66:69]
	v_mfma_f32_16x16x32_bf16 v[70:73], v[14:17], v[38:41], v[70:73]
	v_mfma_f32_16x16x32_bf16 v[74:77], v[6:9], v[46:49], v[74:77]
	v_mfma_f32_16x16x32_bf16 v[80:83], v[14:17], v[46:49], v[78:81]
	v_mfma_f32_16x16x32_bf16 v[84:87], v[6:9], v[54:57], v[84:87]
	v_mfma_f32_16x16x32_bf16 v[88:91], v[14:17], v[54:57], v[88:91]
	v_mfma_f32_16x16x32_bf16 v[92:95], v[6:9], v[62:65], v[92:95]
	v_mfma_f32_16x16x32_bf16 v[96:99], v[14:17], v[62:65], v[96:99]
	s_setprio 0
	s_setprio 1
	v_mfma_f32_16x16x32_bf16 v[100:103], v[18:21], v[34:37], 0
	v_mfma_f32_16x16x32_bf16 v[34:37], v[26:29], v[34:37], 0
	v_mfma_f32_16x16x32_bf16 v[100:103], v[22:25], v[38:41], v[100:103]
	v_mfma_f32_16x16x32_bf16 v[34:37], v[30:33], v[38:41], v[34:37]
	v_mfma_f32_16x16x32_bf16 v[38:41], v[18:21], v[42:45], 0
	v_mfma_f32_16x16x32_bf16 v[104:107], v[22:25], v[46:49], v[38:41]
	v_mfma_f32_16x16x32_bf16 v[38:41], v[26:29], v[42:45], 0
	v_mfma_f32_16x16x32_bf16 v[108:111], v[30:33], v[46:49], v[38:41]
	v_mfma_f32_16x16x32_bf16 v[38:41], v[18:21], v[50:53], 0
	v_mfma_f32_16x16x32_bf16 v[112:115], v[22:25], v[54:57], v[38:41]
	v_mfma_f32_16x16x32_bf16 v[38:41], v[26:29], v[50:53], 0
	v_mfma_f32_16x16x32_bf16 v[48:51], v[30:33], v[54:57], v[38:41]
	v_mfma_f32_16x16x32_bf16 v[38:41], v[18:21], v[58:61], 0
	v_mfma_f32_16x16x32_bf16 v[52:55], v[22:25], v[62:65], v[38:41]
	v_mfma_f32_16x16x32_bf16 v[38:41], v[26:29], v[58:61], 0
	v_mfma_f32_16x16x32_bf16 v[56:59], v[30:33], v[62:65], v[38:41]
	s_setprio 0
	s_barrier
	s_add_i32 s5, s5, s10
	v_lshl_add_u64 v[180:181], v[178:179], 0, v[176:177]
	s_mov_b32 m0, s5
	s_nop 1
	ds_read_b128 v[38:41], v153 offset:16384
	ds_read_b128 v[42:45], v153 offset:17408
	ds_read_b128 v[60:63], v153 offset:18432
	ds_read_b128 v[116:119], v153 offset:19456
	ds_read_b128 v[120:123], v153 offset:20480
	ds_read_b128 v[124:127], v153 offset:21504
	ds_read_b128 v[128:131], v153 offset:22528
	ds_read_b128 v[132:135], v153 offset:23552
	global_load_lds_dwordx4 v[180:181], off
	v_lshl_add_u64 v[182:183], v[178:179], 0, v[140:141]
	s_add_i32 m0, s5, 0x2000
	s_add_i32 s5, s28, s10
	global_load_lds_dwordx4 v[182:183], off
	v_lshl_add_u64 v[46:47], v[0:1], 0, v[176:177]
	s_mov_b32 m0, s5
	v_lshl_add_u64 v[0:1], v[0:1], 0, v[140:141]
	global_load_lds_dwordx4 v[46:47], off
	s_add_i32 m0, s5, 0x2000
	v_lshl_add_u64 v[228:229], v[136:137], 0, v[144:145]
	global_load_lds_dwordx4 v[0:1], off
	s_mov_b32 m0, s11
	v_lshl_add_u64 v[230:231], v[136:137], 0, v[142:143]
	global_load_lds_dwordx4 v[228:229], off
	s_mov_b32 m0, s18
	s_nop 0
	global_load_lds_dwordx4 v[230:231], off
	s_waitcnt vmcnt(8)
	s_waitcnt lgkmcnt(0)
	s_barrier
; #define PG8_STAGE(bufoff, gbase, voff) do { _Pragma("unroll") for (int _i = 0; _i < 2; ++_i) \
;         __builtin_amdgcn_global_load_lds((const unsigned*)((const char*)(gbase) + (voff)[_i]), (PG8_LAS unsigned*)(lds + (bufoff) + ldsw + _i * 8192), 16, 0, 0); } while (0)
; #define PG8_LDA(dst, b, h) do { _Pragma("unroll") for (int m = 0; m < 4; ++m) _Pragma("unroll") for (int k = 0; k < 2; ++k) dst[m][k] = *(const PG8_LAS bf16x8*)(lds + PG8_SA(b, h) + aoff + m * 2048 + k * 1024); } while (0)
; #define PG8_LDB(dst, b, h) do { _Pragma("unroll") for (int n = 0; n < 2; ++n) _Pragma("unroll") for (int k = 0; k < 2; ++k) dst[n][k] = *(const PG8_LAS bf16x8*)(lds + PG8_SB(b, h) + boff + n * 2048 + k * 1024); } while (0)
; #define PG8_MMA(ai, bj, At, Bt) do { __builtin_amdgcn_s_setprio(1); _Pragma("unroll") for (int m = 0; m < 4; ++m) _Pragma("unroll") for (int n = 0; n < 2; ++n) _Pragma("unroll") for (int k = 0; k < 2; ++k) \
;         acc[ai][bj][m][n] = __builtin_amdgcn_mfma_f32_16x16x32_bf16(Bt[n][k], At[m][k], acc[ai][bj][m][n], 0, 0, 0); __builtin_amdgcn_s_setprio(0); } while (0)
; #define PG8_WAIT_L(n) asm volatile("s_waitcnt lgkmcnt(" #n ")" ::: "memory")
; #define PG8_WAIT_VK do { if constexpr (HALFM) PG8_WAIT_V(6); else PG8_WAIT_V(8); } while (0)
; #define PG8_BAR __builtin_amdgcn_s_barrier()
; #define PG8_SCHED __builtin_amdgcn_sched_barrier(0)
; template <class Epi, class Sched, bool ALIGN_EPI = false, bool SP2 = false, bool HALFM = false, bool AMAP = false>
; __device__ __forceinline__ void gemm_phase(PG8_LAS unsigned char* lds, const Gemm g, const Sched& S, const Epi& E, int tid_in) {
;     ...
;             PG8_WAIT_VK; PG8_WAIT_L(0); PG8_BAR; if constexpr (!HALFM) { PG8_MMA(1, 0, At, B0); PG8_MMA(1, 1, At, B1); } PG8_BAR; PG8_SCHED;
;             PG8_LDB(B0, 1, 0); PG8_LDB(B1, 1, 1); PG8_SCHED; PG8_LDA(At, 1, 0); if constexpr (!HALFM) PG8_STAGE(PG8_SA(0, 1), a2 + hstepA, voffA);
;             PG8_WAIT_VK; PG8_WAIT_L(0); PG8_BAR; PG8_MMA(0, 0, At, B0); PG8_MMA(0, 1, At, B1); PG8_BAR; PG8_SCHED;
	s_setprio 1
	v_mfma_f32_16x16x32_bf16 v[136:139], v[2:5], v[38:41], 0
	v_mfma_f32_16x16x32_bf16 v[154:157], v[2:5], v[60:63], 0
	v_mfma_f32_16x16x32_bf16 v[162:165], v[2:5], v[120:123], 0
	v_mfma_f32_16x16x32_bf16 v[0:3], v[2:5], v[128:131], 0
	v_mfma_f32_16x16x32_bf16 v[170:173], v[6:9], v[132:135], v[0:3]
	v_mfma_f32_16x16x32_bf16 v[0:3], v[10:13], v[128:131], 0
	v_mfma_f32_16x16x32_bf16 v[136:139], v[6:9], v[42:45], v[136:139]
	v_mfma_f32_16x16x32_bf16 v[146:149], v[10:13], v[38:41], 0
	v_mfma_f32_16x16x32_bf16 v[154:157], v[6:9], v[116:119], v[154:157]
	v_mfma_f32_16x16x32_bf16 v[158:161], v[10:13], v[60:63], 0
	v_mfma_f32_16x16x32_bf16 v[162:165], v[6:9], v[124:127], v[162:165]
	v_mfma_f32_16x16x32_bf16 v[166:169], v[10:13], v[120:123], 0
	v_mfma_f32_16x16x32_bf16 v[8:11], v[14:17], v[132:135], v[0:3]
	v_mfma_f32_16x16x32_bf16 v[146:149], v[14:17], v[42:45], v[146:149]
	v_mfma_f32_16x16x32_bf16 v[158:161], v[14:17], v[116:119], v[158:161]
	v_mfma_f32_16x16x32_bf16 v[166:169], v[14:17], v[124:127], v[166:169]
	s_setprio 0
	s_setprio 1
	v_mfma_f32_16x16x32_bf16 v[0:3], v[18:21], v[38:41], 0
	v_mfma_f32_16x16x32_bf16 v[12:15], v[22:25], v[42:45], v[0:3]
	v_mfma_f32_16x16x32_bf16 v[0:3], v[26:29], v[38:41], 0
	v_mfma_f32_16x16x32_bf16 v[184:187], v[30:33], v[42:45], v[0:3]
	v_mfma_f32_16x16x32_bf16 v[0:3], v[18:21], v[60:63], 0
	v_mfma_f32_16x16x32_bf16 v[188:191], v[22:25], v[116:119], v[0:3]
	v_mfma_f32_16x16x32_bf16 v[0:3], v[26:29], v[60:63], 0
	v_mfma_f32_16x16x32_bf16 v[116:119], v[30:33], v[116:119], v[0:3]
	v_mfma_f32_16x16x32_bf16 v[0:3], v[18:21], v[120:123], 0
	v_mfma_f32_16x16x32_bf16 v[192:195], v[22:25], v[124:127], v[0:3]
	v_mfma_f32_16x16x32_bf16 v[0:3], v[26:29], v[120:123], 0
	v_mfma_f32_16x16x32_bf16 v[120:123], v[30:33], v[124:127], v[0:3]
	v_mfma_f32_16x16x32_bf16 v[0:3], v[18:21], v[128:131], 0
	v_mfma_f32_16x16x32_bf16 v[196:199], v[22:25], v[132:135], v[0:3]
	v_mfma_f32_16x16x32_bf16 v[0:3], v[26:29], v[128:131], 0
	v_mfma_f32_16x16x32_bf16 v[200:203], v[30:33], v[132:135], v[0:3]
	s_setprio 0
	s_barrier
	s_add_i32 s5, 0, 0x18000
	s_nop 3
	v_add_u32_e32 v0, s5, v151
	s_add_i32 s28, 0, 0x1c000
	ds_read_b128 v[24:27], v0
	ds_read_b128 v[28:31], v0 offset:1024
	ds_read_b128 v[204:207], v0 offset:2048
	ds_read_b128 v[208:211], v0 offset:3072
	v_add_u32_e32 v0, s28, v151
	ds_read_b128 v[212:215], v0
	ds_read_b128 v[216:219], v0 offset:1024
	ds_read_b128 v[222:225], v0 offset:2048
	ds_read_b128 v[232:235], v0 offset:3072
	s_mov_b32 m0, s19
	v_lshl_add_u64 v[16:17], v[174:175], 0, v[144:145]
	ds_read_b128 v[0:3], v153 offset:32768
	ds_read_b128 v[4:7], v153 offset:33792
	ds_read_b128 v[60:63], v153 offset:34816
	ds_read_b128 v[132:135], v153 offset:35840
	ds_read_b128 v[236:239], v153 offset:36864
	ds_read_b128 v[240:243], v153 offset:37888
	ds_read_b128 v[244:247], v153 offset:38912
	ds_read_b128 v[248:251], v153 offset:39936
	global_load_lds_dwordx4 v[16:17], off
	v_lshl_add_u64 v[16:17], v[174:175], 0, v[142:143]
	s_mov_b32 m0, s25
	s_nop 0
	global_load_lds_dwordx4 v[16:17], off
	s_waitcnt vmcnt(8)
	s_waitcnt lgkmcnt(0)
	s_barrier
	s_setprio 1
	v_mfma_f32_16x16x32_bf16 v[16:19], v[24:27], v[0:3], v[66:69]
	v_mfma_f32_16x16x32_bf16 v[128:131], v[28:31], v[4:7], v[16:19]
	v_mfma_f32_16x16x32_bf16 v[16:19], v[204:207], v[0:3], v[70:73]
	v_mfma_f32_16x16x32_bf16 v[124:127], v[208:211], v[4:7], v[16:19]
	v_mfma_f32_16x16x32_bf16 v[16:19], v[24:27], v[60:63], v[74:77]
	v_mfma_f32_16x16x32_bf16 v[76:79], v[28:31], v[132:135], v[16:19]
	v_mfma_f32_16x16x32_bf16 v[16:19], v[204:207], v[60:63], v[80:83]
	v_mfma_f32_16x16x32_bf16 v[72:75], v[208:211], v[132:135], v[16:19]
	v_mfma_f32_16x16x32_bf16 v[16:19], v[24:27], v[236:239], v[84:87]
	v_mfma_f32_16x16x32_bf16 v[44:47], v[28:31], v[240:243], v[16:19]
	v_mfma_f32_16x16x32_bf16 v[16:19], v[204:207], v[236:239], v[88:91]
	v_mfma_f32_16x16x32_bf16 v[40:43], v[208:211], v[240:243], v[16:19]
	v_mfma_f32_16x16x32_bf16 v[16:19], v[24:27], v[244:247], v[92:95]
	v_mfma_f32_16x16x32_bf16 v[20:23], v[28:31], v[248:251], v[16:19]
	v_mfma_f32_16x16x32_bf16 v[16:19], v[204:207], v[244:247], v[96:99]
	v_mfma_f32_16x16x32_bf16 v[16:19], v[208:211], v[248:251], v[16:19]
	s_setprio 0
	s_setprio 1
	v_mfma_f32_16x16x32_bf16 v[64:67], v[212:215], v[0:3], v[100:103]
	v_mfma_f32_16x16x32_bf16 v[0:3], v[222:225], v[0:3], v[34:37]
	v_mfma_f32_16x16x32_bf16 v[96:99], v[232:235], v[4:7], v[0:3]
	v_mfma_f32_16x16x32_bf16 v[0:3], v[212:215], v[60:63], v[104:107]
	v_mfma_f32_16x16x32_bf16 v[68:71], v[216:219], v[132:135], v[0:3]
	v_mfma_f32_16x16x32_bf16 v[0:3], v[222:225], v[60:63], v[108:111]
	v_mfma_f32_16x16x32_bf16 v[100:103], v[216:219], v[4:7], v[64:67]
	v_mfma_f32_16x16x32_bf16 v[64:67], v[232:235], v[132:135], v[0:3]
	v_mfma_f32_16x16x32_bf16 v[0:3], v[212:215], v[236:239], v[112:115]
	v_mfma_f32_16x16x32_bf16 v[36:39], v[216:219], v[240:243], v[0:3]
	v_mfma_f32_16x16x32_bf16 v[0:3], v[222:225], v[236:239], v[48:51]
	v_mfma_f32_16x16x32_bf16 v[32:35], v[232:235], v[240:243], v[0:3]
	v_mfma_f32_16x16x32_bf16 v[0:3], v[212:215], v[244:247], v[52:55]
	v_mfma_f32_16x16x32_bf16 v[4:7], v[216:219], v[248:251], v[0:3]
	v_mfma_f32_16x16x32_bf16 v[0:3], v[222:225], v[244:247], v[56:59]
	v_mfma_f32_16x16x32_bf16 v[0:3], v[232:235], v[248:251], v[0:3]
	s_setprio 0
	s_barrier
; __device__ __forceinline__ int opaque0() { int z; asm volatile("v_mov_b32 %0, 0" : "=v"(z)); return z; }
; #define PG8_STAGE(bufoff, gbase, voff) do { _Pragma("unroll") for (int _i = 0; _i < 2; ++_i) \
;         __builtin_amdgcn_global_load_lds((const unsigned*)((const char*)(gbase) + (voff)[_i]), (PG8_LAS unsigned*)(lds + (bufoff) + ldsw + _i * 8192), 16, 0, 0); } while (0)
; #define PG8_LDA(dst, b, h) do { _Pragma("unroll") for (int m = 0; m < 4; ++m) _Pragma("unroll") for (int k = 0; k < 2; ++k) dst[m][k] = *(const PG8_LAS bf16x8*)(lds + PG8_SA(b, h) + aoff + m * 2048 + k * 1024); } while (0)
; #define PG8_MMA(ai, bj, At, Bt) do { __builtin_amdgcn_s_setprio(1); _Pragma("unroll") for (int m = 0; m < 4; ++m) _Pragma("unroll") for (int n = 0; n < 2; ++n) _Pragma("unroll") for (int k = 0; k < 2; ++k) \
;         acc[ai][bj][m][n] = __builtin_amdgcn_mfma_f32_16x16x32_bf16(Bt[n][k], At[m][k], acc[ai][bj][m][n], 0, 0, 0); __builtin_amdgcn_s_setprio(0); } while (0)
; #define PG8_WAIT_L(n) asm volatile("s_waitcnt lgkmcnt(" #n ")" ::: "memory")
; #define PG8_WAIT_VK do { if constexpr (HALFM) PG8_WAIT_V(6); else PG8_WAIT_V(8); } while (0)
; #define PG8_BAR __builtin_amdgcn_s_barrier()
; #define PG8_SCHED __builtin_amdgcn_sched_barrier(0)
;     __device__ __forceinline__ void operator()(const f32x4 (&acc)[2][2][4][2], const Unit& u, int wr, int wc, int fr, int fq) const {
;         const int z = opaque0(); fr += z; const int s2 = 32 * (wc & 1) + 8 * fq + z;
; #pragma unroll
;         for (int m = 0; m < 4; ++m) { const int k1 = wr * 64 + m * 16 + fr;
;             const f32x4 c0 = *(const f32x4*)(TWC + k1 * 64 + s2), c1 = *(const f32x4*)(TWC + k1 * 64 + s2 + 4), s0 = *(const f32x4*)(TWS + k1 * 64 + s2), s1 = *(const f32x4*)(TWS + k1 * 64 + s2 + 4);
; template <class Epi, class Sched, bool ALIGN_EPI = false, bool SP2 = false, bool HALFM = false, bool AMAP = false>
; __device__ __forceinline__ void gemm_phase(PG8_LAS unsigned char* lds, const Gemm g, const Sched& S, const Epi& E, int tid_in) {
;     ...
;             if constexpr (!HALFM) { PG8_LDA(At, 1, 1); } PG8_STAGE(PG8_SB(1, 0), b3, voffB); PG8_STAGE(PG8_SB(1, 1), b3 + hstepB, voffB); PG8_STAGE(PG8_SA(1, 0), a3, voffA);
;             PG8_WAIT_VK; PG8_WAIT_L(0); PG8_BAR; if constexpr (!HALFM) { PG8_MMA(1, 0, At, B0); PG8_MMA(1, 1, At, B1); } PG8_BAR; PG8_SCHED;
	s_add_i32 s5, s5, s10
	v_lshl_add_u64 v[56:57], v[180:181], 0, s[66:67]
	s_mov_b32 m0, s5
	ds_read_b128 v[48:51], v153 offset:49152
	ds_read_b128 v[52:55], v153 offset:50176
	ds_read_b128 v[80:83], v153 offset:51200
	ds_read_b128 v[112:115], v153 offset:52224
	ds_read_b128 v[236:239], v153 offset:53248
	ds_read_b128 v[240:243], v153 offset:54272
	ds_read_b128 v[244:247], v153 offset:55296
	ds_read_b128 v[248:251], v153 offset:56320
	global_load_lds_dwordx4 v[56:57], off
	v_lshl_add_u64 v[56:57], v[182:183], 0, s[66:67]
	s_add_i32 m0, s5, 0x2000
	s_add_i32 s5, s28, s10
	global_load_lds_dwordx4 v[56:57], off
	v_lshl_add_u64 v[56:57], v[178:179], 0, s[84:85]
	v_lshl_add_u64 v[58:59], v[56:57], 0, v[176:177]
	s_mov_b32 m0, s5
	v_lshl_add_u64 v[56:57], v[56:57], 0, v[140:141]
	global_load_lds_dwordx4 v[58:59], off
	s_add_i32 m0, s5, 0x2000
	s_nop 0
	global_load_lds_dwordx4 v[56:57], off
	v_lshl_add_u64 v[56:57], v[228:229], 0, s[66:67]
	s_mov_b32 m0, s30
	s_nop 0
	global_load_lds_dwordx4 v[56:57], off
	v_lshl_add_u64 v[56:57], v[230:231], 0, s[66:67]
	s_mov_b32 m0, s31
	s_nop 0
	global_load_lds_dwordx4 v[56:57], off
	s_waitcnt vmcnt(8)
	s_waitcnt lgkmcnt(0)
	s_barrier
	s_setprio 1
	v_mfma_f32_16x16x32_bf16 v[56:59], v[24:27], v[48:51], v[136:139]
	v_mfma_f32_16x16x32_bf16 v[136:139], v[28:31], v[52:55], v[56:59]
	v_mfma_f32_16x16x32_bf16 v[56:59], v[204:207], v[48:51], v[146:149]
	v_mfma_f32_16x16x32_bf16 v[132:135], v[208:211], v[52:55], v[56:59]
	v_mfma_f32_16x16x32_bf16 v[56:59], v[24:27], v[80:83], v[154:157]
	v_mfma_f32_16x16x32_bf16 v[92:95], v[28:31], v[112:115], v[56:59]
	v_mfma_f32_16x16x32_bf16 v[56:59], v[204:207], v[80:83], v[158:161]
	v_mfma_f32_16x16x32_bf16 v[88:91], v[208:211], v[112:115], v[56:59]
	v_mfma_f32_16x16x32_bf16 v[56:59], v[24:27], v[236:239], v[162:165]
	v_mfma_f32_16x16x32_bf16 v[60:63], v[28:31], v[240:243], v[56:59]
	v_mfma_f32_16x16x32_bf16 v[56:59], v[204:207], v[236:239], v[166:169]
	v_mfma_f32_16x16x32_bf16 v[24:27], v[24:27], v[244:247], v[170:173]
	v_mfma_f32_16x16x32_bf16 v[8:11], v[204:207], v[244:247], v[8:11]
	v_mfma_f32_16x16x32_bf16 v[56:59], v[208:211], v[240:243], v[56:59]
	v_mfma_f32_16x16x32_bf16 v[28:31], v[28:31], v[248:251], v[24:27]
	v_mfma_f32_16x16x32_bf16 v[24:27], v[208:211], v[248:251], v[8:11]
	s_setprio 0
	s_setprio 1
	v_mfma_f32_16x16x32_bf16 v[8:11], v[212:215], v[48:51], v[12:15]
	v_mfma_f32_16x16x32_bf16 v[108:111], v[216:219], v[52:55], v[8:11]
	v_mfma_f32_16x16x32_bf16 v[8:11], v[222:225], v[48:51], v[184:187]
	v_mfma_f32_16x16x32_bf16 v[104:107], v[232:235], v[52:55], v[8:11]
	v_mfma_f32_16x16x32_bf16 v[8:11], v[212:215], v[80:83], v[188:191]
	v_mfma_f32_16x16x32_bf16 v[84:87], v[216:219], v[112:115], v[8:11]
	v_mfma_f32_16x16x32_bf16 v[8:11], v[222:225], v[80:83], v[116:119]
	v_mfma_f32_16x16x32_bf16 v[80:83], v[232:235], v[112:115], v[8:11]
	v_mfma_f32_16x16x32_bf16 v[8:11], v[212:215], v[236:239], v[192:195]
	v_mfma_f32_16x16x32_bf16 v[52:55], v[216:219], v[240:243], v[8:11]
	v_mfma_f32_16x16x32_bf16 v[8:11], v[222:225], v[236:239], v[120:123]
	v_mfma_f32_16x16x32_bf16 v[48:51], v[232:235], v[240:243], v[8:11]
	v_mfma_f32_16x16x32_bf16 v[8:11], v[212:215], v[244:247], v[196:199]
	v_mfma_f32_16x16x32_bf16 v[12:15], v[216:219], v[248:251], v[8:11]
	v_mfma_f32_16x16x32_bf16 v[8:11], v[222:225], v[244:247], v[200:203]
	v_mfma_f32_16x16x32_bf16 v[8:11], v[232:235], v[248:251], v[8:11]
	s_setprio 0
	s_barrier
	s_andn2_b64 vcc, exec, s[40:41]
	s_cbranch_vccnz .LBB0_491
	s_barrier
.LBB0_491:
	v_mov_b32 v112, 0
	s_lshl_b32 s4, s4, 2
	v_add_u32_e32 v148, v112, v150
	v_add_u32_e32 v158, v152, v112
	v_lshlrev_b32_e32 v112, 6, v148
	v_ashrrev_i32_e32 v113, 31, v112
	v_ashrrev_i32_e32 v159, 31, v158
	v_lshlrev_b64 v[120:121], 2, v[112:113]
	v_lshl_add_u64 v[112:113], s[20:21], 0, v[120:121]
	v_lshlrev_b64 v[146:147], 2, v[158:159]
	v_lshl_add_u64 v[120:121], s[22:23], 0, v[120:121]
	v_lshl_add_u64 v[116:117], v[112:113], 0, v[146:147]
	v_lshl_add_u64 v[154:155], v[120:121], 0, v[146:147]
	global_load_dwordx4 v[112:115], v[116:117], off offset:16
	s_nop 0
	global_load_dwordx4 v[116:119], v[116:117], off
	s_nop 0
	global_load_dwordx4 v[120:123], v[154:155], off offset:16
	s_nop 0
	global_load_dwordx4 v[154:157], v[154:155], off
	v_add_u32_e32 v174, 16, v148
	v_lshlrev_b32_e32 v174, 8, v174
	v_ashrrev_i32_e32 v175, 31, v174
	v_lshl_add_u64 v[218:219], s[20:21], 0, v[174:175]
	v_lshl_add_u64 v[218:219], v[218:219], 0, v[146:147]
	global_load_dwordx4 v[170:173], v[218:219], off offset:16
	global_load_dwordx4 v[178:181], v[218:219], off
	s_nop 0
	v_lshl_add_u64 v[218:219], s[22:23], 0, v[174:175]
	v_lshl_add_u64 v[218:219], v[218:219], 0, v[146:147]
	global_load_dwordx4 v[182:185], v[218:219], off offset:16
	global_load_dwordx4 v[186:189], v[218:219], off
	s_nop 0
	v_add_u32_e32 v174, 32, v148
	v_lshlrev_b32_e32 v174, 8, v174
	v_ashrrev_i32_e32 v175, 31, v174
	v_lshl_add_u64 v[218:219], s[20:21], 0, v[174:175]
	v_lshl_add_u64 v[218:219], v[218:219], 0, v[146:147]
	global_load_dwordx4 v[190:193], v[218:219], off offset:16
	global_load_dwordx4 v[194:197], v[218:219], off
	s_nop 0
	v_lshl_add_u64 v[218:219], s[22:23], 0, v[174:175]
	v_lshl_add_u64 v[218:219], v[218:219], 0, v[146:147]
	global_load_dwordx4 v[198:201], v[218:219], off offset:16
	global_load_dwordx4 v[202:205], v[218:219], off
	s_nop 0
	v_add_u32_e32 v174, 48, v148
	v_lshlrev_b32_e32 v174, 8, v174
	v_ashrrev_i32_e32 v175, 31, v174
	v_lshl_add_u64 v[218:219], s[20:21], 0, v[174:175]
	v_lshl_add_u64 v[218:219], v[218:219], 0, v[146:147]
	global_load_dwordx4 v[206:209], v[218:219], off offset:16
	global_load_dwordx4 v[210:213], v[218:219], off
	s_nop 0
	v_lshl_add_u64 v[218:219], s[22:23], 0, v[174:175]
	v_lshl_add_u64 v[218:219], v[218:219], 0, v[146:147]
	global_load_dwordx4 v[214:217], v[218:219], off offset:16
	global_load_dwordx4 v[222:225], v[218:219], off
	s_nop 0
	s_or_b32 s28, s4, s36
	v_ashrrev_i32_e32 v149, 31, v148
	v_lshlrev_b64 v[160:161], 18, v[148:149]
	s_ashr_i32 s29, s28, 31
	s_lshl_b64 s[62:63], s[28:29], 8
	s_or_b32 s4, s28, 2
	s_ashr_i32 s5, s4, 31
	s_lshl_b64 s[60:61], s[4:5], 8
	s_mov_b64 s[28:29], -1
	s_andn2_b64 vcc, exec, s[6:7]
	s_waitcnt vmcnt(12)
; __device__ __forceinline__ unsigned cvt_pk_bf16(float lo, float hi) { unsigned r; asm volatile("v_cvt_pk_bf16_f32 %0, %1, %2" : "=v"(r) : "v"(lo), "v"(hi)); return r; }
;     __device__ __forceinline__ void operator()(const f32x4 (&acc)[2][2][4][2], const Unit& u, int wr, int wc, int fr, int fq) const {
;     ...
;         for (int m = 0; m < 4; ++m) { const int k1 = wr * 64 + m * 16 + fr;
;             const f32x4 c0 = *(const f32x4*)(TWC + k1 * 64 + s2), c1 = *(const f32x4*)(TWC + k1 * 64 + s2 + 4), s0 = *(const f32x4*)(TWS + k1 * 64 + s2), s1 = *(const f32x4*)(TWS + k1 * 64 + s2 + 4);
; #pragma unroll
;             for (int bj = 0; bj < 2; ++bj) { const int col = 4 * u.pn + 2 * bj + (wc >> 1);
;                 const f32x4 r0 = acc[0][bj][m][0], r1 = acc[0][bj][m][1], i0 = acc[1][bj][m][0], i1 = acc[1][bj][m][1];
;                 const f32x4 or0 = r0 * c0 + i0 * s0, or1 = r1 * c1 + i1 * s1, oi0 = i0 * c0 - r0 * s0, oi1 = i1 * c1 - r1 * s1;
;                 bf16_t* dst = O1T + ((size_t)k1 * 1024 + col) * 128 + s2;
;                 u32x4 w; w.x = cvt_pk_bf16(or0[0], or0[1]); w.y = cvt_pk_bf16(or0[2], or0[3]); w.z = cvt_pk_bf16(or1[0], or1[1]); w.w = cvt_pk_bf16(or1[2], or1[3]);
;                 *(u32x4*)dst = w;
;                 w.x = cvt_pk_bf16(oi0[0], oi0[1]); w.y = cvt_pk_bf16(oi0[2], oi0[3]); w.z = cvt_pk_bf16(oi1[0], oi1[1]); w.w = cvt_pk_bf16(oi1[2], oi1[3]);
;                 *(u32x4*)(dst + 64) = w; }
	v_pk_mul_f32 v[166:167], v[134:135], v[122:123]
	v_pk_mul_f32 v[162:163], v[138:139], v[156:157]
	v_pk_mul_f32 v[168:169], v[132:133], v[120:121]
	v_pk_fma_f32 v[162:163], v[130:131], v[118:119], v[162:163]
	v_pk_mul_f32 v[130:131], v[130:131], v[156:157]
	v_pk_mul_f32 v[164:165], v[136:137], v[154:155]
	v_pk_fma_f32 v[166:167], v[126:127], v[114:115], v[166:167]
	v_pk_fma_f32 v[168:169], v[124:125], v[112:113], v[168:169]
	v_pk_fma_f32 v[130:131], v[138:139], v[118:119], v[130:131] neg_lo:[0,0,1] neg_hi:[0,0,1]
	v_pk_mul_f32 v[126:127], v[126:127], v[122:123]
	v_pk_mul_f32 v[124:125], v[124:125], v[120:121]
	v_lshl_add_u64 v[138:139], s[16:17], 0, v[160:161]
	v_pk_fma_f32 v[164:165], v[128:129], v[116:117], v[164:165]
	v_pk_mul_f32 v[128:129], v[128:129], v[154:155]
	v_pk_fma_f32 v[134:135], v[134:135], v[114:115], v[126:127] neg_lo:[0,0,1] neg_hi:[0,0,1]
	v_pk_fma_f32 v[132:133], v[132:133], v[112:113], v[124:125] neg_lo:[0,0,1] neg_hi:[0,0,1]
	v_lshl_add_u64 v[126:127], v[138:139], 0, s[62:63]
	v_lshlrev_b64 v[124:125], 1, v[158:159]
	v_pk_fma_f32 v[136:137], v[136:137], v[116:117], v[128:129] neg_lo:[0,0,1] neg_hi:[0,0,1]
	v_lshl_add_u64 v[158:159], v[126:127], 0, v[124:125]
	v_cvt_pk_bf16_f32 v126, v164, v165
	v_cvt_pk_bf16_f32 v127, v162, v163
	v_cvt_pk_bf16_f32 v128, v168, v169
	v_cvt_pk_bf16_f32 v129, v166, v167
	global_store_dwordx4 v[158:159], v[126:129], off
	s_nop 1
	v_cvt_pk_bf16_f32 v126, v136, v137
	v_cvt_pk_bf16_f32 v127, v130, v131
	v_cvt_pk_bf16_f32 v128, v132, v133
	v_cvt_pk_bf16_f32 v129, v134, v135
	v_pk_mul_f32 v[132:133], v[104:105], v[120:121]
	global_store_dwordx4 v[158:159], v[126:129], off offset:128
	v_pk_mul_f32 v[130:131], v[106:107], v[122:123]
	v_pk_fma_f32 v[132:133], v[96:97], v[112:113], v[132:133]
	v_pk_mul_f32 v[128:129], v[108:109], v[154:155]
	v_pk_mul_f32 v[96:97], v[96:97], v[120:121]
	v_pk_mul_f32 v[126:127], v[110:111], v[156:157]
	v_pk_fma_f32 v[128:129], v[100:101], v[116:117], v[128:129]
	v_pk_fma_f32 v[130:131], v[98:99], v[114:115], v[130:131]
	v_pk_mul_f32 v[100:101], v[100:101], v[154:155]
	v_pk_mul_f32 v[98:99], v[98:99], v[122:123]
	v_pk_fma_f32 v[104:105], v[104:105], v[112:113], v[96:97] neg_lo:[0,0,1] neg_hi:[0,0,1]
	v_lshl_add_u64 v[96:97], v[138:139], 0, s[60:61]
	v_pk_fma_f32 v[126:127], v[102:103], v[118:119], v[126:127]
	v_pk_mul_f32 v[102:103], v[102:103], v[156:157]
	v_pk_fma_f32 v[100:101], v[108:109], v[116:117], v[100:101] neg_lo:[0,0,1] neg_hi:[0,0,1]
	v_pk_fma_f32 v[106:107], v[106:107], v[114:115], v[98:99] neg_lo:[0,0,1] neg_hi:[0,0,1]
	v_lshl_add_u64 v[108:109], v[96:97], 0, v[124:125]
	v_cvt_pk_bf16_f32 v96, v128, v129
	v_cvt_pk_bf16_f32 v97, v126, v127
	v_cvt_pk_bf16_f32 v98, v132, v133
	v_cvt_pk_bf16_f32 v99, v130, v131
	v_pk_fma_f32 v[102:103], v[110:111], v[118:119], v[102:103] neg_lo:[0,0,1] neg_hi:[0,0,1]
	global_store_dwordx4 v[108:109], v[96:99], off
	s_nop 1
	v_cvt_pk_bf16_f32 v96, v100, v101
	v_cvt_pk_bf16_f32 v97, v102, v103
	v_cvt_pk_bf16_f32 v98, v104, v105
	v_cvt_pk_bf16_f32 v99, v106, v107
	global_store_dwordx4 v[108:109], v[96:99], off offset:128
	v_add_u32_e32 v108, 16, v148
	v_ashrrev_i32_e32 v109, 31, v108
	v_lshlrev_b32_e32 v96, 6, v108
	v_ashrrev_i32_e32 v97, 31, v96
	v_lshlrev_b64 v[104:105], 2, v[96:97]
	v_lshl_add_u64 v[96:97], s[20:21], 0, v[104:105]
	v_lshl_add_u64 v[104:105], s[22:23], 0, v[104:105]
	v_lshl_add_u64 v[100:101], v[96:97], 0, v[146:147]
	v_lshl_add_u64 v[110:111], v[104:105], 0, v[146:147]
	v_lshlrev_b64 v[108:109], 18, v[108:109]
	s_waitcnt vmcnt(12)
	v_pk_mul_f32 v[120:121], v[88:89], v[182:183]
	v_pk_mul_f32 v[116:117], v[92:93], v[186:187]
	v_pk_mul_f32 v[114:115], v[94:95], v[188:189]
	v_pk_fma_f32 v[116:117], v[76:77], v[178:179], v[116:117]
	v_pk_mul_f32 v[76:77], v[76:77], v[186:187]
	v_pk_mul_f32 v[118:119], v[90:91], v[184:185]
	v_pk_fma_f32 v[120:121], v[72:73], v[170:171], v[120:121]
	v_pk_fma_f32 v[76:77], v[92:93], v[178:179], v[76:77] neg_lo:[0,0,1] neg_hi:[0,0,1]
	v_pk_mul_f32 v[72:73], v[72:73], v[182:183]
	v_lshl_add_u64 v[92:93], s[16:17], 0, v[108:109]
	v_pk_fma_f32 v[114:115], v[78:79], v[180:181], v[114:115]
	v_pk_fma_f32 v[118:119], v[74:75], v[172:173], v[118:119]
	v_pk_mul_f32 v[78:79], v[78:79], v[188:189]
	v_pk_mul_f32 v[74:75], v[74:75], v[184:185]
	v_pk_fma_f32 v[88:89], v[88:89], v[170:171], v[72:73] neg_lo:[0,0,1] neg_hi:[0,0,1]
	v_lshl_add_u64 v[72:73], v[92:93], 0, s[62:63]
	v_pk_fma_f32 v[78:79], v[94:95], v[180:181], v[78:79] neg_lo:[0,0,1] neg_hi:[0,0,1]
	v_pk_fma_f32 v[90:91], v[90:91], v[172:173], v[74:75] neg_lo:[0,0,1] neg_hi:[0,0,1]
	v_lshl_add_u64 v[94:95], v[72:73], 0, v[124:125]
	v_cvt_pk_bf16_f32 v72, v116, v117
	v_cvt_pk_bf16_f32 v73, v114, v115
	v_cvt_pk_bf16_f32 v74, v120, v121
	v_cvt_pk_bf16_f32 v75, v118, v119
	global_store_dwordx4 v[94:95], v[72:75], off
	s_nop 1
	v_cvt_pk_bf16_f32 v72, v76, v77
	v_cvt_pk_bf16_f32 v73, v78, v79
	v_cvt_pk_bf16_f32 v74, v88, v89
	v_cvt_pk_bf16_f32 v75, v90, v91
	v_pk_mul_f32 v[78:79], v[80:81], v[182:183]
	global_store_dwordx4 v[94:95], v[72:75], off offset:128
	v_pk_fma_f32 v[78:79], v[64:65], v[170:171], v[78:79]
	v_pk_mul_f32 v[64:65], v[64:65], v[182:183]
	v_pk_mul_f32 v[74:75], v[84:85], v[186:187]
	v_pk_mul_f32 v[76:77], v[82:83], v[184:185]
	v_pk_fma_f32 v[74:75], v[68:69], v[178:179], v[74:75]
	v_pk_mul_f32 v[68:69], v[68:69], v[186:187]
	v_pk_fma_f32 v[80:81], v[80:81], v[170:171], v[64:65] neg_lo:[0,0,1] neg_hi:[0,0,1]
	v_lshl_add_u64 v[64:65], v[92:93], 0, s[60:61]
	v_pk_mul_f32 v[72:73], v[86:87], v[188:189]
	v_pk_fma_f32 v[76:77], v[66:67], v[172:173], v[76:77]
	v_pk_fma_f32 v[68:69], v[84:85], v[178:179], v[68:69] neg_lo:[0,0,1] neg_hi:[0,0,1]
	v_pk_mul_f32 v[66:67], v[66:67], v[184:185]
	v_lshl_add_u64 v[84:85], v[64:65], 0, v[124:125]
	v_cvt_pk_bf16_f32 v64, v74, v75
	v_pk_fma_f32 v[72:73], v[70:71], v[180:181], v[72:73]
	v_pk_mul_f32 v[70:71], v[70:71], v[188:189]
	v_pk_fma_f32 v[82:83], v[82:83], v[172:173], v[66:67] neg_lo:[0,0,1] neg_hi:[0,0,1]
	v_cvt_pk_bf16_f32 v65, v72, v73
	v_cvt_pk_bf16_f32 v66, v78, v79
	v_cvt_pk_bf16_f32 v67, v76, v77
	global_store_dwordx4 v[84:85], v[64:67], off
	v_add_u32_e32 v76, 32, v148
	v_pk_fma_f32 v[70:71], v[86:87], v[180:181], v[70:71] neg_lo:[0,0,1] neg_hi:[0,0,1]
	v_cvt_pk_bf16_f32 v64, v68, v69
	v_ashrrev_i32_e32 v77, 31, v76
	v_cvt_pk_bf16_f32 v65, v70, v71
	v_cvt_pk_bf16_f32 v66, v80, v81
	v_cvt_pk_bf16_f32 v67, v82, v83
	global_store_dwordx4 v[84:85], v[64:67], off offset:128
	s_nop 1
	v_lshlrev_b32_e32 v64, 6, v76
	v_ashrrev_i32_e32 v65, 31, v64
	v_lshlrev_b64 v[72:73], 2, v[64:65]
	v_lshl_add_u64 v[64:65], s[20:21], 0, v[72:73]
	v_lshl_add_u64 v[72:73], s[22:23], 0, v[72:73]
	v_lshl_add_u64 v[68:69], v[64:65], 0, v[146:147]
	v_lshl_add_u64 v[78:79], v[72:73], 0, v[146:147]
	v_lshlrev_b64 v[76:77], 18, v[76:77]
	s_waitcnt vmcnt(12)
; __device__ __forceinline__ unsigned cvt_pk_bf16(float lo, float hi) { unsigned r; asm volatile("v_cvt_pk_bf16_f32 %0, %1, %2" : "=v"(r) : "v"(lo), "v"(hi)); return r; }
;     __device__ __forceinline__ void operator()(const f32x4 (&acc)[2][2][4][2], const Unit& u, int wr, int wc, int fr, int fq) const {
;     ...
;         for (int m = 0; m < 4; ++m) { const int k1 = wr * 64 + m * 16 + fr;
;             const f32x4 c0 = *(const f32x4*)(TWC + k1 * 64 + s2), c1 = *(const f32x4*)(TWC + k1 * 64 + s2 + 4), s0 = *(const f32x4*)(TWS + k1 * 64 + s2), s1 = *(const f32x4*)(TWS + k1 * 64 + s2 + 4);
; #pragma unroll
;             for (int bj = 0; bj < 2; ++bj) { const int col = 4 * u.pn + 2 * bj + (wc >> 1);
;                 const f32x4 r0 = acc[0][bj][m][0], r1 = acc[0][bj][m][1], i0 = acc[1][bj][m][0], i1 = acc[1][bj][m][1];
;                 const f32x4 or0 = r0 * c0 + i0 * s0, or1 = r1 * c1 + i1 * s1, oi0 = i0 * c0 - r0 * s0, oi1 = i1 * c1 - r1 * s1;
;                 bf16_t* dst = O1T + ((size_t)k1 * 1024 + col) * 128 + s2;
;                 u32x4 w; w.x = cvt_pk_bf16(or0[0], or0[1]); w.y = cvt_pk_bf16(or0[2], or0[3]); w.z = cvt_pk_bf16(or1[0], or1[1]); w.w = cvt_pk_bf16(or1[2], or1[3]);
;                 *(u32x4*)dst = w;
;                 w.x = cvt_pk_bf16(oi0[0], oi0[1]); w.y = cvt_pk_bf16(oi0[2], oi0[3]); w.z = cvt_pk_bf16(oi1[0], oi1[1]); w.w = cvt_pk_bf16(oi1[2], oi1[3]);
;                 *(u32x4*)(dst + 64) = w; }
	v_pk_mul_f32 v[88:89], v[56:57], v[198:199]
	v_pk_mul_f32 v[84:85], v[60:61], v[202:203]
	v_pk_mul_f32 v[82:83], v[62:63], v[204:205]
	v_pk_fma_f32 v[84:85], v[44:45], v[194:195], v[84:85]
	v_pk_mul_f32 v[44:45], v[44:45], v[202:203]
	v_pk_mul_f32 v[86:87], v[58:59], v[200:201]
	v_pk_fma_f32 v[88:89], v[40:41], v[190:191], v[88:89]
	v_pk_fma_f32 v[44:45], v[60:61], v[194:195], v[44:45] neg_lo:[0,0,1] neg_hi:[0,0,1]
	v_pk_mul_f32 v[40:41], v[40:41], v[198:199]
	v_lshl_add_u64 v[60:61], s[16:17], 0, v[76:77]
	v_pk_fma_f32 v[82:83], v[46:47], v[196:197], v[82:83]
	v_pk_fma_f32 v[86:87], v[42:43], v[192:193], v[86:87]
	v_pk_mul_f32 v[46:47], v[46:47], v[204:205]
	v_pk_mul_f32 v[42:43], v[42:43], v[200:201]
	v_pk_fma_f32 v[56:57], v[56:57], v[190:191], v[40:41] neg_lo:[0,0,1] neg_hi:[0,0,1]
	v_lshl_add_u64 v[40:41], v[60:61], 0, s[62:63]
	v_pk_fma_f32 v[46:47], v[62:63], v[196:197], v[46:47] neg_lo:[0,0,1] neg_hi:[0,0,1]
	v_pk_fma_f32 v[58:59], v[58:59], v[192:193], v[42:43] neg_lo:[0,0,1] neg_hi:[0,0,1]
	v_lshl_add_u64 v[62:63], v[40:41], 0, v[124:125]
	v_cvt_pk_bf16_f32 v40, v84, v85
	v_cvt_pk_bf16_f32 v41, v82, v83
	v_cvt_pk_bf16_f32 v42, v88, v89
	v_cvt_pk_bf16_f32 v43, v86, v87
	global_store_dwordx4 v[62:63], v[40:43], off
	s_nop 1
	v_cvt_pk_bf16_f32 v40, v44, v45
	v_cvt_pk_bf16_f32 v41, v46, v47
	v_cvt_pk_bf16_f32 v42, v56, v57
	v_cvt_pk_bf16_f32 v43, v58, v59
	v_pk_mul_f32 v[46:47], v[48:49], v[198:199]
	global_store_dwordx4 v[62:63], v[40:43], off offset:128
	v_pk_fma_f32 v[46:47], v[32:33], v[190:191], v[46:47]
	v_pk_mul_f32 v[32:33], v[32:33], v[198:199]
	v_pk_mul_f32 v[42:43], v[52:53], v[202:203]
	v_pk_mul_f32 v[44:45], v[50:51], v[200:201]
	v_pk_fma_f32 v[42:43], v[36:37], v[194:195], v[42:43]
	v_pk_mul_f32 v[36:37], v[36:37], v[202:203]
	v_pk_fma_f32 v[48:49], v[48:49], v[190:191], v[32:33] neg_lo:[0,0,1] neg_hi:[0,0,1]
	v_lshl_add_u64 v[32:33], v[60:61], 0, s[60:61]
	v_pk_mul_f32 v[40:41], v[54:55], v[204:205]
	v_pk_fma_f32 v[44:45], v[34:35], v[192:193], v[44:45]
	v_pk_fma_f32 v[36:37], v[52:53], v[194:195], v[36:37] neg_lo:[0,0,1] neg_hi:[0,0,1]
	v_pk_mul_f32 v[34:35], v[34:35], v[200:201]
	v_lshl_add_u64 v[52:53], v[32:33], 0, v[124:125]
	v_cvt_pk_bf16_f32 v32, v42, v43
	v_pk_fma_f32 v[40:41], v[38:39], v[196:197], v[40:41]
	v_pk_mul_f32 v[38:39], v[38:39], v[204:205]
	v_pk_fma_f32 v[50:51], v[50:51], v[192:193], v[34:35] neg_lo:[0,0,1] neg_hi:[0,0,1]
	v_cvt_pk_bf16_f32 v33, v40, v41
	v_cvt_pk_bf16_f32 v34, v46, v47
	v_cvt_pk_bf16_f32 v35, v44, v45
	global_store_dwordx4 v[52:53], v[32:35], off
	v_add_u32_e32 v44, 48, v148
	v_pk_fma_f32 v[38:39], v[54:55], v[196:197], v[38:39] neg_lo:[0,0,1] neg_hi:[0,0,1]
	v_cvt_pk_bf16_f32 v32, v36, v37
	v_ashrrev_i32_e32 v45, 31, v44
	v_cvt_pk_bf16_f32 v33, v38, v39
	v_cvt_pk_bf16_f32 v34, v48, v49
	v_cvt_pk_bf16_f32 v35, v50, v51
	global_store_dwordx4 v[52:53], v[32:35], off offset:128
	s_nop 1
	v_lshlrev_b32_e32 v32, 6, v44
	v_ashrrev_i32_e32 v33, 31, v32
	v_lshlrev_b64 v[40:41], 2, v[32:33]
	v_lshl_add_u64 v[32:33], s[20:21], 0, v[40:41]
	v_lshl_add_u64 v[40:41], s[22:23], 0, v[40:41]
	v_lshl_add_u64 v[36:37], v[32:33], 0, v[146:147]
	v_lshl_add_u64 v[46:47], v[40:41], 0, v[146:147]
	v_lshlrev_b64 v[44:45], 18, v[44:45]
	s_waitcnt vmcnt(12)
	v_pk_mul_f32 v[56:57], v[24:25], v[214:215]
	v_pk_mul_f32 v[52:53], v[28:29], v[222:223]
	v_pk_mul_f32 v[50:51], v[30:31], v[224:225]
	v_pk_fma_f32 v[52:53], v[20:21], v[210:211], v[52:53]
	v_pk_mul_f32 v[20:21], v[20:21], v[222:223]
	v_pk_fma_f32 v[56:57], v[16:17], v[206:207], v[56:57]
	v_pk_fma_f32 v[20:21], v[28:29], v[210:211], v[20:21] neg_lo:[0,0,1] neg_hi:[0,0,1]
	v_pk_mul_f32 v[16:17], v[16:17], v[214:215]
	v_lshl_add_u64 v[28:29], s[16:17], 0, v[44:45]
	v_pk_fma_f32 v[50:51], v[22:23], v[212:213], v[50:51]
	v_pk_mul_f32 v[54:55], v[26:27], v[216:217]
	v_pk_mul_f32 v[22:23], v[22:23], v[224:225]
	v_pk_fma_f32 v[24:25], v[24:25], v[206:207], v[16:17] neg_lo:[0,0,1] neg_hi:[0,0,1]
	v_lshl_add_u64 v[16:17], v[28:29], 0, s[62:63]
	v_pk_fma_f32 v[54:55], v[18:19], v[208:209], v[54:55]
	v_pk_fma_f32 v[22:23], v[30:31], v[212:213], v[22:23] neg_lo:[0,0,1] neg_hi:[0,0,1]
	v_pk_mul_f32 v[18:19], v[18:19], v[216:217]
	v_lshl_add_u64 v[30:31], v[16:17], 0, v[124:125]
	v_cvt_pk_bf16_f32 v16, v52, v53
	v_cvt_pk_bf16_f32 v17, v50, v51
	v_pk_fma_f32 v[26:27], v[26:27], v[208:209], v[18:19] neg_lo:[0,0,1] neg_hi:[0,0,1]
	v_cvt_pk_bf16_f32 v18, v56, v57
	v_cvt_pk_bf16_f32 v19, v54, v55
	global_store_dwordx4 v[30:31], v[16:19], off
	s_nop 1
	v_cvt_pk_bf16_f32 v16, v20, v21
	v_cvt_pk_bf16_f32 v17, v22, v23
	v_cvt_pk_bf16_f32 v18, v24, v25
	v_cvt_pk_bf16_f32 v19, v26, v27
	global_store_dwordx4 v[30:31], v[16:19], off offset:128
	v_pk_mul_f32 v[20:21], v[12:13], v[222:223]
	v_pk_mul_f32 v[24:25], v[4:5], v[222:223]
	v_pk_mul_f32 v[16:17], v[14:15], v[224:225]
	v_pk_fma_f32 v[22:23], v[4:5], v[210:211], v[20:21]
	v_pk_fma_f32 v[18:19], v[6:7], v[212:213], v[16:17]
	v_pk_mul_f32 v[16:17], v[10:11], v[216:217]
	v_pk_mul_f32 v[6:7], v[6:7], v[224:225]
	v_pk_mul_f32 v[20:21], v[8:9], v[214:215]
	v_pk_fma_f32 v[16:17], v[2:3], v[208:209], v[16:17]
	v_pk_fma_f32 v[4:5], v[14:15], v[212:213], v[6:7] neg_lo:[0,0,1] neg_hi:[0,0,1]
	v_pk_fma_f32 v[6:7], v[12:13], v[210:211], v[24:25] neg_lo:[0,0,1] neg_hi:[0,0,1]
	v_pk_mul_f32 v[2:3], v[2:3], v[216:217]
	v_pk_mul_f32 v[12:13], v[0:1], v[214:215]
	v_pk_fma_f32 v[20:21], v[0:1], v[206:207], v[20:21]
	v_pk_fma_f32 v[0:1], v[10:11], v[208:209], v[2:3] neg_lo:[0,0,1] neg_hi:[0,0,1]
	v_pk_fma_f32 v[2:3], v[8:9], v[206:207], v[12:13] neg_lo:[0,0,1] neg_hi:[0,0,1]
	v_lshl_add_u64 v[8:9], v[28:29], 0, s[60:61]
	v_lshl_add_u64 v[12:13], v[8:9], 0, v[124:125]
	v_cvt_pk_bf16_f32 v8, v22, v23
	v_cvt_pk_bf16_f32 v9, v18, v19
	v_cvt_pk_bf16_f32 v10, v20, v21
	v_cvt_pk_bf16_f32 v11, v16, v17
	global_store_dwordx4 v[12:13], v[8:11], off
	v_cvt_pk_bf16_f32 v6, v6, v7
	v_cvt_pk_bf16_f32 v7, v4, v5
	s_nop 1
	v_cvt_pk_bf16_f32 v8, v2, v3
	v_cvt_pk_bf16_f32 v9, v0, v1
	global_store_dwordx4 v[12:13], v[6:9], off offset:128
	s_cbranch_vccnz .LBB0_482
	s_andn2_b64 vcc, exec, s[14:15]
	s_cbranch_vccnz .LBB0_481
	s_barrier
	s_branch .LBB0_481

; #define PG8_STAGE(bufoff, gbase, voff) do { _Pragma("unroll") for (int _i = 0; _i < 2; ++_i) \
;         __builtin_amdgcn_global_load_lds((const unsigned*)((const char*)(gbase) + (voff)[_i]), (PG8_LAS unsigned*)(lds + (bufoff) + ldsw + _i * 8192), 16, 0, 0); } while (0)
; #define PG8_LDA(dst, b, h) do { _Pragma("unroll") for (int m = 0; m < 4; ++m) _Pragma("unroll") for (int k = 0; k < 2; ++k) dst[m][k] = *(const PG8_LAS bf16x8*)(lds + PG8_SA(b, h) + aoff + m * 2048 + k * 1024); } while (0)
; #define PG8_LDB(dst, b, h) do { _Pragma("unroll") for (int n = 0; n < 2; ++n) _Pragma("unroll") for (int k = 0; k < 2; ++k) dst[n][k] = *(const PG8_LAS bf16x8*)(lds + PG8_SB(b, h) + boff + n * 2048 + k * 1024); } while (0)
; #define PG8_MMA(ai, bj, At, Bt) do { __builtin_amdgcn_s_setprio(1); _Pragma("unroll") for (int m = 0; m < 4; ++m) _Pragma("unroll") for (int n = 0; n < 2; ++n) _Pragma("unroll") for (int k = 0; k < 2; ++k) \
;         acc[ai][bj][m][n] = __builtin_amdgcn_mfma_f32_16x16x32_bf16(Bt[n][k], At[m][k], acc[ai][bj][m][n], 0, 0, 0); __builtin_amdgcn_s_setprio(0); } while (0)
; #define PG8_WAIT_V(n) asm volatile("s_waitcnt vmcnt(" #n ")" ::: "memory")
; #define PG8_WAIT_L(n) asm volatile("s_waitcnt lgkmcnt(" #n ")" ::: "memory")
; #define PG8_WAIT_VK do { if constexpr (HALFM) PG8_WAIT_V(6); else PG8_WAIT_V(8); } while (0)
; template <class Epi, class Sched, bool ALIGN_EPI = false, bool SP2 = false, bool HALFM = false, bool AMAP = false>
; __device__ __forceinline__ void gemm_phase(PG8_LAS unsigned char* lds, const Gemm g, const Sched& S, const Epi& E, int tid_in) {
;     ...
;         PG8_STAGE(PG8_SB(1, 0), cB + kstep, voffB); PG8_STAGE(PG8_SA(1, 0), cA + kstep, voffA); PG8_STAGE(PG8_SB(1, 1), cB + hstepB + kstep, voffB);
;         PG8_WAIT_V(6); PG8_BAR;
;     ...
;             PG8_LDB(B0, 0, 0); PG8_LDB(B1, 0, 1); PG8_SCHED; PG8_LDA(At, 0, 0); if constexpr (!HALFM) PG8_STAGE(PG8_SA(1, 1), a1 + hstepA, voffA);
;             PG8_WAIT_VK; PG8_WAIT_L(0); PG8_BAR; PG8_MMA(0, 0, At, B0); PG8_MMA(0, 1, At, B1); PG8_BAR; PG8_SCHED;
;             if constexpr (!HALFM) { PG8_LDA(At, 0, 1); } PG8_STAGE(PG8_SB(0, 0), b2, voffB); PG8_STAGE(PG8_SB(0, 1), b2 + hstepB, voffB); PG8_STAGE(PG8_SA(0, 0), a2, voffA);
;             PG8_WAIT_VK; PG8_WAIT_L(0); PG8_BAR; if constexpr (!HALFM) { PG8_MMA(1, 0, At, B0); PG8_MMA(1, 1, At, B1); } PG8_BAR; PG8_SCHED;
.LBB0_558:
	s_add_i32 s23, 0, 0x18000
	s_add_i32 s14, s23, s21
	v_lshl_add_u64 v[164:165], v[8:9], 0, s[66:67]
	s_mov_b32 m0, s14
	s_add_i32 s16, s14, 0x2000
	s_waitcnt vmcnt(2)
	s_barrier
	global_load_lds_dwordx4 v[164:165], off
	v_lshl_add_u64 v[166:167], v[10:11], 0, s[66:67]
	s_mov_b32 m0, s16
	s_add_i32 s15, s18, 0x8000
	global_load_lds_dwordx4 v[166:167], off
	v_lshl_add_u64 v[168:169], v[16:17], 0, s[66:67]
	s_mov_b32 m0, s15
	s_add_i32 s17, s18, 0xa000
	s_add_i32 s25, 0, 0x1c000
	global_load_lds_dwordx4 v[168:169], off
	v_lshl_add_u64 v[170:171], v[18:19], 0, s[66:67]
	s_mov_b32 m0, s17
	v_lshl_add_u64 v[24:25], v[24:25], 0, s[84:85]
	s_add_i32 s28, s25, s21
	global_load_lds_dwordx4 v[170:171], off
	v_lshl_add_u64 v[172:173], v[24:25], 0, v[176:177]
	s_mov_b32 m0, s28
	s_add_i32 s29, s28, 0x2000
	global_load_lds_dwordx4 v[172:173], off
	v_lshl_add_u64 v[174:175], v[24:25], 0, v[20:21]
	s_mov_b32 m0, s29
	v_and_b32_e32 v65, 15, v64
	global_load_lds_dwordx4 v[174:175], off
	v_and_b32_e32 v66, 48, v64
	v_lshlrev_b32_e32 v21, 2, v64
	s_and_b32 s13, s10, 3
	v_lshl_or_b32 v20, v65, 6, v66
	s_lshl_b32 s30, s5, 13
	v_and_b32_e32 v21, 32, v21
	v_bitop3_b32 v24, v20, s30, v21 bitop3:0xde
	s_lshl_b32 s30, s13, 12
	v_bitop3_b32 v20, v20, s30, v21 bitop3:0xde
	s_add_i32 s30, 0, 0x10000
	s_add_i32 s31, 0, 0x14000
	v_add_u32_e32 v32, s30, v20
	v_add_u32_e32 v48, s31, v20
	s_waitcnt vmcnt(6)
	s_barrier
	v_add_u32_e32 v67, 0, v24
	v_add_u32_e32 v120, s23, v20
	v_add_u32_e32 v128, s25, v20
	v_lshl_add_u64 v[88:89], v[22:23], 0, s[84:85]
	ds_read_b128 v[20:23], v32
	ds_read_b128 v[24:27], v32 offset:1024
	ds_read_b128 v[28:31], v32 offset:2048
	ds_read_b128 v[32:35], v32 offset:3072
	ds_read_b128 v[36:39], v48
	ds_read_b128 v[40:43], v48 offset:1024
	ds_read_b128 v[44:47], v48 offset:2048
	ds_read_b128 v[48:51], v48 offset:3072
	s_add_i32 s25, s30, s21
	s_add_i32 s21, s31, s21
	s_add_i32 m0, s18, 0xc000
	s_add_i32 s23, s18, 0xe000
	s_add_i32 s30, s25, 0x2000
	s_add_i32 s31, s21, 0x2000
	s_cmpk_gt_u32 s11, 0xff
	v_lshl_add_u64 v[0:1], v[88:89], 0, v[0:1]
	ds_read_b128 v[52:55], v67
	ds_read_b128 v[56:59], v67 offset:1024
	ds_read_b128 v[60:63], v67 offset:2048
	ds_read_b128 v[68:71], v67 offset:3072
	ds_read_b128 v[72:75], v67 offset:4096
	ds_read_b128 v[76:79], v67 offset:5120
	ds_read_b128 v[80:83], v67 offset:6144
	ds_read_b128 v[84:87], v67 offset:7168
	global_load_lds_dwordx4 v[0:1], off
	v_lshl_add_u64 v[0:1], v[88:89], 0, v[2:3]
	s_mov_b32 m0, s23
	s_nop 0
	global_load_lds_dwordx4 v[0:1], off
	s_waitcnt vmcnt(8)
	s_waitcnt lgkmcnt(0)
	s_barrier
	s_setprio 1
	v_mfma_f32_16x16x32_bf16 v[0:3], v[20:23], v[52:55], 0
	v_mfma_f32_16x16x32_bf16 v[92:95], v[20:23], v[60:63], 0
	v_mfma_f32_16x16x32_bf16 v[100:103], v[20:23], v[72:75], 0
	v_mfma_f32_16x16x32_bf16 v[20:23], v[20:23], v[80:83], 0
	v_mfma_f32_16x16x32_bf16 v[0:3], v[24:27], v[56:59], v[0:3]
	v_mfma_f32_16x16x32_bf16 v[92:95], v[24:27], v[68:71], v[92:95]
	v_mfma_f32_16x16x32_bf16 v[100:103], v[24:27], v[76:79], v[100:103]
	v_mfma_f32_16x16x32_bf16 v[20:23], v[24:27], v[84:87], v[20:23]
	v_mfma_f32_16x16x32_bf16 v[24:27], v[28:31], v[80:83], 0
	v_mfma_f32_16x16x32_bf16 v[88:91], v[28:31], v[52:55], 0
	v_mfma_f32_16x16x32_bf16 v[96:99], v[28:31], v[60:63], 0
	v_mfma_f32_16x16x32_bf16 v[104:107], v[28:31], v[72:75], 0
	v_mfma_f32_16x16x32_bf16 v[28:31], v[32:35], v[84:87], v[24:27]
	v_mfma_f32_16x16x32_bf16 v[88:91], v[32:35], v[56:59], v[88:91]
	v_mfma_f32_16x16x32_bf16 v[96:99], v[32:35], v[68:71], v[96:99]
	v_mfma_f32_16x16x32_bf16 v[104:107], v[32:35], v[76:79], v[104:107]
	s_setprio 0
	s_setprio 1
	v_mfma_f32_16x16x32_bf16 v[24:27], v[36:39], v[52:55], 0
	v_mfma_f32_16x16x32_bf16 v[108:111], v[40:43], v[56:59], v[24:27]
	v_mfma_f32_16x16x32_bf16 v[24:27], v[44:47], v[52:55], 0
	v_mfma_f32_16x16x32_bf16 v[52:55], v[48:51], v[56:59], v[24:27]
	v_mfma_f32_16x16x32_bf16 v[24:27], v[36:39], v[60:63], 0
	v_mfma_f32_16x16x32_bf16 v[112:115], v[40:43], v[68:71], v[24:27]
	v_mfma_f32_16x16x32_bf16 v[24:27], v[44:47], v[60:63], 0
	v_mfma_f32_16x16x32_bf16 v[68:71], v[48:51], v[68:71], v[24:27]
	v_mfma_f32_16x16x32_bf16 v[24:27], v[36:39], v[72:75], 0
	v_mfma_f32_16x16x32_bf16 v[116:119], v[40:43], v[76:79], v[24:27]
	v_mfma_f32_16x16x32_bf16 v[24:27], v[44:47], v[72:75], 0
	v_mfma_f32_16x16x32_bf16 v[72:75], v[48:51], v[76:79], v[24:27]
	v_mfma_f32_16x16x32_bf16 v[24:27], v[36:39], v[80:83], 0
	v_mfma_f32_16x16x32_bf16 v[76:79], v[40:43], v[84:87], v[24:27]
	v_mfma_f32_16x16x32_bf16 v[24:27], v[44:47], v[80:83], 0
	v_mfma_f32_16x16x32_bf16 v[80:83], v[48:51], v[84:87], v[24:27]
	s_setprio 0
	s_barrier
; #define PG8_STAGE(bufoff, gbase, voff) do { _Pragma("unroll") for (int _i = 0; _i < 2; ++_i) \
;         __builtin_amdgcn_global_load_lds((const unsigned*)((const char*)(gbase) + (voff)[_i]), (PG8_LAS unsigned*)(lds + (bufoff) + ldsw + _i * 8192), 16, 0, 0); } while (0)
; #define PG8_LDA(dst, b, h) do { _Pragma("unroll") for (int m = 0; m < 4; ++m) _Pragma("unroll") for (int k = 0; k < 2; ++k) dst[m][k] = *(const PG8_LAS bf16x8*)(lds + PG8_SA(b, h) + aoff + m * 2048 + k * 1024); } while (0)
; #define PG8_LDB(dst, b, h) do { _Pragma("unroll") for (int n = 0; n < 2; ++n) _Pragma("unroll") for (int k = 0; k < 2; ++k) dst[n][k] = *(const PG8_LAS bf16x8*)(lds + PG8_SB(b, h) + boff + n * 2048 + k * 1024); } while (0)
; #define PG8_MMA(ai, bj, At, Bt) do { __builtin_amdgcn_s_setprio(1); _Pragma("unroll") for (int m = 0; m < 4; ++m) _Pragma("unroll") for (int n = 0; n < 2; ++n) _Pragma("unroll") for (int k = 0; k < 2; ++k) \
;         acc[ai][bj][m][n] = __builtin_amdgcn_mfma_f32_16x16x32_bf16(Bt[n][k], At[m][k], acc[ai][bj][m][n], 0, 0, 0); __builtin_amdgcn_s_setprio(0); } while (0)
; template <class Epi, class Sched, bool ALIGN_EPI = false, bool SP2 = false, bool HALFM = false, bool AMAP = false>
; __device__ __forceinline__ void gemm_phase(PG8_LAS unsigned char* lds, const Gemm g, const Sched& S, const Epi& E, int tid_in) {
;     ...
;             PG8_WAIT_VK; PG8_WAIT_L(0); PG8_BAR; PG8_MMA(0, 0, At, B0); PG8_MMA(0, 1, At, B1); PG8_BAR; PG8_SCHED;
;             if constexpr (!HALFM) { PG8_LDA(At, 0, 1); } PG8_STAGE(PG8_SB(0, 0), b2, voffB); PG8_STAGE(PG8_SB(0, 1), b2 + hstepB, voffB); PG8_STAGE(PG8_SA(0, 0), a2, voffA);
;             PG8_WAIT_VK; PG8_WAIT_L(0); PG8_BAR; if constexpr (!HALFM) { PG8_MMA(1, 0, At, B0); PG8_MMA(1, 1, At, B1); } PG8_BAR; PG8_SCHED;
;             PG8_LDB(B0, 1, 0); PG8_LDB(B1, 1, 1); PG8_SCHED; PG8_LDA(At, 1, 0); if constexpr (!HALFM) PG8_STAGE(PG8_SA(0, 1), a2 + hstepA, voffA);
;             PG8_WAIT_VK; PG8_WAIT_L(0); PG8_BAR; PG8_MMA(0, 0, At, B0); PG8_MMA(0, 1, At, B1); PG8_BAR; PG8_SCHED;
;             if constexpr (!HALFM) { PG8_LDA(At, 1, 1); } PG8_STAGE(PG8_SB(1, 0), b3, voffB); PG8_STAGE(PG8_SB(1, 1), b3 + hstepB, voffB); PG8_STAGE(PG8_SA(1, 0), a3, voffA);
;             PG8_WAIT_VK; PG8_WAIT_L(0); PG8_BAR; if constexpr (!HALFM) { PG8_MMA(1, 0, At, B0); PG8_MMA(1, 1, At, B1); } PG8_BAR; PG8_SCHED;
	s_mov_b32 m0, s25
	s_nop 0
	global_load_lds_dwordx4 v[8:9], off
	s_mov_b32 m0, s30
	s_nop 0
	global_load_lds_dwordx4 v[10:11], off
	s_mov_b32 m0, s21
	s_nop 0
	global_load_lds_dwordx4 v[12:13], off
	s_mov_b32 m0, s31
	s_nop 0
	global_load_lds_dwordx4 v[14:15], off
	s_mov_b32 m0, s18
	s_nop 0
	global_load_lds_dwordx4 v[16:17], off
	s_mov_b32 m0, s22
	s_nop 0
	global_load_lds_dwordx4 v[18:19], off
	s_waitcnt vmcnt(8)
	s_waitcnt lgkmcnt(0)
	s_barrier
	s_setprio 1
	s_setprio 0
	s_setprio 1
	s_setprio 0
	s_barrier
	ds_read_b128 v[8:11], v120
	ds_read_b128 v[12:15], v120 offset:1024
	ds_read_b128 v[36:39], v120 offset:2048
	ds_read_b128 v[44:47], v120 offset:3072
	ds_read_b128 v[84:87], v128
	ds_read_b128 v[120:123], v128 offset:1024
	ds_read_b128 v[124:127], v128 offset:2048
	ds_read_b128 v[128:131], v128 offset:3072
	s_mov_b32 m0, s19
	ds_read_b128 v[132:135], v67 offset:32768
	ds_read_b128 v[136:139], v67 offset:33792
	ds_read_b128 v[140:143], v67 offset:34816
	ds_read_b128 v[144:147], v67 offset:35840
	ds_read_b128 v[148:151], v67 offset:36864
	ds_read_b128 v[152:155], v67 offset:37888
	ds_read_b128 v[156:159], v67 offset:38912
	ds_read_b128 v[160:163], v67 offset:39936
	global_load_lds_dwordx4 v[4:5], off
	s_mov_b32 m0, s20
	s_nop 0
	global_load_lds_dwordx4 v[6:7], off
	s_waitcnt vmcnt(8)
	s_waitcnt lgkmcnt(0)
	s_barrier
	s_setprio 1
	v_mfma_f32_16x16x32_bf16 v[0:3], v[8:11], v[132:135], v[0:3]
	v_mfma_f32_16x16x32_bf16 v[56:59], v[12:15], v[136:139], v[0:3]
	v_mfma_f32_16x16x32_bf16 v[0:3], v[36:39], v[132:135], v[88:91]
	v_mfma_f32_16x16x32_bf16 v[48:51], v[44:47], v[136:139], v[0:3]
	v_mfma_f32_16x16x32_bf16 v[0:3], v[8:11], v[140:143], v[92:95]
	v_mfma_f32_16x16x32_bf16 v[40:43], v[12:15], v[144:147], v[0:3]
	v_mfma_f32_16x16x32_bf16 v[0:3], v[36:39], v[140:143], v[96:99]
	v_mfma_f32_16x16x32_bf16 v[32:35], v[44:47], v[144:147], v[0:3]
	v_mfma_f32_16x16x32_bf16 v[0:3], v[8:11], v[148:151], v[100:103]
	v_mfma_f32_16x16x32_bf16 v[24:27], v[12:15], v[152:155], v[0:3]
	v_mfma_f32_16x16x32_bf16 v[0:3], v[36:39], v[148:151], v[104:107]
	v_mfma_f32_16x16x32_bf16 v[16:19], v[44:47], v[152:155], v[0:3]
	v_mfma_f32_16x16x32_bf16 v[0:3], v[8:11], v[156:159], v[20:23]
	v_mfma_f32_16x16x32_bf16 v[8:11], v[12:15], v[160:163], v[0:3]
	v_mfma_f32_16x16x32_bf16 v[0:3], v[36:39], v[156:159], v[28:31]
	v_mfma_f32_16x16x32_bf16 v[0:3], v[44:47], v[160:163], v[0:3]
	s_setprio 0
	s_setprio 1
	v_mfma_f32_16x16x32_bf16 v[4:7], v[84:87], v[132:135], v[108:111]
	v_mfma_f32_16x16x32_bf16 v[60:63], v[120:123], v[136:139], v[4:7]
	v_mfma_f32_16x16x32_bf16 v[4:7], v[124:127], v[132:135], v[52:55]
	v_mfma_f32_16x16x32_bf16 v[52:55], v[128:131], v[136:139], v[4:7]
	v_mfma_f32_16x16x32_bf16 v[4:7], v[84:87], v[140:143], v[112:115]
	v_mfma_f32_16x16x32_bf16 v[44:47], v[120:123], v[144:147], v[4:7]
	v_mfma_f32_16x16x32_bf16 v[4:7], v[124:127], v[140:143], v[68:71]
	v_mfma_f32_16x16x32_bf16 v[36:39], v[128:131], v[144:147], v[4:7]
	v_mfma_f32_16x16x32_bf16 v[4:7], v[84:87], v[148:151], v[116:119]
	v_mfma_f32_16x16x32_bf16 v[28:31], v[120:123], v[152:155], v[4:7]
	v_mfma_f32_16x16x32_bf16 v[4:7], v[124:127], v[148:151], v[72:75]
	v_mfma_f32_16x16x32_bf16 v[20:23], v[128:131], v[152:155], v[4:7]
	v_mfma_f32_16x16x32_bf16 v[4:7], v[84:87], v[156:159], v[76:79]
	v_mfma_f32_16x16x32_bf16 v[12:15], v[120:123], v[160:163], v[4:7]
	v_mfma_f32_16x16x32_bf16 v[4:7], v[124:127], v[156:159], v[80:83]
	v_mfma_f32_16x16x32_bf16 v[4:7], v[128:131], v[160:163], v[4:7]
	s_setprio 0
	s_barrier
	s_mov_b32 m0, s14
	s_nop 0
	global_load_lds_dwordx4 v[164:165], off
	s_mov_b32 m0, s16
	s_nop 0
	global_load_lds_dwordx4 v[166:167], off
	s_mov_b32 m0, s28
	s_nop 0
	global_load_lds_dwordx4 v[172:173], off
	s_mov_b32 m0, s29
	s_nop 0
	global_load_lds_dwordx4 v[174:175], off
	s_mov_b32 m0, s15
	s_nop 0
	global_load_lds_dwordx4 v[168:169], off
	s_mov_b32 m0, s17
	s_nop 0
	global_load_lds_dwordx4 v[170:171], off
	s_waitcnt vmcnt(8)
	s_waitcnt lgkmcnt(0)
	s_barrier
	s_setprio 1
	s_setprio 0
	s_setprio 1
	s_setprio 0
	s_barrier
	s_cbranch_scc1 .LBB0_549
	s_barrier
	s_branch .LBB0_549

; #define PG8_STAGE(bufoff, gbase, voff) do { _Pragma("unroll") for (int _i = 0; _i < 2; ++_i) \
;         __builtin_amdgcn_global_load_lds((const unsigned*)((const char*)(gbase) + (voff)[_i]), (PG8_LAS unsigned*)(lds + (bufoff) + ldsw + _i * 8192), 16, 0, 0); } while (0)
; #define PG8_LDA(dst, b, h) do { _Pragma("unroll") for (int m = 0; m < 4; ++m) _Pragma("unroll") for (int k = 0; k < 2; ++k) dst[m][k] = *(const PG8_LAS bf16x8*)(lds + PG8_SA(b, h) + aoff + m * 2048 + k * 1024); } while (0)
; #define PG8_LDB(dst, b, h) do { _Pragma("unroll") for (int n = 0; n < 2; ++n) _Pragma("unroll") for (int k = 0; k < 2; ++k) dst[n][k] = *(const PG8_LAS bf16x8*)(lds + PG8_SB(b, h) + boff + n * 2048 + k * 1024); } while (0)
; #define PG8_MMA(ai, bj, At, Bt) do { __builtin_amdgcn_s_setprio(1); _Pragma("unroll") for (int m = 0; m < 4; ++m) _Pragma("unroll") for (int n = 0; n < 2; ++n) _Pragma("unroll") for (int k = 0; k < 2; ++k) \
;         acc[ai][bj][m][n] = __builtin_amdgcn_mfma_f32_16x16x32_bf16(Bt[n][k], At[m][k], acc[ai][bj][m][n], 0, 0, 0); __builtin_amdgcn_s_setprio(0); } while (0)
; #define PG8_WAIT_L(n) asm volatile("s_waitcnt lgkmcnt(" #n ")" ::: "memory")
; #define PG8_WAIT_VK do { if constexpr (HALFM) PG8_WAIT_V(6); else PG8_WAIT_V(8); } while (0)
; #define PG8_BAR __builtin_amdgcn_s_barrier()
; #define PG8_SCHED __builtin_amdgcn_sched_barrier(0)
; template <class Epi, class Sched, bool ALIGN_EPI = false, bool SP2 = false, bool HALFM = false, bool AMAP = false>
; __device__ __forceinline__ void gemm_phase(PG8_LAS unsigned char* lds, const Gemm g, const Sched& S, const Epi& E, int tid_in) {
;     ...
;             PG8_LDB(B0, 0, 0); PG8_LDB(B1, 0, 1); PG8_SCHED; PG8_LDA(At, 0, 0); if constexpr (!HALFM) PG8_STAGE(PG8_SA(1, 1), a1 + hstepA, voffA);
;             PG8_WAIT_VK; PG8_WAIT_L(0); PG8_BAR; PG8_MMA(0, 0, At, B0); PG8_MMA(0, 1, At, B1); PG8_BAR; PG8_SCHED;
;             if constexpr (!HALFM) { PG8_LDA(At, 0, 1); } PG8_STAGE(PG8_SB(0, 0), b2, voffB); PG8_STAGE(PG8_SB(0, 1), b2 + hstepB, voffB); PG8_STAGE(PG8_SA(0, 0), a2, voffA);
;             PG8_WAIT_VK; PG8_WAIT_L(0); PG8_BAR; if constexpr (!HALFM) { PG8_MMA(1, 0, At, B0); PG8_MMA(1, 1, At, B1); } PG8_BAR; PG8_SCHED;
.LBB0_650:
	s_add_u32 s30, s28, 0xfff80080
	s_addc_u32 s31, s29, -1
	s_add_i32 s76, 0, 0x10000
	s_cmp_eq_u32 s80, 28
	s_cselect_b32 s49, s36, s31
	s_cselect_b32 s48, s37, s30
	s_cselect_b32 s31, s41, s63
	s_cselect_b32 s30, s43, s62
	s_add_i32 s81, 0, 0x14000
	v_add_u32_e32 v140, s76, v189
	v_add_u32_e32 v166, s81, v189
	ds_read_b128 v[128:131], v140
	ds_read_b128 v[132:135], v140 offset:1024
	ds_read_b128 v[136:139], v140 offset:2048
	ds_read_b128 v[140:143], v140 offset:3072
	ds_read_b128 v[144:147], v166
	ds_read_b128 v[148:151], v166 offset:1024
	ds_read_b128 v[162:165], v166 offset:2048
	ds_read_b128 v[166:169], v166 offset:3072
	v_lshl_add_u64 v[174:175], s[28:29], 0, v[160:161]
	s_add_i32 m0, s11, 0xc000
	ds_read_b128 v[170:173], v191
	ds_read_b128 v[184:187], v191 offset:1024
	ds_read_b128 v[192:195], v191 offset:2048
	ds_read_b128 v[196:199], v191 offset:3072
	ds_read_b128 v[200:203], v191 offset:4096
	ds_read_b128 v[204:207], v191 offset:5120
	ds_read_b128 v[208:211], v191 offset:6144
	ds_read_b128 v[212:215], v191 offset:7168
	global_load_lds_dwordx4 v[174:175], off
	v_lshl_add_u64 v[174:175], s[28:29], 0, v[158:159]
	s_add_i32 m0, s11, 0xe000
	s_nop 0
	global_load_lds_dwordx4 v[174:175], off
	s_waitcnt vmcnt(8)
	s_waitcnt lgkmcnt(0)
	s_barrier
	s_setprio 1
	v_mfma_f32_16x16x32_bf16 v[124:127], v[128:131], v[170:173], v[124:127]
	v_mfma_f32_16x16x32_bf16 v[120:123], v[136:139], v[170:173], v[120:123]
	v_mfma_f32_16x16x32_bf16 v[108:111], v[128:131], v[192:195], v[108:111]
	v_mfma_f32_16x16x32_bf16 v[104:107], v[136:139], v[192:195], v[104:107]
	v_mfma_f32_16x16x32_bf16 v[92:95], v[128:131], v[200:203], v[92:95]
	v_mfma_f32_16x16x32_bf16 v[88:91], v[136:139], v[200:203], v[88:91]
	v_mfma_f32_16x16x32_bf16 v[76:79], v[128:131], v[208:211], v[76:79]
	v_mfma_f32_16x16x32_bf16 v[72:75], v[136:139], v[208:211], v[72:75]
	v_mfma_f32_16x16x32_bf16 v[124:127], v[132:135], v[184:187], v[124:127]
	v_mfma_f32_16x16x32_bf16 v[120:123], v[140:143], v[184:187], v[120:123]
	v_mfma_f32_16x16x32_bf16 v[108:111], v[132:135], v[196:199], v[108:111]
	v_mfma_f32_16x16x32_bf16 v[104:107], v[140:143], v[196:199], v[104:107]
	v_mfma_f32_16x16x32_bf16 v[92:95], v[132:135], v[204:207], v[92:95]
	v_mfma_f32_16x16x32_bf16 v[88:91], v[140:143], v[204:207], v[88:91]
	v_mfma_f32_16x16x32_bf16 v[76:79], v[132:135], v[212:215], v[76:79]
	v_mfma_f32_16x16x32_bf16 v[72:75], v[140:143], v[212:215], v[72:75]
	s_setprio 0
	s_setprio 1
	v_mfma_f32_16x16x32_bf16 v[116:119], v[144:147], v[170:173], v[116:119]
	v_mfma_f32_16x16x32_bf16 v[112:115], v[162:165], v[170:173], v[112:115]
	v_mfma_f32_16x16x32_bf16 v[100:103], v[144:147], v[192:195], v[100:103]
	v_mfma_f32_16x16x32_bf16 v[96:99], v[162:165], v[192:195], v[96:99]
	v_mfma_f32_16x16x32_bf16 v[84:87], v[144:147], v[200:203], v[84:87]
	v_mfma_f32_16x16x32_bf16 v[80:83], v[162:165], v[200:203], v[80:83]
	v_mfma_f32_16x16x32_bf16 v[68:71], v[144:147], v[208:211], v[68:71]
	v_mfma_f32_16x16x32_bf16 v[64:67], v[162:165], v[208:211], v[64:67]
	v_mfma_f32_16x16x32_bf16 v[116:119], v[148:151], v[184:187], v[116:119]
	v_mfma_f32_16x16x32_bf16 v[112:115], v[166:169], v[184:187], v[112:115]
	v_mfma_f32_16x16x32_bf16 v[100:103], v[148:151], v[196:199], v[100:103]
	v_mfma_f32_16x16x32_bf16 v[96:99], v[166:169], v[196:199], v[96:99]
	v_mfma_f32_16x16x32_bf16 v[84:87], v[148:151], v[204:207], v[84:87]
	v_mfma_f32_16x16x32_bf16 v[80:83], v[166:169], v[204:207], v[80:83]
	v_mfma_f32_16x16x32_bf16 v[68:71], v[148:151], v[212:215], v[68:71]
	v_mfma_f32_16x16x32_bf16 v[64:67], v[166:169], v[212:215], v[64:67]
	s_setprio 0
	s_barrier
	s_add_i32 s76, s76, s10
	v_lshl_add_u64 v[174:175], s[30:31], 0, v[176:177]
	s_mov_b32 m0, s76
	ds_read_b128 v[170:173], v191 offset:16384
	ds_read_b128 v[184:187], v191 offset:17408
	ds_read_b128 v[192:195], v191 offset:18432
	ds_read_b128 v[196:199], v191 offset:19456
	ds_read_b128 v[200:203], v191 offset:20480
	ds_read_b128 v[204:207], v191 offset:21504
	ds_read_b128 v[208:211], v191 offset:22528
	ds_read_b128 v[212:215], v191 offset:23552
	global_load_lds_dwordx4 v[174:175], off
	s_add_i32 m0, s76, 0x2000
	s_add_u32 s76, s30, 0x80000
	v_lshl_add_u64 v[178:179], s[30:31], 0, v[152:153]
	s_addc_u32 s77, s31, 0
	s_add_i32 s81, s81, s10
	global_load_lds_dwordx4 v[178:179], off
	v_lshl_add_u64 v[180:181], s[76:77], 0, v[176:177]
	s_mov_b32 m0, s81
	v_lshl_add_u64 v[182:183], s[48:49], 0, v[154:155]
	global_load_lds_dwordx4 v[180:181], off
	v_lshl_add_u64 v[180:181], s[76:77], 0, v[152:153]
	s_add_i32 m0, s81, 0x2000
	s_nop 0
	global_load_lds_dwordx4 v[180:181], off
	v_lshl_add_u64 v[180:181], s[48:49], 0, v[156:157]
	s_mov_b32 m0, s11
	s_nop 0
	global_load_lds_dwordx4 v[180:181], off
	s_mov_b32 m0, s18
	s_nop 0
	global_load_lds_dwordx4 v[182:183], off
	s_waitcnt vmcnt(8)
	s_waitcnt lgkmcnt(0)
	s_barrier
; #define PG8_STAGE(bufoff, gbase, voff) do { _Pragma("unroll") for (int _i = 0; _i < 2; ++_i) \
;         __builtin_amdgcn_global_load_lds((const unsigned*)((const char*)(gbase) + (voff)[_i]), (PG8_LAS unsigned*)(lds + (bufoff) + ldsw + _i * 8192), 16, 0, 0); } while (0)
; #define PG8_LDA(dst, b, h) do { _Pragma("unroll") for (int m = 0; m < 4; ++m) _Pragma("unroll") for (int k = 0; k < 2; ++k) dst[m][k] = *(const PG8_LAS bf16x8*)(lds + PG8_SA(b, h) + aoff + m * 2048 + k * 1024); } while (0)
; #define PG8_LDB(dst, b, h) do { _Pragma("unroll") for (int n = 0; n < 2; ++n) _Pragma("unroll") for (int k = 0; k < 2; ++k) dst[n][k] = *(const PG8_LAS bf16x8*)(lds + PG8_SB(b, h) + boff + n * 2048 + k * 1024); } while (0)
; #define PG8_MMA(ai, bj, At, Bt) do { __builtin_amdgcn_s_setprio(1); _Pragma("unroll") for (int m = 0; m < 4; ++m) _Pragma("unroll") for (int n = 0; n < 2; ++n) _Pragma("unroll") for (int k = 0; k < 2; ++k) \
;         acc[ai][bj][m][n] = __builtin_amdgcn_mfma_f32_16x16x32_bf16(Bt[n][k], At[m][k], acc[ai][bj][m][n], 0, 0, 0); __builtin_amdgcn_s_setprio(0); } while (0)
; #define PG8_WAIT_L(n) asm volatile("s_waitcnt lgkmcnt(" #n ")" ::: "memory")
; #define PG8_WAIT_VK do { if constexpr (HALFM) PG8_WAIT_V(6); else PG8_WAIT_V(8); } while (0)
; #define PG8_BAR __builtin_amdgcn_s_barrier()
; #define PG8_SCHED __builtin_amdgcn_sched_barrier(0)
; template <class Epi, class Sched, bool ALIGN_EPI = false, bool SP2 = false, bool HALFM = false, bool AMAP = false>
; __device__ __forceinline__ void gemm_phase(PG8_LAS unsigned char* lds, const Gemm g, const Sched& S, const Epi& E, int tid_in) {
;     ...
;             PG8_WAIT_VK; PG8_WAIT_L(0); PG8_BAR; if constexpr (!HALFM) { PG8_MMA(1, 0, At, B0); PG8_MMA(1, 1, At, B1); } PG8_BAR; PG8_SCHED;
;             PG8_LDB(B0, 1, 0); PG8_LDB(B1, 1, 1); PG8_SCHED; PG8_LDA(At, 1, 0); if constexpr (!HALFM) PG8_STAGE(PG8_SA(0, 1), a2 + hstepA, voffA);
;             PG8_WAIT_VK; PG8_WAIT_L(0); PG8_BAR; PG8_MMA(0, 0, At, B0); PG8_MMA(0, 1, At, B1); PG8_BAR; PG8_SCHED;
	s_setprio 1
	v_mfma_f32_16x16x32_bf16 v[60:63], v[128:131], v[170:173], v[60:63]
	v_mfma_f32_16x16x32_bf16 v[56:59], v[136:139], v[170:173], v[56:59]
	v_mfma_f32_16x16x32_bf16 v[44:47], v[128:131], v[192:195], v[44:47]
	v_mfma_f32_16x16x32_bf16 v[40:43], v[136:139], v[192:195], v[40:43]
	v_mfma_f32_16x16x32_bf16 v[28:31], v[128:131], v[200:203], v[28:31]
	v_mfma_f32_16x16x32_bf16 v[24:27], v[136:139], v[200:203], v[24:27]
	v_mfma_f32_16x16x32_bf16 v[12:15], v[128:131], v[208:211], v[12:15]
	v_mfma_f32_16x16x32_bf16 v[8:11], v[136:139], v[208:211], v[8:11]
	v_mfma_f32_16x16x32_bf16 v[60:63], v[132:135], v[184:187], v[60:63]
	v_mfma_f32_16x16x32_bf16 v[56:59], v[140:143], v[184:187], v[56:59]
	v_mfma_f32_16x16x32_bf16 v[44:47], v[132:135], v[196:199], v[44:47]
	v_mfma_f32_16x16x32_bf16 v[40:43], v[140:143], v[196:199], v[40:43]
	v_mfma_f32_16x16x32_bf16 v[28:31], v[132:135], v[204:207], v[28:31]
	v_mfma_f32_16x16x32_bf16 v[24:27], v[140:143], v[204:207], v[24:27]
	v_mfma_f32_16x16x32_bf16 v[12:15], v[132:135], v[212:215], v[12:15]
	v_mfma_f32_16x16x32_bf16 v[8:11], v[140:143], v[212:215], v[8:11]
	s_setprio 0
	s_setprio 1
	v_mfma_f32_16x16x32_bf16 v[52:55], v[144:147], v[170:173], v[52:55]
	v_mfma_f32_16x16x32_bf16 v[48:51], v[162:165], v[170:173], v[48:51]
	v_mfma_f32_16x16x32_bf16 v[36:39], v[144:147], v[192:195], v[36:39]
	v_mfma_f32_16x16x32_bf16 v[32:35], v[162:165], v[192:195], v[32:35]
	v_mfma_f32_16x16x32_bf16 v[20:23], v[144:147], v[200:203], v[20:23]
	v_mfma_f32_16x16x32_bf16 v[16:19], v[162:165], v[200:203], v[16:19]
	v_mfma_f32_16x16x32_bf16 v[4:7], v[144:147], v[208:211], v[4:7]
	v_mfma_f32_16x16x32_bf16 v[0:3], v[162:165], v[208:211], v[0:3]
	v_mfma_f32_16x16x32_bf16 v[52:55], v[148:151], v[184:187], v[52:55]
	v_mfma_f32_16x16x32_bf16 v[48:51], v[166:169], v[184:187], v[48:51]
	v_mfma_f32_16x16x32_bf16 v[36:39], v[148:151], v[196:199], v[36:39]
	v_mfma_f32_16x16x32_bf16 v[32:35], v[166:169], v[196:199], v[32:35]
	v_mfma_f32_16x16x32_bf16 v[20:23], v[148:151], v[204:207], v[20:23]
	v_mfma_f32_16x16x32_bf16 v[16:19], v[166:169], v[204:207], v[16:19]
	v_mfma_f32_16x16x32_bf16 v[4:7], v[148:151], v[212:215], v[4:7]
	v_mfma_f32_16x16x32_bf16 v[0:3], v[166:169], v[212:215], v[0:3]
	s_setprio 0
	s_barrier
	s_add_i32 s76, 0, 0x18000
	s_add_i32 s77, 0, 0x1c000
	v_add_u32_e32 v140, s76, v189
	v_add_u32_e32 v166, s77, v189
	ds_read_b128 v[128:131], v140
	ds_read_b128 v[132:135], v140 offset:1024
	ds_read_b128 v[136:139], v140 offset:2048
	ds_read_b128 v[140:143], v140 offset:3072
	ds_read_b128 v[144:147], v166
	ds_read_b128 v[148:151], v166 offset:1024
	ds_read_b128 v[162:165], v166 offset:2048
	ds_read_b128 v[166:169], v166 offset:3072
	s_add_u32 s48, s48, 0x80000
	s_addc_u32 s49, s49, 0
	s_mov_b32 m0, s19
	v_lshl_add_u64 v[216:217], s[48:49], 0, v[156:157]
	ds_read_b128 v[170:173], v191 offset:32768
	ds_read_b128 v[184:187], v191 offset:33792
	ds_read_b128 v[192:195], v191 offset:34816
	ds_read_b128 v[196:199], v191 offset:35840
	ds_read_b128 v[200:203], v191 offset:36864
	ds_read_b128 v[204:207], v191 offset:37888
	ds_read_b128 v[208:211], v191 offset:38912
	ds_read_b128 v[212:215], v191 offset:39936
	global_load_lds_dwordx4 v[216:217], off
	v_lshl_add_u64 v[216:217], s[48:49], 0, v[154:155]
	s_mov_b32 m0, s25
	s_nop 0
	global_load_lds_dwordx4 v[216:217], off
	s_waitcnt vmcnt(8)
	s_waitcnt lgkmcnt(0)
	s_barrier
	s_setprio 1
	v_mfma_f32_16x16x32_bf16 v[124:127], v[128:131], v[170:173], v[124:127]
	v_mfma_f32_16x16x32_bf16 v[120:123], v[136:139], v[170:173], v[120:123]
	v_mfma_f32_16x16x32_bf16 v[108:111], v[128:131], v[192:195], v[108:111]
	v_mfma_f32_16x16x32_bf16 v[104:107], v[136:139], v[192:195], v[104:107]
	v_mfma_f32_16x16x32_bf16 v[92:95], v[128:131], v[200:203], v[92:95]
	v_mfma_f32_16x16x32_bf16 v[88:91], v[136:139], v[200:203], v[88:91]
	v_mfma_f32_16x16x32_bf16 v[76:79], v[128:131], v[208:211], v[76:79]
	v_mfma_f32_16x16x32_bf16 v[72:75], v[136:139], v[208:211], v[72:75]
	v_mfma_f32_16x16x32_bf16 v[124:127], v[132:135], v[184:187], v[124:127]
	v_mfma_f32_16x16x32_bf16 v[120:123], v[140:143], v[184:187], v[120:123]
	v_mfma_f32_16x16x32_bf16 v[108:111], v[132:135], v[196:199], v[108:111]
	v_mfma_f32_16x16x32_bf16 v[104:107], v[140:143], v[196:199], v[104:107]
	v_mfma_f32_16x16x32_bf16 v[92:95], v[132:135], v[204:207], v[92:95]
	v_mfma_f32_16x16x32_bf16 v[88:91], v[140:143], v[204:207], v[88:91]
	v_mfma_f32_16x16x32_bf16 v[76:79], v[132:135], v[212:215], v[76:79]
	v_mfma_f32_16x16x32_bf16 v[72:75], v[140:143], v[212:215], v[72:75]
	s_setprio 0
	s_setprio 1
	v_mfma_f32_16x16x32_bf16 v[116:119], v[144:147], v[170:173], v[116:119]
	v_mfma_f32_16x16x32_bf16 v[112:115], v[162:165], v[170:173], v[112:115]
	v_mfma_f32_16x16x32_bf16 v[100:103], v[144:147], v[192:195], v[100:103]
	v_mfma_f32_16x16x32_bf16 v[96:99], v[162:165], v[192:195], v[96:99]
	v_mfma_f32_16x16x32_bf16 v[84:87], v[144:147], v[200:203], v[84:87]
	v_mfma_f32_16x16x32_bf16 v[80:83], v[162:165], v[200:203], v[80:83]
	v_mfma_f32_16x16x32_bf16 v[68:71], v[144:147], v[208:211], v[68:71]
	v_mfma_f32_16x16x32_bf16 v[64:67], v[162:165], v[208:211], v[64:67]
	v_mfma_f32_16x16x32_bf16 v[116:119], v[148:151], v[184:187], v[116:119]
	v_mfma_f32_16x16x32_bf16 v[112:115], v[166:169], v[184:187], v[112:115]
	v_mfma_f32_16x16x32_bf16 v[100:103], v[148:151], v[196:199], v[100:103]
	v_mfma_f32_16x16x32_bf16 v[96:99], v[166:169], v[196:199], v[96:99]
	v_mfma_f32_16x16x32_bf16 v[84:87], v[148:151], v[204:207], v[84:87]
	v_mfma_f32_16x16x32_bf16 v[80:83], v[166:169], v[204:207], v[80:83]
	v_mfma_f32_16x16x32_bf16 v[68:71], v[148:151], v[212:215], v[68:71]
	v_mfma_f32_16x16x32_bf16 v[64:67], v[166:169], v[212:215], v[64:67]
	s_setprio 0
	s_barrier
; #define PG8_STAGE(bufoff, gbase, voff) do { _Pragma("unroll") for (int _i = 0; _i < 2; ++_i) \
;         __builtin_amdgcn_global_load_lds((const unsigned*)((const char*)(gbase) + (voff)[_i]), (PG8_LAS unsigned*)(lds + (bufoff) + ldsw + _i * 8192), 16, 0, 0); } while (0)
; #define PG8_LDA(dst, b, h) do { _Pragma("unroll") for (int m = 0; m < 4; ++m) _Pragma("unroll") for (int k = 0; k < 2; ++k) dst[m][k] = *(const PG8_LAS bf16x8*)(lds + PG8_SA(b, h) + aoff + m * 2048 + k * 1024); } while (0)
; #define PG8_MMA(ai, bj, At, Bt) do { __builtin_amdgcn_s_setprio(1); _Pragma("unroll") for (int m = 0; m < 4; ++m) _Pragma("unroll") for (int n = 0; n < 2; ++n) _Pragma("unroll") for (int k = 0; k < 2; ++k) \
;         acc[ai][bj][m][n] = __builtin_amdgcn_mfma_f32_16x16x32_bf16(Bt[n][k], At[m][k], acc[ai][bj][m][n], 0, 0, 0); __builtin_amdgcn_s_setprio(0); } while (0)
; #define PG8_WAIT_L(n) asm volatile("s_waitcnt lgkmcnt(" #n ")" ::: "memory")
; #define PG8_WAIT_VK do { if constexpr (HALFM) PG8_WAIT_V(6); else PG8_WAIT_V(8); } while (0)
; #define PG8_BAR __builtin_amdgcn_s_barrier()
; #define PG8_SCHED __builtin_amdgcn_sched_barrier(0)
; template <class Epi, class Sched, bool ALIGN_EPI = false, bool SP2 = false, bool HALFM = false, bool AMAP = false>
; __device__ __forceinline__ void gemm_phase(PG8_LAS unsigned char* lds, const Gemm g, const Sched& S, const Epi& E, int tid_in) {
;     ...
;             if constexpr (!HALFM) { PG8_LDA(At, 1, 1); } PG8_STAGE(PG8_SB(1, 0), b3, voffB); PG8_STAGE(PG8_SB(1, 1), b3 + hstepB, voffB); PG8_STAGE(PG8_SA(1, 0), a3, voffA);
;             PG8_WAIT_VK; PG8_WAIT_L(0); PG8_BAR; if constexpr (!HALFM) { PG8_MMA(1, 0, At, B0); PG8_MMA(1, 1, At, B1); } PG8_BAR; PG8_SCHED;
	s_add_i32 s48, s76, s10
	v_lshl_add_u64 v[174:175], v[174:175], 0, s[66:67]
	s_mov_b32 m0, s48
	ds_read_b128 v[170:173], v191 offset:49152
	ds_read_b128 v[184:187], v191 offset:50176
	ds_read_b128 v[192:195], v191 offset:51200
	ds_read_b128 v[196:199], v191 offset:52224
	ds_read_b128 v[200:203], v191 offset:53248
	ds_read_b128 v[204:207], v191 offset:54272
	ds_read_b128 v[208:211], v191 offset:55296
	ds_read_b128 v[212:215], v191 offset:56320
	global_load_lds_dwordx4 v[174:175], off
	s_add_i32 m0, s48, 0x2000
	s_add_u32 s30, s30, 0x80080
	v_lshl_add_u64 v[174:175], v[178:179], 0, s[66:67]
	s_addc_u32 s31, s31, 0
	s_add_i32 s48, s77, s10
	global_load_lds_dwordx4 v[174:175], off
	v_lshl_add_u64 v[174:175], s[30:31], 0, v[176:177]
	s_mov_b32 m0, s48
	s_nop 0
	global_load_lds_dwordx4 v[174:175], off
	v_lshl_add_u64 v[174:175], s[30:31], 0, v[152:153]
	s_add_i32 m0, s48, 0x2000
	s_nop 0
	global_load_lds_dwordx4 v[174:175], off
	v_lshl_add_u64 v[174:175], v[180:181], 0, s[66:67]
	s_mov_b32 m0, s39
	s_nop 0
	global_load_lds_dwordx4 v[174:175], off
	v_lshl_add_u64 v[174:175], v[182:183], 0, s[66:67]
	s_mov_b32 m0, s58
	s_nop 0
	global_load_lds_dwordx4 v[174:175], off
	s_waitcnt vmcnt(8)
	s_waitcnt lgkmcnt(0)
	s_barrier
	s_setprio 1
	v_mfma_f32_16x16x32_bf16 v[60:63], v[128:131], v[170:173], v[60:63]
	v_mfma_f32_16x16x32_bf16 v[56:59], v[136:139], v[170:173], v[56:59]
	v_mfma_f32_16x16x32_bf16 v[44:47], v[128:131], v[192:195], v[44:47]
	v_mfma_f32_16x16x32_bf16 v[40:43], v[136:139], v[192:195], v[40:43]
	v_mfma_f32_16x16x32_bf16 v[28:31], v[128:131], v[200:203], v[28:31]
	v_mfma_f32_16x16x32_bf16 v[24:27], v[136:139], v[200:203], v[24:27]
	v_mfma_f32_16x16x32_bf16 v[12:15], v[128:131], v[208:211], v[12:15]
	v_mfma_f32_16x16x32_bf16 v[8:11], v[136:139], v[208:211], v[8:11]
	v_mfma_f32_16x16x32_bf16 v[60:63], v[132:135], v[184:187], v[60:63]
	v_mfma_f32_16x16x32_bf16 v[56:59], v[140:143], v[184:187], v[56:59]
	v_mfma_f32_16x16x32_bf16 v[44:47], v[132:135], v[196:199], v[44:47]
	v_mfma_f32_16x16x32_bf16 v[40:43], v[140:143], v[196:199], v[40:43]
	v_mfma_f32_16x16x32_bf16 v[28:31], v[132:135], v[204:207], v[28:31]
	v_mfma_f32_16x16x32_bf16 v[24:27], v[140:143], v[204:207], v[24:27]
	v_mfma_f32_16x16x32_bf16 v[12:15], v[132:135], v[212:215], v[12:15]
	v_mfma_f32_16x16x32_bf16 v[8:11], v[140:143], v[212:215], v[8:11]
	s_setprio 0
	s_setprio 1
	v_mfma_f32_16x16x32_bf16 v[52:55], v[144:147], v[170:173], v[52:55]
	v_mfma_f32_16x16x32_bf16 v[48:51], v[162:165], v[170:173], v[48:51]
	v_mfma_f32_16x16x32_bf16 v[36:39], v[144:147], v[192:195], v[36:39]
	v_mfma_f32_16x16x32_bf16 v[32:35], v[162:165], v[192:195], v[32:35]
	v_mfma_f32_16x16x32_bf16 v[20:23], v[144:147], v[200:203], v[20:23]
	v_mfma_f32_16x16x32_bf16 v[16:19], v[162:165], v[200:203], v[16:19]
	v_mfma_f32_16x16x32_bf16 v[4:7], v[144:147], v[208:211], v[4:7]
	v_mfma_f32_16x16x32_bf16 v[0:3], v[162:165], v[208:211], v[0:3]
	v_mfma_f32_16x16x32_bf16 v[52:55], v[148:151], v[184:187], v[52:55]
	v_mfma_f32_16x16x32_bf16 v[48:51], v[166:169], v[184:187], v[48:51]
	v_mfma_f32_16x16x32_bf16 v[36:39], v[148:151], v[196:199], v[36:39]
	v_mfma_f32_16x16x32_bf16 v[32:35], v[166:169], v[196:199], v[32:35]
	v_mfma_f32_16x16x32_bf16 v[20:23], v[148:151], v[204:207], v[20:23]
	v_mfma_f32_16x16x32_bf16 v[16:19], v[166:169], v[204:207], v[16:19]
	v_mfma_f32_16x16x32_bf16 v[4:7], v[148:151], v[212:215], v[4:7]
	v_mfma_f32_16x16x32_bf16 v[0:3], v[166:169], v[212:215], v[0:3]
	s_setprio 0
	s_barrier
	s_add_i32 s80, s80, 2
	s_add_u32 s62, s62, 0x100
	s_addc_u32 s63, s63, 0
	s_add_u32 s28, s28, 0x100
	s_addc_u32 s29, s29, 0
	s_cmp_gt_u32 s80, 29
	s_cbranch_scc0 .LBB0_650
	s_and_b64 vcc, exec, s[22:23]
	s_cbranch_vccz .LBB0_653
	s_barrier
; __device__ __forceinline__ unsigned cvt_pk_bf16(float lo, float hi) { unsigned r; asm volatile("v_cvt_pk_bf16_f32 %0, %1, %2" : "=v"(r) : "v"(lo), "v"(hi)); return r; }
; __device__ __forceinline__ float sum_fq(float s) { return sum_xor32(sum_xor16(s)); }
;     __device__ __forceinline__ void operator()(const f32x4 (&acc)[2][2][4][2], const Unit& u, int wr, int wc, int fr, int fq) const {
;         const int z = opaque0(); const int row0 = u.pm * BM + wr * 64 + fr + z, col0 = u.pn * BM + wc * 32 + 8 * fq + z;
; #pragma unroll
;         for (int ai = 0; ai < 2; ++ai) {
;             u32x4 rb[4][2];
; #pragma unroll
;             for (int m = 0; m < 4; ++m) { const size_t off = (size_t)(row0 + ai * HALF + m * 16) * 2048 + col0;
; #pragma unroll
;                 for (int bj = 0; bj < 2; ++bj) rb[m][bj] = *(const u32x4*)(xb + off + bj * HALF); }
;             __builtin_amdgcn_sched_barrier(0);
; #pragma unroll
;             for (int m = 0; m < 4; ++m) { const int row = row0 + ai * HALF + m * 16; const size_t off = (size_t)row * 2048 + col0; float sq = 0.f;
; #pragma unroll
;                 for (int bj = 0; bj < 2; ++bj) { const u32x4 r = rb[m][bj];
;                     const f32x4 b0 = (f32x4){__builtin_bit_cast(float, r.x << 16), __builtin_bit_cast(float, r.x & 0xffff0000u), __builtin_bit_cast(float, r.y << 16), __builtin_bit_cast(float, r.y & 0xffff0000u)};
;                     const f32x4 b1 = (f32x4){__builtin_bit_cast(float, r.z << 16), __builtin_bit_cast(float, r.z & 0xffff0000u), __builtin_bit_cast(float, r.w << 16), __builtin_bit_cast(float, r.w & 0xffff0000u)};
;                     const f32x4 o0 = b0 + acc[ai][bj][m][0] * alpha, o1 = b1 + acc[ai][bj][m][1] * alpha;
;                     if (wf) { *(f32x4*)(fout + off + bj * HALF) = o0; *(f32x4*)(fout + off + bj * HALF + 4) = o1; }
;                     sq += (o0[0] * o0[0] + o0[1] * o0[1]) + (o0[2] * o0[2] + o0[3] * o0[3]) + (o1[0] * o1[0] + o1[1] * o1[1]) + (o1[2] * o1[2] + o1[3] * o1[3]);
;                     u32x4 w; w.x = cvt_pk_bf16(o0[0], o0[1]); w.y = cvt_pk_bf16(o0[2], o0[3]); w.z = cvt_pk_bf16(o1[0], o1[1]); w.w = cvt_pk_bf16(o1[2], o1[3]);
;                     *(u32x4*)(xb + off + bj * HALF) = w; }
;                 sq = sum_fq(sq);
;                 if (fq == 0) ssq[(size_t)row * 32 + u.pn * 4 + wc] = sq; }
.LBB0_653:
	v_lshl_or_b32 v129, s60, 8, v190
	v_mov_b32 v128, 0
	s_lshl_b32 s28, s61, 8
	v_add_u32_e32 v162, v129, v128
	v_add3_u32 v164, s28, v188, v128
	v_ashrrev_i32_e32 v163, 31, v162
	v_lshlrev_b64 v[178:179], 1, v[162:163]
	v_ashrrev_i32_e32 v165, 31, v164
	v_add_u32_e32 v184, 16, v164
	v_lshl_add_u64 v[166:167], s[16:17], 0, v[178:179]
	v_lshlrev_b64 v[180:181], 12, v[164:165]
	v_ashrrev_i32_e32 v185, 31, v184
	v_add_u32_e32 v172, 32, v164
	v_lshl_add_u64 v[128:129], v[166:167], 0, v[180:181]
	v_lshlrev_b64 v[186:187], 12, v[184:185]
	v_ashrrev_i32_e32 v173, 31, v172
	v_add_u32_e32 v168, 48, v164
	global_load_dwordx4 v[192:195], v[128:129], off
	global_load_dwordx4 v[196:199], v[128:129], off offset:256
	v_lshl_add_u64 v[128:129], v[166:167], 0, v[186:187]
	v_lshlrev_b64 v[174:175], 12, v[172:173]
	v_ashrrev_i32_e32 v169, 31, v168
	global_load_dwordx4 v[148:151], v[128:129], off
	global_load_dwordx4 v[144:147], v[128:129], off offset:256
	v_lshl_add_u64 v[128:129], v[166:167], 0, v[174:175]
	v_lshlrev_b64 v[170:171], 12, v[168:169]
	global_load_dwordx4 v[140:143], v[128:129], off
	global_load_dwordx4 v[136:139], v[128:129], off offset:256
	v_lshl_add_u64 v[128:129], v[166:167], 0, v[170:171]
	global_load_dwordx4 v[132:135], v[128:129], off
	s_nop 0
	global_load_dwordx4 v[128:131], v[128:129], off offset:256
	v_add_u32_e32 v218, 0x80, v164
	v_ashrrev_i32_e32 v219, 31, v218
	v_lshlrev_b64 v[240:241], 12, v[218:219]
	v_lshl_add_u64 v[240:241], v[166:167], 0, v[240:241]
	global_load_dwordx4 v[202:205], v[240:241], off
	global_load_dwordx4 v[206:209], v[240:241], off offset:256
	v_add_u32_e32 v218, 0x90, v164
	v_ashrrev_i32_e32 v219, 31, v218
	v_lshlrev_b64 v[240:241], 12, v[218:219]
	v_lshl_add_u64 v[240:241], v[166:167], 0, v[240:241]
	global_load_dwordx4 v[210:213], v[240:241], off
	global_load_dwordx4 v[214:217], v[240:241], off offset:256
	v_add_u32_e32 v218, 0xa0, v164
	v_ashrrev_i32_e32 v219, 31, v218
	v_lshlrev_b64 v[240:241], 12, v[218:219]
	v_lshl_add_u64 v[240:241], v[166:167], 0, v[240:241]
	global_load_dwordx4 v[222:225], v[240:241], off
	global_load_dwordx4 v[228:231], v[240:241], off offset:256
	v_add_u32_e32 v218, 0xb0, v164
	v_ashrrev_i32_e32 v219, 31, v218
	v_lshlrev_b64 v[240:241], 12, v[218:219]
	v_lshl_add_u64 v[240:241], v[166:167], 0, v[240:241]
	global_load_dwordx4 v[232:235], v[240:241], off
	global_load_dwordx4 v[236:239], v[240:241], off offset:256
	s_lshl_b32 s28, s60, 2
	s_ashr_i32 s29, s28, 31
	s_waitcnt vmcnt(8)
	v_lshlrev_b32_e32 v182, 16, v192
	v_and_b32_e32 v183, 0xffff0000, v192
	v_lshlrev_b32_e32 v192, 16, v193
	v_and_b32_e32 v193, 0xffff0000, v193
	v_lshlrev_b32_e32 v200, 16, v194
	v_and_b32_e32 v201, 0xffff0000, v194
	v_lshlrev_b32_e32 v194, 16, v195
	v_and_b32_e32 v195, 0xffff0000, v195
	v_pk_add_f32 v[126:127], v[126:127], v[192:193]
	v_pk_add_f32 v[124:125], v[124:125], v[182:183]
	v_pk_add_f32 v[182:183], v[122:123], v[194:195]
	v_pk_add_f32 v[122:123], v[120:121], v[200:201]
	v_mul_f32_e32 v120, v125, v125
	v_mul_f32_e32 v121, v127, v127
	v_fmac_f32_e32 v120, v124, v124
	v_fmac_f32_e32 v121, v126, v126
	v_add_f32_e32 v120, v120, v121
	v_mul_f32_e32 v121, v123, v123
	v_fmac_f32_e32 v121, v122, v122
	v_add_f32_e32 v120, v121, v120
	v_mul_f32_e32 v121, v183, v183
	v_fmac_f32_e32 v121, v182, v182
	v_add_f32_e32 v192, v121, v120
	v_cvt_pk_bf16_f32 v120, v124, v125
	v_lshl_add_u64 v[124:125], s[16:17], 0, v[180:181]
	v_cvt_pk_bf16_f32 v121, v126, v127
	v_cvt_pk_bf16_f32 v122, v122, v123
	v_cvt_pk_bf16_f32 v123, v182, v183
	v_lshl_add_u64 v[124:125], v[124:125], 0, v[178:179]
	global_store_dwordx4 v[124:125], v[120:123], off
	v_lshlrev_b32_e32 v126, 16, v198
	v_and_b32_e32 v127, 0xffff0000, v198
	v_lshlrev_b32_e32 v120, 16, v196
	v_and_b32_e32 v121, 0xffff0000, v196
	v_lshlrev_b32_e32 v122, 16, v197
	v_and_b32_e32 v123, 0xffff0000, v197
	v_lshlrev_b32_e32 v178, 16, v199
	v_and_b32_e32 v179, 0xffff0000, v199
	v_pk_add_f32 v[118:119], v[118:119], v[122:123]
	v_pk_add_f32 v[116:117], v[116:117], v[120:121]
	v_pk_add_f32 v[120:121], v[114:115], v[178:179]
	v_pk_add_f32 v[114:115], v[112:113], v[126:127]
	v_mul_f32_e32 v112, v117, v117
	v_mul_f32_e32 v113, v119, v119
	v_fmac_f32_e32 v112, v116, v116
	v_fmac_f32_e32 v113, v118, v118
	v_add_f32_e32 v112, v112, v113
	v_mul_f32_e32 v113, v115, v115
	v_fmac_f32_e32 v113, v114, v114
	v_add_f32_e32 v112, v113, v112
	v_mul_f32_e32 v113, v121, v121
	v_fmac_f32_e32 v113, v120, v120
	v_add_f32_e32 v112, v113, v112
	v_add_f32_e32 v122, v192, v112
	v_cvt_pk_bf16_f32 v112, v116, v117
	v_cvt_pk_bf16_f32 v113, v118, v119
	v_cvt_pk_bf16_f32 v114, v114, v115
	v_cvt_pk_bf16_f32 v115, v120, v121
	global_store_dwordx4 v[124:125], v[112:115], off offset:256
	s_nop 1
	v_mov_b32_e32 v112, v122
	s_nop 1
	v_permlane16_swap_b32 v122, v112
	s_nop 0
	v_add_f32_e32 v112, v122, v112
	v_mov_b32_e32 v113, v112
	s_nop 1
	v_permlane32_swap_b32 v112, v113
	s_and_saveexec_b64 s[30:31], s[4:5]
	s_cbranch_execz .LBB0_655
	v_lshlrev_b64 v[114:115], 7, v[164:165]
	v_lshl_add_u64 v[114:115], s[20:21], 0, v[114:115]
	v_lshl_add_u64 v[114:115], s[28:29], 2, v[114:115]
	s_lshl_b32 s36, s38, 2
	s_mov_b32 s37, s24
	v_lshl_add_u64 v[114:115], v[114:115], 0, s[36:37]
	v_add_f32_e32 v112, v112, v113
	global_store_dword v[114:115], v112, off

; __device__ __forceinline__ unsigned cvt_pk_bf16(float lo, float hi) { unsigned r; asm volatile("v_cvt_pk_bf16_f32 %0, %1, %2" : "=v"(r) : "v"(lo), "v"(hi)); return r; }
; __device__ __forceinline__ float sum_fq(float s) { return sum_xor32(sum_xor16(s)); }
;     __device__ __forceinline__ void operator()(const f32x4 (&acc)[2][2][4][2], const Unit& u, int wr, int wc, int fr, int fq) const {
;     ...
;         for (int ai = 0; ai < 2; ++ai) {
;             u32x4 rb[4][2];
; #pragma unroll
;             for (int m = 0; m < 4; ++m) { const size_t off = (size_t)(row0 + ai * HALF + m * 16) * 2048 + col0;
; #pragma unroll
;                 for (int bj = 0; bj < 2; ++bj) rb[m][bj] = *(const u32x4*)(xb + off + bj * HALF); }
;             __builtin_amdgcn_sched_barrier(0);
; #pragma unroll
;             for (int m = 0; m < 4; ++m) { const int row = row0 + ai * HALF + m * 16; const size_t off = (size_t)row * 2048 + col0; float sq = 0.f;
; #pragma unroll
;                 for (int bj = 0; bj < 2; ++bj) { const u32x4 r = rb[m][bj];
;                     const f32x4 b0 = (f32x4){__builtin_bit_cast(float, r.x << 16), __builtin_bit_cast(float, r.x & 0xffff0000u), __builtin_bit_cast(float, r.y << 16), __builtin_bit_cast(float, r.y & 0xffff0000u)};
;                     const f32x4 b1 = (f32x4){__builtin_bit_cast(float, r.z << 16), __builtin_bit_cast(float, r.z & 0xffff0000u), __builtin_bit_cast(float, r.w << 16), __builtin_bit_cast(float, r.w & 0xffff0000u)};
;                     const f32x4 o0 = b0 + acc[ai][bj][m][0] * alpha, o1 = b1 + acc[ai][bj][m][1] * alpha;
;                     if (wf) { *(f32x4*)(fout + off + bj * HALF) = o0; *(f32x4*)(fout + off + bj * HALF + 4) = o1; }
;                     sq += (o0[0] * o0[0] + o0[1] * o0[1]) + (o0[2] * o0[2] + o0[3] * o0[3]) + (o1[0] * o1[0] + o1[1] * o1[1]) + (o1[2] * o1[2] + o1[3] * o1[3]);
;                     u32x4 w; w.x = cvt_pk_bf16(o0[0], o0[1]); w.y = cvt_pk_bf16(o0[2], o0[3]); w.z = cvt_pk_bf16(o1[0], o1[1]); w.w = cvt_pk_bf16(o1[2], o1[3]);
;                     *(u32x4*)(xb + off + bj * HALF) = w; }
;                 sq = sum_fq(sq);
;                 if (fq == 0) ssq[(size_t)row * 32 + u.pn * 4 + wc] = sq; }
;             __builtin_amdgcn_sched_barrier(0); }
.LBB0_661:
	s_or_b64 exec, exec, s[30:31]
	v_add_u32_e32 v100, 0x80, v164
	v_ashrrev_i32_e32 v101, 31, v100
	v_add_u32_e32 v96, 0x90, v164
	v_lshlrev_b64 v[110:111], 12, v[100:101]
	v_ashrrev_i32_e32 v97, 31, v96
	v_add_u32_e32 v92, 0xa0, v164
	v_lshl_add_u64 v[64:65], v[166:167], 0, v[110:111]
	v_lshlrev_b64 v[98:99], 12, v[96:97]
	v_ashrrev_i32_e32 v93, 31, v92
	v_add_u32_e32 v88, 0xb0, v164
	v_lshl_add_u64 v[64:65], v[166:167], 0, v[98:99]
	v_lshlrev_b64 v[94:95], 12, v[92:93]
	v_ashrrev_i32_e32 v89, 31, v88
	v_lshl_add_u64 v[64:65], v[166:167], 0, v[94:95]
	v_lshlrev_b64 v[90:91], 12, v[88:89]
	v_lshl_add_u64 v[64:65], v[166:167], 0, v[90:91]
	s_waitcnt vmcnt(8)
	v_lshlrev_b32_e32 v112, 16, v202
	v_and_b32_e32 v113, 0xffff0000, v202
	v_lshlrev_b32_e32 v102, 16, v203
	v_and_b32_e32 v103, 0xffff0000, v203
	v_lshlrev_b32_e32 v114, 16, v204
	v_and_b32_e32 v115, 0xffff0000, v204
	v_lshlrev_b32_e32 v104, 16, v205
	v_and_b32_e32 v105, 0xffff0000, v205
	v_pk_add_f32 v[62:63], v[62:63], v[102:103]
	v_pk_add_f32 v[60:61], v[60:61], v[112:113]
	v_pk_add_f32 v[102:103], v[58:59], v[104:105]
	v_pk_add_f32 v[58:59], v[56:57], v[114:115]
	v_mul_f32_e32 v56, v61, v61
	v_mul_f32_e32 v57, v63, v63
	v_fmac_f32_e32 v56, v60, v60
	v_fmac_f32_e32 v57, v62, v62
	v_add_f32_e32 v56, v56, v57
	v_mul_f32_e32 v57, v59, v59
	v_fmac_f32_e32 v57, v58, v58
	v_add_f32_e32 v56, v57, v56
	v_mul_f32_e32 v57, v103, v103
	v_fmac_f32_e32 v57, v102, v102
	v_add_f32_e32 v104, v57, v56
	v_cvt_pk_bf16_f32 v56, v60, v61
	v_lshl_add_u64 v[60:61], s[16:17], 0, v[110:111]
	v_cvt_pk_bf16_f32 v57, v62, v63
	v_cvt_pk_bf16_f32 v58, v58, v59
	v_cvt_pk_bf16_f32 v59, v102, v103
	v_lshl_add_u64 v[60:61], v[162:163], 1, v[60:61]
	global_store_dwordx4 v[60:61], v[56:59], off
	v_lshlrev_b32_e32 v62, 16, v208
	v_and_b32_e32 v63, 0xffff0000, v208
	v_lshlrev_b32_e32 v56, 16, v206
	v_and_b32_e32 v57, 0xffff0000, v206
	v_lshlrev_b32_e32 v58, 16, v207
	v_and_b32_e32 v59, 0xffff0000, v207
	v_lshlrev_b32_e32 v102, 16, v209
	v_and_b32_e32 v103, 0xffff0000, v209
	v_pk_add_f32 v[54:55], v[54:55], v[58:59]
	v_pk_add_f32 v[52:53], v[52:53], v[56:57]
	v_pk_add_f32 v[56:57], v[50:51], v[102:103]
	v_pk_add_f32 v[50:51], v[48:49], v[62:63]
	v_mul_f32_e32 v48, v53, v53
	v_mul_f32_e32 v49, v55, v55
	v_fmac_f32_e32 v48, v52, v52
	v_fmac_f32_e32 v49, v54, v54
	v_add_f32_e32 v48, v48, v49
	v_mul_f32_e32 v49, v51, v51
	v_fmac_f32_e32 v49, v50, v50
	v_add_f32_e32 v48, v49, v48
	v_mul_f32_e32 v49, v57, v57
	v_fmac_f32_e32 v49, v56, v56
	v_add_f32_e32 v48, v49, v48
	v_add_f32_e32 v58, v104, v48
	v_cvt_pk_bf16_f32 v48, v52, v53
	v_cvt_pk_bf16_f32 v49, v54, v55
	v_cvt_pk_bf16_f32 v50, v50, v51
	v_cvt_pk_bf16_f32 v51, v56, v57
	global_store_dwordx4 v[60:61], v[48:51], off offset:256
	s_nop 1
	v_mov_b32_e32 v48, v58
	s_nop 1
	v_permlane16_swap_b32 v48, v58
	s_nop 0
	v_add_f32_e32 v48, v48, v58
	v_mov_b32_e32 v49, v48
	s_nop 1
	v_permlane32_swap_b32 v48, v49
	s_and_saveexec_b64 s[30:31], s[4:5]
	s_cbranch_execz .LBB0_663
	v_lshlrev_b64 v[50:51], 7, v[100:101]
	v_lshl_add_u64 v[50:51], s[20:21], 0, v[50:51]
	v_lshl_add_u64 v[50:51], s[28:29], 2, v[50:51]
	s_lshl_b32 s36, s38, 2
	s_mov_b32 s37, s24
	v_lshl_add_u64 v[50:51], v[50:51], 0, s[36:37]
	v_add_f32_e32 v48, v48, v49
	global_store_dword v[50:51], v48, off
.LBB0_663:
	s_or_b64 exec, exec, s[30:31]
	v_lshlrev_b32_e32 v48, 16, v210
	v_and_b32_e32 v49, 0xffff0000, v210
	v_lshlrev_b32_e32 v50, 16, v211
	v_and_b32_e32 v51, 0xffff0000, v211
	v_lshlrev_b32_e32 v52, 16, v212
	v_and_b32_e32 v53, 0xffff0000, v212
	v_lshlrev_b32_e32 v54, 16, v213
	v_and_b32_e32 v55, 0xffff0000, v213
	v_pk_add_f32 v[46:47], v[46:47], v[50:51]
	v_pk_add_f32 v[44:45], v[44:45], v[48:49]
	v_pk_add_f32 v[48:49], v[42:43], v[54:55]
	v_pk_add_f32 v[42:43], v[40:41], v[52:53]
	v_mul_f32_e32 v40, v45, v45
	v_mul_f32_e32 v41, v47, v47
	v_fmac_f32_e32 v40, v44, v44
	v_fmac_f32_e32 v41, v46, v46
	v_add_f32_e32 v40, v40, v41
	v_mul_f32_e32 v41, v43, v43
	v_fmac_f32_e32 v41, v42, v42
	v_add_f32_e32 v40, v41, v40
	v_mul_f32_e32 v41, v49, v49
	v_fmac_f32_e32 v41, v48, v48
	v_add_f32_e32 v50, v41, v40
	v_cvt_pk_bf16_f32 v40, v44, v45
	v_lshl_add_u64 v[44:45], s[16:17], 0, v[98:99]
	v_cvt_pk_bf16_f32 v41, v46, v47
	v_cvt_pk_bf16_f32 v42, v42, v43
	v_cvt_pk_bf16_f32 v43, v48, v49
	v_lshl_add_u64 v[44:45], v[162:163], 1, v[44:45]
	global_store_dwordx4 v[44:45], v[40:43], off
	v_lshlrev_b32_e32 v46, 16, v216
	v_and_b32_e32 v47, 0xffff0000, v216
	v_lshlrev_b32_e32 v40, 16, v214
	v_and_b32_e32 v41, 0xffff0000, v214
	v_lshlrev_b32_e32 v42, 16, v215
	v_and_b32_e32 v43, 0xffff0000, v215
	v_lshlrev_b32_e32 v48, 16, v217
	v_and_b32_e32 v49, 0xffff0000, v217
	v_pk_add_f32 v[38:39], v[38:39], v[42:43]
	v_pk_add_f32 v[36:37], v[36:37], v[40:41]
	v_pk_add_f32 v[40:41], v[34:35], v[48:49]
	v_pk_add_f32 v[34:35], v[32:33], v[46:47]
	v_mul_f32_e32 v32, v37, v37
	v_mul_f32_e32 v33, v39, v39
	v_fmac_f32_e32 v32, v36, v36
	v_fmac_f32_e32 v33, v38, v38
	v_add_f32_e32 v32, v32, v33
	v_mul_f32_e32 v33, v35, v35
	v_fmac_f32_e32 v33, v34, v34
	v_add_f32_e32 v32, v33, v32
	v_mul_f32_e32 v33, v41, v41
	v_fmac_f32_e32 v33, v40, v40
	v_add_f32_e32 v32, v33, v32
	v_add_f32_e32 v42, v50, v32
	v_cvt_pk_bf16_f32 v32, v36, v37
	v_cvt_pk_bf16_f32 v33, v38, v39
	v_cvt_pk_bf16_f32 v34, v34, v35
	v_cvt_pk_bf16_f32 v35, v40, v41
	global_store_dwordx4 v[44:45], v[32:35], off offset:256
	s_nop 1
	v_mov_b32_e32 v32, v42
	s_nop 1
	v_permlane16_swap_b32 v42, v32
	s_nop 0
	v_add_f32_e32 v32, v42, v32
	v_mov_b32_e32 v33, v32
	s_nop 1
	v_permlane32_swap_b32 v33, v32
	s_and_saveexec_b64 s[30:31], s[4:5]
	s_cbranch_execz .LBB0_665
	v_lshlrev_b64 v[34:35], 7, v[96:97]
	v_lshl_add_u64 v[34:35], s[20:21], 0, v[34:35]
	v_lshl_add_u64 v[34:35], s[28:29], 2, v[34:35]
	s_lshl_b32 s36, s38, 2
	s_mov_b32 s37, s24
	v_lshl_add_u64 v[34:35], v[34:35], 0, s[36:37]
	v_add_f32_e32 v32, v33, v32
	global_store_dword v[34:35], v32, off
; __device__ __forceinline__ unsigned cvt_pk_bf16(float lo, float hi) { unsigned r; asm volatile("v_cvt_pk_bf16_f32 %0, %1, %2" : "=v"(r) : "v"(lo), "v"(hi)); return r; }
; __device__ __forceinline__ float sum_fq(float s) { return sum_xor32(sum_xor16(s)); }
;     __device__ __forceinline__ void operator()(const f32x4 (&acc)[2][2][4][2], const Unit& u, int wr, int wc, int fr, int fq) const {
;     ...
;             for (int m = 0; m < 4; ++m) { const int row = row0 + ai * HALF + m * 16; const size_t off = (size_t)row * 2048 + col0; float sq = 0.f;
; #pragma unroll
;                 for (int bj = 0; bj < 2; ++bj) { const u32x4 r = rb[m][bj];
;                     const f32x4 b0 = (f32x4){__builtin_bit_cast(float, r.x << 16), __builtin_bit_cast(float, r.x & 0xffff0000u), __builtin_bit_cast(float, r.y << 16), __builtin_bit_cast(float, r.y & 0xffff0000u)};
;                     const f32x4 b1 = (f32x4){__builtin_bit_cast(float, r.z << 16), __builtin_bit_cast(float, r.z & 0xffff0000u), __builtin_bit_cast(float, r.w << 16), __builtin_bit_cast(float, r.w & 0xffff0000u)};
;                     const f32x4 o0 = b0 + acc[ai][bj][m][0] * alpha, o1 = b1 + acc[ai][bj][m][1] * alpha;
;                     if (wf) { *(f32x4*)(fout + off + bj * HALF) = o0; *(f32x4*)(fout + off + bj * HALF + 4) = o1; }
;                     sq += (o0[0] * o0[0] + o0[1] * o0[1]) + (o0[2] * o0[2] + o0[3] * o0[3]) + (o1[0] * o1[0] + o1[1] * o1[1]) + (o1[2] * o1[2] + o1[3] * o1[3]);
;                     u32x4 w; w.x = cvt_pk_bf16(o0[0], o0[1]); w.y = cvt_pk_bf16(o0[2], o0[3]); w.z = cvt_pk_bf16(o1[0], o1[1]); w.w = cvt_pk_bf16(o1[2], o1[3]);
;                     *(u32x4*)(xb + off + bj * HALF) = w; }
;                 sq = sum_fq(sq);
;                 if (fq == 0) ssq[(size_t)row * 32 + u.pn * 4 + wc] = sq; }
.LBB0_665:
	s_or_b64 exec, exec, s[30:31]
	v_lshlrev_b32_e32 v32, 16, v222
	v_and_b32_e32 v33, 0xffff0000, v222
	v_lshlrev_b32_e32 v34, 16, v223
	v_and_b32_e32 v35, 0xffff0000, v223
	v_lshlrev_b32_e32 v36, 16, v224
	v_and_b32_e32 v37, 0xffff0000, v224
	v_lshlrev_b32_e32 v38, 16, v225
	v_and_b32_e32 v39, 0xffff0000, v225
	v_pk_add_f32 v[30:31], v[30:31], v[34:35]
	v_pk_add_f32 v[28:29], v[28:29], v[32:33]
	v_pk_add_f32 v[32:33], v[26:27], v[38:39]
	v_pk_add_f32 v[26:27], v[24:25], v[36:37]
	v_mul_f32_e32 v24, v29, v29
	v_mul_f32_e32 v25, v31, v31
	v_fmac_f32_e32 v24, v28, v28
	v_fmac_f32_e32 v25, v30, v30
	v_add_f32_e32 v24, v24, v25
	v_mul_f32_e32 v25, v27, v27
	v_fmac_f32_e32 v25, v26, v26
	v_add_f32_e32 v24, v25, v24
	v_mul_f32_e32 v25, v33, v33
	v_fmac_f32_e32 v25, v32, v32
	v_add_f32_e32 v34, v25, v24
	v_cvt_pk_bf16_f32 v24, v28, v29
	v_lshl_add_u64 v[28:29], s[16:17], 0, v[94:95]
	v_cvt_pk_bf16_f32 v25, v30, v31
	v_cvt_pk_bf16_f32 v26, v26, v27
	v_cvt_pk_bf16_f32 v27, v32, v33
	v_lshl_add_u64 v[28:29], v[162:163], 1, v[28:29]
	global_store_dwordx4 v[28:29], v[24:27], off
	v_lshlrev_b32_e32 v30, 16, v230
	v_and_b32_e32 v31, 0xffff0000, v230
	v_lshlrev_b32_e32 v24, 16, v228
	v_and_b32_e32 v25, 0xffff0000, v228
	v_lshlrev_b32_e32 v26, 16, v229
	v_and_b32_e32 v27, 0xffff0000, v229
	v_lshlrev_b32_e32 v32, 16, v231
	v_and_b32_e32 v33, 0xffff0000, v231
	v_pk_add_f32 v[22:23], v[22:23], v[26:27]
	v_pk_add_f32 v[20:21], v[20:21], v[24:25]
	v_pk_add_f32 v[24:25], v[18:19], v[32:33]
	v_pk_add_f32 v[18:19], v[16:17], v[30:31]
	v_mul_f32_e32 v16, v21, v21
	v_mul_f32_e32 v17, v23, v23
	v_fmac_f32_e32 v16, v20, v20
	v_fmac_f32_e32 v17, v22, v22
	v_add_f32_e32 v16, v16, v17
	v_mul_f32_e32 v17, v19, v19
	v_fmac_f32_e32 v17, v18, v18
	v_add_f32_e32 v16, v17, v16
	v_mul_f32_e32 v17, v25, v25
	v_fmac_f32_e32 v17, v24, v24
	v_add_f32_e32 v16, v17, v16
	v_add_f32_e32 v26, v34, v16
	v_cvt_pk_bf16_f32 v16, v20, v21
	v_cvt_pk_bf16_f32 v17, v22, v23
	v_cvt_pk_bf16_f32 v18, v18, v19
	v_cvt_pk_bf16_f32 v19, v24, v25
	global_store_dwordx4 v[28:29], v[16:19], off offset:256
	s_nop 1
	v_mov_b32_e32 v16, v26
	s_nop 1
	v_permlane16_swap_b32 v16, v26
	s_nop 0
	v_add_f32_e32 v16, v16, v26
	v_mov_b32_e32 v17, v16
	s_nop 1
	v_permlane32_swap_b32 v16, v17
	s_and_saveexec_b64 s[30:31], s[4:5]
	s_cbranch_execz .LBB0_667
	v_lshlrev_b64 v[18:19], 7, v[92:93]
	v_lshl_add_u64 v[18:19], s[20:21], 0, v[18:19]
	v_lshl_add_u64 v[18:19], s[28:29], 2, v[18:19]
	s_lshl_b32 s36, s38, 2
	s_mov_b32 s37, s24
	v_lshl_add_u64 v[18:19], v[18:19], 0, s[36:37]
	v_add_f32_e32 v16, v16, v17
	global_store_dword v[18:19], v16, off
.LBB0_667:
	s_or_b64 exec, exec, s[30:31]
	v_lshlrev_b32_e32 v16, 16, v232
	v_and_b32_e32 v17, 0xffff0000, v232
	v_lshlrev_b32_e32 v18, 16, v233
	v_and_b32_e32 v19, 0xffff0000, v233
	v_lshlrev_b32_e32 v20, 16, v234
	v_and_b32_e32 v21, 0xffff0000, v234
	v_lshlrev_b32_e32 v22, 16, v235
	v_and_b32_e32 v23, 0xffff0000, v235
	v_pk_add_f32 v[14:15], v[14:15], v[18:19]
	v_pk_add_f32 v[12:13], v[12:13], v[16:17]
	v_pk_add_f32 v[16:17], v[10:11], v[22:23]
	v_pk_add_f32 v[10:11], v[8:9], v[20:21]
	v_mul_f32_e32 v8, v13, v13
	v_mul_f32_e32 v9, v15, v15
	v_fmac_f32_e32 v8, v12, v12
	v_fmac_f32_e32 v9, v14, v14
	v_add_f32_e32 v8, v8, v9
	v_mul_f32_e32 v9, v11, v11
	v_fmac_f32_e32 v9, v10, v10
	v_add_f32_e32 v8, v9, v8
	v_mul_f32_e32 v9, v17, v17
	v_fmac_f32_e32 v9, v16, v16
	v_add_f32_e32 v18, v9, v8
	v_cvt_pk_bf16_f32 v8, v12, v13
	v_lshl_add_u64 v[12:13], s[16:17], 0, v[90:91]
	v_cvt_pk_bf16_f32 v9, v14, v15
	v_cvt_pk_bf16_f32 v10, v10, v11
	v_cvt_pk_bf16_f32 v11, v16, v17
	v_lshl_add_u64 v[12:13], v[162:163], 1, v[12:13]
	global_store_dwordx4 v[12:13], v[8:11], off
	v_lshlrev_b32_e32 v14, 16, v238
	v_and_b32_e32 v15, 0xffff0000, v238
	v_lshlrev_b32_e32 v8, 16, v236
	v_and_b32_e32 v9, 0xffff0000, v236
	v_lshlrev_b32_e32 v10, 16, v237
	v_and_b32_e32 v11, 0xffff0000, v237
	v_lshlrev_b32_e32 v16, 16, v239
	v_and_b32_e32 v17, 0xffff0000, v239
	v_pk_add_f32 v[6:7], v[6:7], v[10:11]
	v_pk_add_f32 v[4:5], v[4:5], v[8:9]
	v_pk_add_f32 v[8:9], v[2:3], v[16:17]
	v_pk_add_f32 v[2:3], v[0:1], v[14:15]
	v_mul_f32_e32 v0, v5, v5
	v_mul_f32_e32 v1, v7, v7
	v_fmac_f32_e32 v0, v4, v4
	v_fmac_f32_e32 v1, v6, v6
	v_add_f32_e32 v0, v0, v1
	v_mul_f32_e32 v1, v3, v3
	v_fmac_f32_e32 v1, v2, v2
	v_add_f32_e32 v0, v1, v0
	v_mul_f32_e32 v1, v9, v9
	v_fmac_f32_e32 v1, v8, v8
	v_add_f32_e32 v0, v1, v0
	v_add_f32_e32 v10, v18, v0
	v_cvt_pk_bf16_f32 v0, v4, v5
	v_cvt_pk_bf16_f32 v1, v6, v7
	v_cvt_pk_bf16_f32 v2, v2, v3
	v_cvt_pk_bf16_f32 v3, v8, v9
	global_store_dwordx4 v[12:13], v[0:3], off offset:256
	s_nop 1
	v_mov_b32_e32 v0, v10
	s_nop 1
	v_permlane16_swap_b32 v10, v0
	s_nop 0
	v_add_f32_e32 v0, v10, v0
	v_mov_b32_e32 v1, v0
	s_nop 1
	v_permlane32_swap_b32 v1, v0
	s_and_saveexec_b64 s[30:31], s[4:5]
	s_cbranch_execz .LBB0_669
	v_lshlrev_b64 v[2:3], 7, v[88:89]
	v_lshl_add_u64 v[2:3], s[20:21], 0, v[2:3]
	v_lshl_add_u64 v[2:3], s[28:29], 2, v[2:3]
	s_lshl_b32 s28, s38, 2
	s_mov_b32 s29, s24
	v_lshl_add_u64 v[2:3], v[2:3], 0, s[28:29]
	v_add_f32_e32 v0, v1, v0
	global_store_dword v[2:3], v0, off
